# Gated DeltaNet staging branch hand-written; per-tile output flush moved from the GDN recurrence waves to the staging waves
# speedup vs baseline: 1.0193x; 1.0053x over previous
.Lgc_loop:
	ds_read_b128 v[18:21], v100 offset:0
	ds_read_b128 v[22:25], v100 offset:16
	ds_read_b128 v[26:29], v100 offset:528
	ds_read_b128 v[30:33], v100 offset:544
	ds_read_b64 v[34:35], v101 offset:33792
	ds_read_b64 v[36:37], v117 offset:37888
	ds_read_b128 v[38:41], v100 offset:1056
	ds_read_b128 v[42:45], v100 offset:1072
	ds_read_b128 v[46:49], v100 offset:1584
	ds_read_b128 v[50:53], v100 offset:1600
	ds_read_b64 v[54:55], v101 offset:33920
	ds_read_b64 v[56:57], v117 offset:37896
	s_waitcnt lgkmcnt(6)
	v_pk_mul_f32 v[94:95], v[18:19], v[2:3] op_sel:[0,0] op_sel_hi:[0,1]
	v_pk_mul_f32 v[96:97], v[18:19], v[4:5] op_sel:[1,0] op_sel_hi:[1,1]
	v_pk_fma_f32 v[94:95], v[20:21], v[6:7], v[94:95] op_sel:[0,0,0] op_sel_hi:[0,1,1]
	v_pk_fma_f32 v[96:97], v[20:21], v[8:9], v[96:97] op_sel:[1,0,0] op_sel_hi:[1,1,1]
	v_pk_fma_f32 v[94:95], v[22:23], v[10:11], v[94:95] op_sel:[0,0,0] op_sel_hi:[0,1,1]
	v_pk_fma_f32 v[96:97], v[22:23], v[12:13], v[96:97] op_sel:[1,0,0] op_sel_hi:[1,1,1]
	v_pk_fma_f32 v[94:95], v[24:25], v[14:15], v[94:95] op_sel:[0,0,0] op_sel_hi:[0,1,1]
	v_pk_fma_f32 v[96:97], v[24:25], v[16:17], v[96:97] op_sel:[1,0,0] op_sel_hi:[1,1,1]
	s_nop 0
	v_pk_add_f32 v[94:95], v[94:95], v[96:97]
	s_nop 1
	v_add_f32_dpp v94, v94, v94 quad_perm:[1,0,3,2] row_mask:0xf bank_mask:0xf
	v_add_f32_dpp v95, v95, v95 quad_perm:[1,0,3,2] row_mask:0xf bank_mask:0xf
	s_nop 0
	v_add_f32_dpp v94, v94, v94 quad_perm:[2,3,0,1] row_mask:0xf bank_mask:0xf
	v_add_f32_dpp v95, v95, v95 quad_perm:[2,3,0,1] row_mask:0xf bank_mask:0xf
	s_nop 0
	v_add_f32_dpp v94, v94, v94 row_half_mirror row_mask:0xf bank_mask:0xf
	v_add_f32_dpp v95, v95, v95 row_half_mirror row_mask:0xf bank_mask:0xf
	s_nop 0
	v_add_f32_dpp v94, v94, v94 row_mirror row_mask:0xf bank_mask:0xf
	v_add_f32_dpp v95, v95, v95 row_mirror row_mask:0xf bank_mask:0xf
	v_pk_fma_f32 v[98:99], v[36:37], v[94:95], v[34:35] op_sel:[1,0,0] op_sel_hi:[1,1,1] neg_lo:[1,0,0] neg_hi:[1,0,0]
	s_nop 0
	v_pk_mul_f32 v[106:107], v[36:37], v[98:99] op_sel:[0,0] op_sel_hi:[0,1]
	ds_read_b128 v[58:61], v100 offset:2112
	ds_read_b128 v[62:65], v100 offset:2128
	ds_read_b128 v[66:69], v100 offset:2640
	ds_read_b128 v[70:73], v100 offset:2656
	ds_read_b64 v[74:75], v101 offset:34048
	ds_read_b64 v[76:77], v117 offset:37904
	v_pk_mul_f32 v[78:79], v[18:19], v[106:107] op_sel:[0,0] op_sel_hi:[0,1]
	v_pk_mul_f32 v[80:81], v[18:19], v[106:107] op_sel:[1,0] op_sel_hi:[1,1]
	v_pk_mul_f32 v[82:83], v[20:21], v[106:107] op_sel:[0,0] op_sel_hi:[0,1]
	v_pk_mul_f32 v[84:85], v[20:21], v[106:107] op_sel:[1,0] op_sel_hi:[1,1]
	v_pk_fma_f32 v[2:3], v[2:3], v[36:37], v[78:79] op_sel:[0,1,0] op_sel_hi:[1,1,1]
	v_pk_fma_f32 v[4:5], v[4:5], v[36:37], v[80:81] op_sel:[0,1,0] op_sel_hi:[1,1,1]
	v_pk_fma_f32 v[6:7], v[6:7], v[36:37], v[82:83] op_sel:[0,1,0] op_sel_hi:[1,1,1]
	v_pk_fma_f32 v[8:9], v[8:9], v[36:37], v[84:85] op_sel:[0,1,0] op_sel_hi:[1,1,1]
	v_pk_mul_f32 v[86:87], v[22:23], v[106:107] op_sel:[0,0] op_sel_hi:[0,1]
	v_pk_mul_f32 v[88:89], v[22:23], v[106:107] op_sel:[1,0] op_sel_hi:[1,1]
	v_pk_mul_f32 v[90:91], v[24:25], v[106:107] op_sel:[0,0] op_sel_hi:[0,1]
	v_pk_mul_f32 v[92:93], v[24:25], v[106:107] op_sel:[1,0] op_sel_hi:[1,1]
	v_pk_fma_f32 v[10:11], v[10:11], v[36:37], v[86:87] op_sel:[0,1,0] op_sel_hi:[1,1,1]
	v_pk_fma_f32 v[12:13], v[12:13], v[36:37], v[88:89] op_sel:[0,1,0] op_sel_hi:[1,1,1]
	v_pk_fma_f32 v[14:15], v[14:15], v[36:37], v[90:91] op_sel:[0,1,0] op_sel_hi:[1,1,1]
	v_pk_fma_f32 v[16:17], v[16:17], v[36:37], v[92:93] op_sel:[0,1,0] op_sel_hi:[1,1,1]
	s_waitcnt lgkmcnt(6)
	v_pk_mul_f32 v[94:95], v[38:39], v[2:3] op_sel:[0,0] op_sel_hi:[0,1]
	v_pk_mul_f32 v[96:97], v[38:39], v[4:5] op_sel:[1,0] op_sel_hi:[1,1]
	v_pk_fma_f32 v[94:95], v[40:41], v[6:7], v[94:95] op_sel:[0,0,0] op_sel_hi:[0,1,1]
	v_pk_fma_f32 v[96:97], v[40:41], v[8:9], v[96:97] op_sel:[1,0,0] op_sel_hi:[1,1,1]
	v_pk_fma_f32 v[94:95], v[42:43], v[10:11], v[94:95] op_sel:[0,0,0] op_sel_hi:[0,1,1]
	v_pk_fma_f32 v[96:97], v[42:43], v[12:13], v[96:97] op_sel:[1,0,0] op_sel_hi:[1,1,1]
	v_pk_fma_f32 v[94:95], v[44:45], v[14:15], v[94:95] op_sel:[0,0,0] op_sel_hi:[0,1,1]
	v_pk_fma_f32 v[96:97], v[44:45], v[16:17], v[96:97] op_sel:[1,0,0] op_sel_hi:[1,1,1]
	v_pk_mul_f32 v[108:109], v[26:27], v[2:3] op_sel:[0,0] op_sel_hi:[0,1]
	v_pk_add_f32 v[94:95], v[94:95], v[96:97]
	v_pk_mul_f32 v[110:111], v[26:27], v[4:5] op_sel:[1,0] op_sel_hi:[1,1]
	v_pk_fma_f32 v[108:109], v[28:29], v[6:7], v[108:109] op_sel:[0,0,0] op_sel_hi:[0,1,1]
	v_add_f32_dpp v94, v94, v94 quad_perm:[1,0,3,2] row_mask:0xf bank_mask:0xf
	v_add_f32_dpp v95, v95, v95 quad_perm:[1,0,3,2] row_mask:0xf bank_mask:0xf
	v_pk_fma_f32 v[110:111], v[28:29], v[8:9], v[110:111] op_sel:[1,0,0] op_sel_hi:[1,1,1]
	v_add_f32_dpp v94, v94, v94 quad_perm:[2,3,0,1] row_mask:0xf bank_mask:0xf
	v_add_f32_dpp v95, v95, v95 quad_perm:[2,3,0,1] row_mask:0xf bank_mask:0xf
	v_pk_fma_f32 v[108:109], v[30:31], v[10:11], v[108:109] op_sel:[0,0,0] op_sel_hi:[0,1,1]
	v_add_f32_dpp v94, v94, v94 row_half_mirror row_mask:0xf bank_mask:0xf
	v_add_f32_dpp v95, v95, v95 row_half_mirror row_mask:0xf bank_mask:0xf
	v_pk_fma_f32 v[110:111], v[30:31], v[12:13], v[110:111] op_sel:[1,0,0] op_sel_hi:[1,1,1]
	v_add_f32_dpp v94, v94, v94 row_mirror row_mask:0xf bank_mask:0xf
	v_add_f32_dpp v95, v95, v95 row_mirror row_mask:0xf bank_mask:0xf
	v_pk_fma_f32 v[108:109], v[32:33], v[14:15], v[108:109] op_sel:[0,0,0] op_sel_hi:[0,1,1]
	v_pk_fma_f32 v[110:111], v[32:33], v[16:17], v[110:111] op_sel:[1,0,0] op_sel_hi:[1,1,1]
	s_nop 0
	v_pk_add_f32 v[108:109], v[108:109], v[110:111]
	v_pk_fma_f32 v[98:99], v[56:57], v[94:95], v[54:55] op_sel:[1,0,0] op_sel_hi:[1,1,1] neg_lo:[1,0,0] neg_hi:[1,0,0]
	s_nop 0
	v_pk_mul_f32 v[106:107], v[56:57], v[98:99] op_sel:[0,0] op_sel_hi:[0,1]
	ds_write_b64 v102, v[108:109] offset:0
	ds_read_b128 v[18:21], v100 offset:3168
	ds_read_b128 v[22:25], v100 offset:3184
	ds_read_b128 v[26:29], v100 offset:3696
	ds_read_b128 v[30:33], v100 offset:3712
	ds_read_b64 v[34:35], v101 offset:34176
	ds_read_b64 v[36:37], v117 offset:37912
	v_pk_mul_f32 v[78:79], v[38:39], v[106:107] op_sel:[0,0] op_sel_hi:[0,1]
	v_pk_mul_f32 v[80:81], v[38:39], v[106:107] op_sel:[1,0] op_sel_hi:[1,1]
	v_pk_mul_f32 v[82:83], v[40:41], v[106:107] op_sel:[0,0] op_sel_hi:[0,1]
	v_pk_mul_f32 v[84:85], v[40:41], v[106:107] op_sel:[1,0] op_sel_hi:[1,1]
	v_pk_fma_f32 v[2:3], v[2:3], v[56:57], v[78:79] op_sel:[0,1,0] op_sel_hi:[1,1,1]
	v_pk_fma_f32 v[4:5], v[4:5], v[56:57], v[80:81] op_sel:[0,1,0] op_sel_hi:[1,1,1]
	v_pk_fma_f32 v[6:7], v[6:7], v[56:57], v[82:83] op_sel:[0,1,0] op_sel_hi:[1,1,1]
	v_pk_fma_f32 v[8:9], v[8:9], v[56:57], v[84:85] op_sel:[0,1,0] op_sel_hi:[1,1,1]
	v_pk_mul_f32 v[86:87], v[42:43], v[106:107] op_sel:[0,0] op_sel_hi:[0,1]
	v_pk_mul_f32 v[88:89], v[42:43], v[106:107] op_sel:[1,0] op_sel_hi:[1,1]
	v_pk_mul_f32 v[90:91], v[44:45], v[106:107] op_sel:[0,0] op_sel_hi:[0,1]
	v_pk_mul_f32 v[92:93], v[44:45], v[106:107] op_sel:[1,0] op_sel_hi:[1,1]
	v_pk_fma_f32 v[10:11], v[10:11], v[56:57], v[86:87] op_sel:[0,1,0] op_sel_hi:[1,1,1]
	v_pk_fma_f32 v[12:13], v[12:13], v[56:57], v[88:89] op_sel:[0,1,0] op_sel_hi:[1,1,1]
	v_pk_fma_f32 v[14:15], v[14:15], v[56:57], v[90:91] op_sel:[0,1,0] op_sel_hi:[1,1,1]
	v_pk_fma_f32 v[16:17], v[16:17], v[56:57], v[92:93] op_sel:[0,1,0] op_sel_hi:[1,1,1]
	s_waitcnt lgkmcnt(7)
	v_pk_mul_f32 v[94:95], v[58:59], v[2:3] op_sel:[0,0] op_sel_hi:[0,1]
	v_pk_mul_f32 v[96:97], v[58:59], v[4:5] op_sel:[1,0] op_sel_hi:[1,1]
	v_pk_fma_f32 v[94:95], v[60:61], v[6:7], v[94:95] op_sel:[0,0,0] op_sel_hi:[0,1,1]
	v_pk_fma_f32 v[96:97], v[60:61], v[8:9], v[96:97] op_sel:[1,0,0] op_sel_hi:[1,1,1]
	v_pk_fma_f32 v[94:95], v[62:63], v[10:11], v[94:95] op_sel:[0,0,0] op_sel_hi:[0,1,1]
	v_pk_fma_f32 v[96:97], v[62:63], v[12:13], v[96:97] op_sel:[1,0,0] op_sel_hi:[1,1,1]
	v_pk_fma_f32 v[94:95], v[64:65], v[14:15], v[94:95] op_sel:[0,0,0] op_sel_hi:[0,1,1]
	v_pk_fma_f32 v[96:97], v[64:65], v[16:17], v[96:97] op_sel:[1,0,0] op_sel_hi:[1,1,1]
	v_pk_mul_f32 v[112:113], v[46:47], v[2:3] op_sel:[0,0] op_sel_hi:[0,1]
	v_pk_add_f32 v[94:95], v[94:95], v[96:97]
	v_pk_mul_f32 v[114:115], v[46:47], v[4:5] op_sel:[1,0] op_sel_hi:[1,1]
	v_pk_fma_f32 v[112:113], v[48:49], v[6:7], v[112:113] op_sel:[0,0,0] op_sel_hi:[0,1,1]
	v_add_f32_dpp v94, v94, v94 quad_perm:[1,0,3,2] row_mask:0xf bank_mask:0xf
	v_add_f32_dpp v95, v95, v95 quad_perm:[1,0,3,2] row_mask:0xf bank_mask:0xf
	v_pk_fma_f32 v[114:115], v[48:49], v[8:9], v[114:115] op_sel:[1,0,0] op_sel_hi:[1,1,1]
	v_add_f32_dpp v94, v94, v94 quad_perm:[2,3,0,1] row_mask:0xf bank_mask:0xf
	v_add_f32_dpp v95, v95, v95 quad_perm:[2,3,0,1] row_mask:0xf bank_mask:0xf
	v_pk_fma_f32 v[112:113], v[50:51], v[10:11], v[112:113] op_sel:[0,0,0] op_sel_hi:[0,1,1]
	v_add_f32_dpp v94, v94, v94 row_half_mirror row_mask:0xf bank_mask:0xf
	v_add_f32_dpp v95, v95, v95 row_half_mirror row_mask:0xf bank_mask:0xf
	v_pk_fma_f32 v[114:115], v[50:51], v[12:13], v[114:115] op_sel:[1,0,0] op_sel_hi:[1,1,1]
	v_add_f32_dpp v94, v94, v94 row_mirror row_mask:0xf bank_mask:0xf
	v_add_f32_dpp v95, v95, v95 row_mirror row_mask:0xf bank_mask:0xf
	v_pk_fma_f32 v[112:113], v[52:53], v[14:15], v[112:113] op_sel:[0,0,0] op_sel_hi:[0,1,1]
	v_pk_fma_f32 v[114:115], v[52:53], v[16:17], v[114:115] op_sel:[1,0,0] op_sel_hi:[1,1,1]
	s_nop 0
	v_pk_add_f32 v[112:113], v[112:113], v[114:115]
	v_pk_fma_f32 v[98:99], v[76:77], v[94:95], v[74:75] op_sel:[1,0,0] op_sel_hi:[1,1,1] neg_lo:[1,0,0] neg_hi:[1,0,0]
	s_nop 0
	v_pk_mul_f32 v[106:107], v[76:77], v[98:99] op_sel:[0,0] op_sel_hi:[0,1]
	ds_write_b64 v102, v[112:113] offset:2048
	ds_read_b128 v[38:41], v100 offset:4224
	ds_read_b128 v[42:45], v100 offset:4240
	ds_read_b128 v[46:49], v100 offset:4752
	ds_read_b128 v[50:53], v100 offset:4768
	ds_read_b64 v[54:55], v101 offset:34304
	ds_read_b64 v[56:57], v117 offset:37920
	v_pk_mul_f32 v[78:79], v[58:59], v[106:107] op_sel:[0,0] op_sel_hi:[0,1]
	v_pk_mul_f32 v[80:81], v[58:59], v[106:107] op_sel:[1,0] op_sel_hi:[1,1]
	v_pk_mul_f32 v[82:83], v[60:61], v[106:107] op_sel:[0,0] op_sel_hi:[0,1]
	v_pk_mul_f32 v[84:85], v[60:61], v[106:107] op_sel:[1,0] op_sel_hi:[1,1]
	v_pk_fma_f32 v[2:3], v[2:3], v[76:77], v[78:79] op_sel:[0,1,0] op_sel_hi:[1,1,1]
	v_pk_fma_f32 v[4:5], v[4:5], v[76:77], v[80:81] op_sel:[0,1,0] op_sel_hi:[1,1,1]
	v_pk_fma_f32 v[6:7], v[6:7], v[76:77], v[82:83] op_sel:[0,1,0] op_sel_hi:[1,1,1]
	v_pk_fma_f32 v[8:9], v[8:9], v[76:77], v[84:85] op_sel:[0,1,0] op_sel_hi:[1,1,1]
	v_pk_mul_f32 v[86:87], v[62:63], v[106:107] op_sel:[0,0] op_sel_hi:[0,1]
	v_pk_mul_f32 v[88:89], v[62:63], v[106:107] op_sel:[1,0] op_sel_hi:[1,1]
	v_pk_mul_f32 v[90:91], v[64:65], v[106:107] op_sel:[0,0] op_sel_hi:[0,1]
	v_pk_mul_f32 v[92:93], v[64:65], v[106:107] op_sel:[1,0] op_sel_hi:[1,1]
	v_pk_fma_f32 v[10:11], v[10:11], v[76:77], v[86:87] op_sel:[0,1,0] op_sel_hi:[1,1,1]
	v_pk_fma_f32 v[12:13], v[12:13], v[76:77], v[88:89] op_sel:[0,1,0] op_sel_hi:[1,1,1]
	v_pk_fma_f32 v[14:15], v[14:15], v[76:77], v[90:91] op_sel:[0,1,0] op_sel_hi:[1,1,1]
	v_pk_fma_f32 v[16:17], v[16:17], v[76:77], v[92:93] op_sel:[0,1,0] op_sel_hi:[1,1,1]
	s_waitcnt lgkmcnt(7)
	v_pk_mul_f32 v[94:95], v[18:19], v[2:3] op_sel:[0,0] op_sel_hi:[0,1]
	v_pk_mul_f32 v[96:97], v[18:19], v[4:5] op_sel:[1,0] op_sel_hi:[1,1]
	v_pk_fma_f32 v[94:95], v[20:21], v[6:7], v[94:95] op_sel:[0,0,0] op_sel_hi:[0,1,1]
	v_pk_fma_f32 v[96:97], v[20:21], v[8:9], v[96:97] op_sel:[1,0,0] op_sel_hi:[1,1,1]
	v_pk_fma_f32 v[94:95], v[22:23], v[10:11], v[94:95] op_sel:[0,0,0] op_sel_hi:[0,1,1]
	v_pk_fma_f32 v[96:97], v[22:23], v[12:13], v[96:97] op_sel:[1,0,0] op_sel_hi:[1,1,1]
	v_pk_fma_f32 v[94:95], v[24:25], v[14:15], v[94:95] op_sel:[0,0,0] op_sel_hi:[0,1,1]
	v_pk_fma_f32 v[96:97], v[24:25], v[16:17], v[96:97] op_sel:[1,0,0] op_sel_hi:[1,1,1]
	v_pk_mul_f32 v[108:109], v[66:67], v[2:3] op_sel:[0,0] op_sel_hi:[0,1]
	v_pk_add_f32 v[94:95], v[94:95], v[96:97]
	v_pk_mul_f32 v[110:111], v[66:67], v[4:5] op_sel:[1,0] op_sel_hi:[1,1]
	v_pk_fma_f32 v[108:109], v[68:69], v[6:7], v[108:109] op_sel:[0,0,0] op_sel_hi:[0,1,1]
	v_add_f32_dpp v94, v94, v94 quad_perm:[1,0,3,2] row_mask:0xf bank_mask:0xf
	v_add_f32_dpp v95, v95, v95 quad_perm:[1,0,3,2] row_mask:0xf bank_mask:0xf
	v_pk_fma_f32 v[110:111], v[68:69], v[8:9], v[110:111] op_sel:[1,0,0] op_sel_hi:[1,1,1]
	v_add_f32_dpp v94, v94, v94 quad_perm:[2,3,0,1] row_mask:0xf bank_mask:0xf
	v_add_f32_dpp v95, v95, v95 quad_perm:[2,3,0,1] row_mask:0xf bank_mask:0xf
	v_pk_fma_f32 v[108:109], v[70:71], v[10:11], v[108:109] op_sel:[0,0,0] op_sel_hi:[0,1,1]
	v_add_f32_dpp v94, v94, v94 row_half_mirror row_mask:0xf bank_mask:0xf
	v_add_f32_dpp v95, v95, v95 row_half_mirror row_mask:0xf bank_mask:0xf
	v_pk_fma_f32 v[110:111], v[70:71], v[12:13], v[110:111] op_sel:[1,0,0] op_sel_hi:[1,1,1]
	v_add_f32_dpp v94, v94, v94 row_mirror row_mask:0xf bank_mask:0xf
	v_add_f32_dpp v95, v95, v95 row_mirror row_mask:0xf bank_mask:0xf
	v_pk_fma_f32 v[108:109], v[72:73], v[14:15], v[108:109] op_sel:[0,0,0] op_sel_hi:[0,1,1]
	v_pk_fma_f32 v[110:111], v[72:73], v[16:17], v[110:111] op_sel:[1,0,0] op_sel_hi:[1,1,1]
	s_nop 0
	v_pk_add_f32 v[108:109], v[108:109], v[110:111]
	v_pk_fma_f32 v[98:99], v[36:37], v[94:95], v[34:35] op_sel:[1,0,0] op_sel_hi:[1,1,1] neg_lo:[1,0,0] neg_hi:[1,0,0]
	s_nop 0
	v_pk_mul_f32 v[106:107], v[36:37], v[98:99] op_sel:[0,0] op_sel_hi:[0,1]
	ds_write_b64 v102, v[108:109] offset:4096
	ds_read_b128 v[58:61], v100 offset:5280
	ds_read_b128 v[62:65], v100 offset:5296
	ds_read_b128 v[66:69], v100 offset:5808
	ds_read_b128 v[70:73], v100 offset:5824
	ds_read_b64 v[74:75], v101 offset:34432
	ds_read_b64 v[76:77], v117 offset:37928
	v_pk_mul_f32 v[78:79], v[18:19], v[106:107] op_sel:[0,0] op_sel_hi:[0,1]
	v_pk_mul_f32 v[80:81], v[18:19], v[106:107] op_sel:[1,0] op_sel_hi:[1,1]
	v_pk_mul_f32 v[82:83], v[20:21], v[106:107] op_sel:[0,0] op_sel_hi:[0,1]
	v_pk_mul_f32 v[84:85], v[20:21], v[106:107] op_sel:[1,0] op_sel_hi:[1,1]
	v_pk_fma_f32 v[2:3], v[2:3], v[36:37], v[78:79] op_sel:[0,1,0] op_sel_hi:[1,1,1]
	v_pk_fma_f32 v[4:5], v[4:5], v[36:37], v[80:81] op_sel:[0,1,0] op_sel_hi:[1,1,1]
	v_pk_fma_f32 v[6:7], v[6:7], v[36:37], v[82:83] op_sel:[0,1,0] op_sel_hi:[1,1,1]
	v_pk_fma_f32 v[8:9], v[8:9], v[36:37], v[84:85] op_sel:[0,1,0] op_sel_hi:[1,1,1]
	v_pk_mul_f32 v[86:87], v[22:23], v[106:107] op_sel:[0,0] op_sel_hi:[0,1]
	v_pk_mul_f32 v[88:89], v[22:23], v[106:107] op_sel:[1,0] op_sel_hi:[1,1]
	v_pk_mul_f32 v[90:91], v[24:25], v[106:107] op_sel:[0,0] op_sel_hi:[0,1]
	v_pk_mul_f32 v[92:93], v[24:25], v[106:107] op_sel:[1,0] op_sel_hi:[1,1]
	v_pk_fma_f32 v[10:11], v[10:11], v[36:37], v[86:87] op_sel:[0,1,0] op_sel_hi:[1,1,1]
	v_pk_fma_f32 v[12:13], v[12:13], v[36:37], v[88:89] op_sel:[0,1,0] op_sel_hi:[1,1,1]
	v_pk_fma_f32 v[14:15], v[14:15], v[36:37], v[90:91] op_sel:[0,1,0] op_sel_hi:[1,1,1]
	v_pk_fma_f32 v[16:17], v[16:17], v[36:37], v[92:93] op_sel:[0,1,0] op_sel_hi:[1,1,1]
	s_waitcnt lgkmcnt(7)
	v_pk_mul_f32 v[94:95], v[38:39], v[2:3] op_sel:[0,0] op_sel_hi:[0,1]
	v_pk_mul_f32 v[96:97], v[38:39], v[4:5] op_sel:[1,0] op_sel_hi:[1,1]
	v_pk_fma_f32 v[94:95], v[40:41], v[6:7], v[94:95] op_sel:[0,0,0] op_sel_hi:[0,1,1]
	v_pk_fma_f32 v[96:97], v[40:41], v[8:9], v[96:97] op_sel:[1,0,0] op_sel_hi:[1,1,1]
	v_pk_fma_f32 v[94:95], v[42:43], v[10:11], v[94:95] op_sel:[0,0,0] op_sel_hi:[0,1,1]
	v_pk_fma_f32 v[96:97], v[42:43], v[12:13], v[96:97] op_sel:[1,0,0] op_sel_hi:[1,1,1]
	v_pk_fma_f32 v[94:95], v[44:45], v[14:15], v[94:95] op_sel:[0,0,0] op_sel_hi:[0,1,1]
	v_pk_fma_f32 v[96:97], v[44:45], v[16:17], v[96:97] op_sel:[1,0,0] op_sel_hi:[1,1,1]
	v_pk_mul_f32 v[112:113], v[26:27], v[2:3] op_sel:[0,0] op_sel_hi:[0,1]
	v_pk_add_f32 v[94:95], v[94:95], v[96:97]
	v_pk_mul_f32 v[114:115], v[26:27], v[4:5] op_sel:[1,0] op_sel_hi:[1,1]
	v_pk_fma_f32 v[112:113], v[28:29], v[6:7], v[112:113] op_sel:[0,0,0] op_sel_hi:[0,1,1]
	v_add_f32_dpp v94, v94, v94 quad_perm:[1,0,3,2] row_mask:0xf bank_mask:0xf
	v_add_f32_dpp v95, v95, v95 quad_perm:[1,0,3,2] row_mask:0xf bank_mask:0xf
	v_pk_fma_f32 v[114:115], v[28:29], v[8:9], v[114:115] op_sel:[1,0,0] op_sel_hi:[1,1,1]
	v_add_f32_dpp v94, v94, v94 quad_perm:[2,3,0,1] row_mask:0xf bank_mask:0xf
	v_add_f32_dpp v95, v95, v95 quad_perm:[2,3,0,1] row_mask:0xf bank_mask:0xf
	v_pk_fma_f32 v[112:113], v[30:31], v[10:11], v[112:113] op_sel:[0,0,0] op_sel_hi:[0,1,1]
	v_add_f32_dpp v94, v94, v94 row_half_mirror row_mask:0xf bank_mask:0xf
	v_add_f32_dpp v95, v95, v95 row_half_mirror row_mask:0xf bank_mask:0xf
	v_pk_fma_f32 v[114:115], v[30:31], v[12:13], v[114:115] op_sel:[1,0,0] op_sel_hi:[1,1,1]
	v_add_f32_dpp v94, v94, v94 row_mirror row_mask:0xf bank_mask:0xf
	v_add_f32_dpp v95, v95, v95 row_mirror row_mask:0xf bank_mask:0xf
	v_pk_fma_f32 v[112:113], v[32:33], v[14:15], v[112:113] op_sel:[0,0,0] op_sel_hi:[0,1,1]
	v_pk_fma_f32 v[114:115], v[32:33], v[16:17], v[114:115] op_sel:[1,0,0] op_sel_hi:[1,1,1]
	s_nop 0
	v_pk_add_f32 v[112:113], v[112:113], v[114:115]
	v_pk_fma_f32 v[98:99], v[56:57], v[94:95], v[54:55] op_sel:[1,0,0] op_sel_hi:[1,1,1] neg_lo:[1,0,0] neg_hi:[1,0,0]
	s_nop 0
	v_pk_mul_f32 v[106:107], v[56:57], v[98:99] op_sel:[0,0] op_sel_hi:[0,1]
	ds_write_b64 v102, v[112:113] offset:6144
	ds_read_b128 v[18:21], v100 offset:6336
	ds_read_b128 v[22:25], v100 offset:6352
	ds_read_b128 v[26:29], v100 offset:6864
	ds_read_b128 v[30:33], v100 offset:6880
	ds_read_b64 v[34:35], v101 offset:34560
	ds_read_b64 v[36:37], v117 offset:37936
	v_pk_mul_f32 v[78:79], v[38:39], v[106:107] op_sel:[0,0] op_sel_hi:[0,1]
	v_pk_mul_f32 v[80:81], v[38:39], v[106:107] op_sel:[1,0] op_sel_hi:[1,1]
	v_pk_mul_f32 v[82:83], v[40:41], v[106:107] op_sel:[0,0] op_sel_hi:[0,1]
	v_pk_mul_f32 v[84:85], v[40:41], v[106:107] op_sel:[1,0] op_sel_hi:[1,1]
	v_pk_fma_f32 v[2:3], v[2:3], v[56:57], v[78:79] op_sel:[0,1,0] op_sel_hi:[1,1,1]
	v_pk_fma_f32 v[4:5], v[4:5], v[56:57], v[80:81] op_sel:[0,1,0] op_sel_hi:[1,1,1]
	v_pk_fma_f32 v[6:7], v[6:7], v[56:57], v[82:83] op_sel:[0,1,0] op_sel_hi:[1,1,1]
	v_pk_fma_f32 v[8:9], v[8:9], v[56:57], v[84:85] op_sel:[0,1,0] op_sel_hi:[1,1,1]
	v_pk_mul_f32 v[86:87], v[42:43], v[106:107] op_sel:[0,0] op_sel_hi:[0,1]
	v_pk_mul_f32 v[88:89], v[42:43], v[106:107] op_sel:[1,0] op_sel_hi:[1,1]
	v_pk_mul_f32 v[90:91], v[44:45], v[106:107] op_sel:[0,0] op_sel_hi:[0,1]
	v_pk_mul_f32 v[92:93], v[44:45], v[106:107] op_sel:[1,0] op_sel_hi:[1,1]
	v_pk_fma_f32 v[10:11], v[10:11], v[56:57], v[86:87] op_sel:[0,1,0] op_sel_hi:[1,1,1]
	v_pk_fma_f32 v[12:13], v[12:13], v[56:57], v[88:89] op_sel:[0,1,0] op_sel_hi:[1,1,1]
	v_pk_fma_f32 v[14:15], v[14:15], v[56:57], v[90:91] op_sel:[0,1,0] op_sel_hi:[1,1,1]
	v_pk_fma_f32 v[16:17], v[16:17], v[56:57], v[92:93] op_sel:[0,1,0] op_sel_hi:[1,1,1]
	s_waitcnt lgkmcnt(7)
	v_pk_mul_f32 v[94:95], v[58:59], v[2:3] op_sel:[0,0] op_sel_hi:[0,1]
	v_pk_mul_f32 v[96:97], v[58:59], v[4:5] op_sel:[1,0] op_sel_hi:[1,1]
	v_pk_fma_f32 v[94:95], v[60:61], v[6:7], v[94:95] op_sel:[0,0,0] op_sel_hi:[0,1,1]
	v_pk_fma_f32 v[96:97], v[60:61], v[8:9], v[96:97] op_sel:[1,0,0] op_sel_hi:[1,1,1]
	v_pk_fma_f32 v[94:95], v[62:63], v[10:11], v[94:95] op_sel:[0,0,0] op_sel_hi:[0,1,1]
	v_pk_fma_f32 v[96:97], v[62:63], v[12:13], v[96:97] op_sel:[1,0,0] op_sel_hi:[1,1,1]
	v_pk_fma_f32 v[94:95], v[64:65], v[14:15], v[94:95] op_sel:[0,0,0] op_sel_hi:[0,1,1]
	v_pk_fma_f32 v[96:97], v[64:65], v[16:17], v[96:97] op_sel:[1,0,0] op_sel_hi:[1,1,1]
	v_pk_mul_f32 v[108:109], v[46:47], v[2:3] op_sel:[0,0] op_sel_hi:[0,1]
	v_pk_add_f32 v[94:95], v[94:95], v[96:97]
	v_pk_mul_f32 v[110:111], v[46:47], v[4:5] op_sel:[1,0] op_sel_hi:[1,1]
	v_pk_fma_f32 v[108:109], v[48:49], v[6:7], v[108:109] op_sel:[0,0,0] op_sel_hi:[0,1,1]
	v_add_f32_dpp v94, v94, v94 quad_perm:[1,0,3,2] row_mask:0xf bank_mask:0xf
	v_add_f32_dpp v95, v95, v95 quad_perm:[1,0,3,2] row_mask:0xf bank_mask:0xf
	v_pk_fma_f32 v[110:111], v[48:49], v[8:9], v[110:111] op_sel:[1,0,0] op_sel_hi:[1,1,1]
	v_add_f32_dpp v94, v94, v94 quad_perm:[2,3,0,1] row_mask:0xf bank_mask:0xf
	v_add_f32_dpp v95, v95, v95 quad_perm:[2,3,0,1] row_mask:0xf bank_mask:0xf
	v_pk_fma_f32 v[108:109], v[50:51], v[10:11], v[108:109] op_sel:[0,0,0] op_sel_hi:[0,1,1]
	v_add_f32_dpp v94, v94, v94 row_half_mirror row_mask:0xf bank_mask:0xf
	v_add_f32_dpp v95, v95, v95 row_half_mirror row_mask:0xf bank_mask:0xf
	v_pk_fma_f32 v[110:111], v[50:51], v[12:13], v[110:111] op_sel:[1,0,0] op_sel_hi:[1,1,1]
	v_add_f32_dpp v94, v94, v94 row_mirror row_mask:0xf bank_mask:0xf
	v_add_f32_dpp v95, v95, v95 row_mirror row_mask:0xf bank_mask:0xf
	v_pk_fma_f32 v[108:109], v[52:53], v[14:15], v[108:109] op_sel:[0,0,0] op_sel_hi:[0,1,1]
	v_pk_fma_f32 v[110:111], v[52:53], v[16:17], v[110:111] op_sel:[1,0,0] op_sel_hi:[1,1,1]
	s_nop 0
	v_pk_add_f32 v[108:109], v[108:109], v[110:111]
	v_pk_fma_f32 v[98:99], v[76:77], v[94:95], v[74:75] op_sel:[1,0,0] op_sel_hi:[1,1,1] neg_lo:[1,0,0] neg_hi:[1,0,0]
	s_nop 0
	v_pk_mul_f32 v[106:107], v[76:77], v[98:99] op_sel:[0,0] op_sel_hi:[0,1]
	ds_write_b64 v102, v[108:109] offset:8192
	ds_read_b128 v[38:41], v100 offset:7392
	ds_read_b128 v[42:45], v100 offset:7408
	ds_read_b128 v[46:49], v100 offset:7920
	ds_read_b128 v[50:53], v100 offset:7936
	ds_read_b64 v[54:55], v101 offset:34688
	ds_read_b64 v[56:57], v117 offset:37944
	v_pk_mul_f32 v[78:79], v[58:59], v[106:107] op_sel:[0,0] op_sel_hi:[0,1]
	v_pk_mul_f32 v[80:81], v[58:59], v[106:107] op_sel:[1,0] op_sel_hi:[1,1]
	v_pk_mul_f32 v[82:83], v[60:61], v[106:107] op_sel:[0,0] op_sel_hi:[0,1]
	v_pk_mul_f32 v[84:85], v[60:61], v[106:107] op_sel:[1,0] op_sel_hi:[1,1]
	v_pk_fma_f32 v[2:3], v[2:3], v[76:77], v[78:79] op_sel:[0,1,0] op_sel_hi:[1,1,1]
	v_pk_fma_f32 v[4:5], v[4:5], v[76:77], v[80:81] op_sel:[0,1,0] op_sel_hi:[1,1,1]
	v_pk_fma_f32 v[6:7], v[6:7], v[76:77], v[82:83] op_sel:[0,1,0] op_sel_hi:[1,1,1]
	v_pk_fma_f32 v[8:9], v[8:9], v[76:77], v[84:85] op_sel:[0,1,0] op_sel_hi:[1,1,1]
	v_pk_mul_f32 v[86:87], v[62:63], v[106:107] op_sel:[0,0] op_sel_hi:[0,1]
	v_pk_mul_f32 v[88:89], v[62:63], v[106:107] op_sel:[1,0] op_sel_hi:[1,1]
	v_pk_mul_f32 v[90:91], v[64:65], v[106:107] op_sel:[0,0] op_sel_hi:[0,1]
	v_pk_mul_f32 v[92:93], v[64:65], v[106:107] op_sel:[1,0] op_sel_hi:[1,1]
	v_pk_fma_f32 v[10:11], v[10:11], v[76:77], v[86:87] op_sel:[0,1,0] op_sel_hi:[1,1,1]
	v_pk_fma_f32 v[12:13], v[12:13], v[76:77], v[88:89] op_sel:[0,1,0] op_sel_hi:[1,1,1]
	v_pk_fma_f32 v[14:15], v[14:15], v[76:77], v[90:91] op_sel:[0,1,0] op_sel_hi:[1,1,1]
	v_pk_fma_f32 v[16:17], v[16:17], v[76:77], v[92:93] op_sel:[0,1,0] op_sel_hi:[1,1,1]
	s_waitcnt lgkmcnt(7)
	v_pk_mul_f32 v[94:95], v[18:19], v[2:3] op_sel:[0,0] op_sel_hi:[0,1]
	v_pk_mul_f32 v[96:97], v[18:19], v[4:5] op_sel:[1,0] op_sel_hi:[1,1]
	v_pk_fma_f32 v[94:95], v[20:21], v[6:7], v[94:95] op_sel:[0,0,0] op_sel_hi:[0,1,1]
	v_pk_fma_f32 v[96:97], v[20:21], v[8:9], v[96:97] op_sel:[1,0,0] op_sel_hi:[1,1,1]
	v_pk_fma_f32 v[94:95], v[22:23], v[10:11], v[94:95] op_sel:[0,0,0] op_sel_hi:[0,1,1]
	v_pk_fma_f32 v[96:97], v[22:23], v[12:13], v[96:97] op_sel:[1,0,0] op_sel_hi:[1,1,1]
	v_pk_fma_f32 v[94:95], v[24:25], v[14:15], v[94:95] op_sel:[0,0,0] op_sel_hi:[0,1,1]
	v_pk_fma_f32 v[96:97], v[24:25], v[16:17], v[96:97] op_sel:[1,0,0] op_sel_hi:[1,1,1]
	v_pk_mul_f32 v[112:113], v[66:67], v[2:3] op_sel:[0,0] op_sel_hi:[0,1]
	v_pk_add_f32 v[94:95], v[94:95], v[96:97]
	v_pk_mul_f32 v[114:115], v[66:67], v[4:5] op_sel:[1,0] op_sel_hi:[1,1]
	v_pk_fma_f32 v[112:113], v[68:69], v[6:7], v[112:113] op_sel:[0,0,0] op_sel_hi:[0,1,1]
	v_add_f32_dpp v94, v94, v94 quad_perm:[1,0,3,2] row_mask:0xf bank_mask:0xf
	v_add_f32_dpp v95, v95, v95 quad_perm:[1,0,3,2] row_mask:0xf bank_mask:0xf
	v_pk_fma_f32 v[114:115], v[68:69], v[8:9], v[114:115] op_sel:[1,0,0] op_sel_hi:[1,1,1]
	v_add_f32_dpp v94, v94, v94 quad_perm:[2,3,0,1] row_mask:0xf bank_mask:0xf
	v_add_f32_dpp v95, v95, v95 quad_perm:[2,3,0,1] row_mask:0xf bank_mask:0xf
	v_pk_fma_f32 v[112:113], v[70:71], v[10:11], v[112:113] op_sel:[0,0,0] op_sel_hi:[0,1,1]
	v_add_f32_dpp v94, v94, v94 row_half_mirror row_mask:0xf bank_mask:0xf
	v_add_f32_dpp v95, v95, v95 row_half_mirror row_mask:0xf bank_mask:0xf
	v_pk_fma_f32 v[114:115], v[70:71], v[12:13], v[114:115] op_sel:[1,0,0] op_sel_hi:[1,1,1]
	v_add_f32_dpp v94, v94, v94 row_mirror row_mask:0xf bank_mask:0xf
	v_add_f32_dpp v95, v95, v95 row_mirror row_mask:0xf bank_mask:0xf
	v_pk_fma_f32 v[112:113], v[72:73], v[14:15], v[112:113] op_sel:[0,0,0] op_sel_hi:[0,1,1]
	v_pk_fma_f32 v[114:115], v[72:73], v[16:17], v[114:115] op_sel:[1,0,0] op_sel_hi:[1,1,1]
	s_nop 0
	v_pk_add_f32 v[112:113], v[112:113], v[114:115]
	v_pk_fma_f32 v[98:99], v[36:37], v[94:95], v[34:35] op_sel:[1,0,0] op_sel_hi:[1,1,1] neg_lo:[1,0,0] neg_hi:[1,0,0]
	s_nop 0
	v_pk_mul_f32 v[106:107], v[36:37], v[98:99] op_sel:[0,0] op_sel_hi:[0,1]
	ds_write_b64 v102, v[112:113] offset:10240
	ds_read_b128 v[58:61], v100 offset:8448
	ds_read_b128 v[62:65], v100 offset:8464
	ds_read_b128 v[66:69], v100 offset:8976
	ds_read_b128 v[70:73], v100 offset:8992
	ds_read_b64 v[74:75], v101 offset:34816
	ds_read_b64 v[76:77], v117 offset:37952
	v_pk_mul_f32 v[78:79], v[18:19], v[106:107] op_sel:[0,0] op_sel_hi:[0,1]
	v_pk_mul_f32 v[80:81], v[18:19], v[106:107] op_sel:[1,0] op_sel_hi:[1,1]
	v_pk_mul_f32 v[82:83], v[20:21], v[106:107] op_sel:[0,0] op_sel_hi:[0,1]
	v_pk_mul_f32 v[84:85], v[20:21], v[106:107] op_sel:[1,0] op_sel_hi:[1,1]
	v_pk_fma_f32 v[2:3], v[2:3], v[36:37], v[78:79] op_sel:[0,1,0] op_sel_hi:[1,1,1]
	v_pk_fma_f32 v[4:5], v[4:5], v[36:37], v[80:81] op_sel:[0,1,0] op_sel_hi:[1,1,1]
	v_pk_fma_f32 v[6:7], v[6:7], v[36:37], v[82:83] op_sel:[0,1,0] op_sel_hi:[1,1,1]
	v_pk_fma_f32 v[8:9], v[8:9], v[36:37], v[84:85] op_sel:[0,1,0] op_sel_hi:[1,1,1]
	v_pk_mul_f32 v[86:87], v[22:23], v[106:107] op_sel:[0,0] op_sel_hi:[0,1]
	v_pk_mul_f32 v[88:89], v[22:23], v[106:107] op_sel:[1,0] op_sel_hi:[1,1]
	v_pk_mul_f32 v[90:91], v[24:25], v[106:107] op_sel:[0,0] op_sel_hi:[0,1]
	v_pk_mul_f32 v[92:93], v[24:25], v[106:107] op_sel:[1,0] op_sel_hi:[1,1]
	v_pk_fma_f32 v[10:11], v[10:11], v[36:37], v[86:87] op_sel:[0,1,0] op_sel_hi:[1,1,1]
	v_pk_fma_f32 v[12:13], v[12:13], v[36:37], v[88:89] op_sel:[0,1,0] op_sel_hi:[1,1,1]
	v_pk_fma_f32 v[14:15], v[14:15], v[36:37], v[90:91] op_sel:[0,1,0] op_sel_hi:[1,1,1]
	v_pk_fma_f32 v[16:17], v[16:17], v[36:37], v[92:93] op_sel:[0,1,0] op_sel_hi:[1,1,1]
	s_waitcnt lgkmcnt(7)
	v_pk_mul_f32 v[94:95], v[38:39], v[2:3] op_sel:[0,0] op_sel_hi:[0,1]
	v_pk_mul_f32 v[96:97], v[38:39], v[4:5] op_sel:[1,0] op_sel_hi:[1,1]
	v_pk_fma_f32 v[94:95], v[40:41], v[6:7], v[94:95] op_sel:[0,0,0] op_sel_hi:[0,1,1]
	v_pk_fma_f32 v[96:97], v[40:41], v[8:9], v[96:97] op_sel:[1,0,0] op_sel_hi:[1,1,1]
	v_pk_fma_f32 v[94:95], v[42:43], v[10:11], v[94:95] op_sel:[0,0,0] op_sel_hi:[0,1,1]
	v_pk_fma_f32 v[96:97], v[42:43], v[12:13], v[96:97] op_sel:[1,0,0] op_sel_hi:[1,1,1]
	v_pk_fma_f32 v[94:95], v[44:45], v[14:15], v[94:95] op_sel:[0,0,0] op_sel_hi:[0,1,1]
	v_pk_fma_f32 v[96:97], v[44:45], v[16:17], v[96:97] op_sel:[1,0,0] op_sel_hi:[1,1,1]
	v_pk_mul_f32 v[108:109], v[26:27], v[2:3] op_sel:[0,0] op_sel_hi:[0,1]
	v_pk_add_f32 v[94:95], v[94:95], v[96:97]
	v_pk_mul_f32 v[110:111], v[26:27], v[4:5] op_sel:[1,0] op_sel_hi:[1,1]
	v_pk_fma_f32 v[108:109], v[28:29], v[6:7], v[108:109] op_sel:[0,0,0] op_sel_hi:[0,1,1]
	v_add_f32_dpp v94, v94, v94 quad_perm:[1,0,3,2] row_mask:0xf bank_mask:0xf
	v_add_f32_dpp v95, v95, v95 quad_perm:[1,0,3,2] row_mask:0xf bank_mask:0xf
	v_pk_fma_f32 v[110:111], v[28:29], v[8:9], v[110:111] op_sel:[1,0,0] op_sel_hi:[1,1,1]
	v_add_f32_dpp v94, v94, v94 quad_perm:[2,3,0,1] row_mask:0xf bank_mask:0xf
	v_add_f32_dpp v95, v95, v95 quad_perm:[2,3,0,1] row_mask:0xf bank_mask:0xf
	v_pk_fma_f32 v[108:109], v[30:31], v[10:11], v[108:109] op_sel:[0,0,0] op_sel_hi:[0,1,1]
	v_add_f32_dpp v94, v94, v94 row_half_mirror row_mask:0xf bank_mask:0xf
	v_add_f32_dpp v95, v95, v95 row_half_mirror row_mask:0xf bank_mask:0xf
	v_pk_fma_f32 v[110:111], v[30:31], v[12:13], v[110:111] op_sel:[1,0,0] op_sel_hi:[1,1,1]
	v_add_f32_dpp v94, v94, v94 row_mirror row_mask:0xf bank_mask:0xf
	v_add_f32_dpp v95, v95, v95 row_mirror row_mask:0xf bank_mask:0xf
	v_pk_fma_f32 v[108:109], v[32:33], v[14:15], v[108:109] op_sel:[0,0,0] op_sel_hi:[0,1,1]
	v_pk_fma_f32 v[110:111], v[32:33], v[16:17], v[110:111] op_sel:[1,0,0] op_sel_hi:[1,1,1]
	s_nop 0
	v_pk_add_f32 v[108:109], v[108:109], v[110:111]
	v_pk_fma_f32 v[98:99], v[56:57], v[94:95], v[54:55] op_sel:[1,0,0] op_sel_hi:[1,1,1] neg_lo:[1,0,0] neg_hi:[1,0,0]
	s_nop 0
	v_pk_mul_f32 v[106:107], v[56:57], v[98:99] op_sel:[0,0] op_sel_hi:[0,1]
	ds_write_b64 v102, v[108:109] offset:12288
	ds_read_b128 v[18:21], v100 offset:9504
	ds_read_b128 v[22:25], v100 offset:9520
	ds_read_b128 v[26:29], v100 offset:10032
	ds_read_b128 v[30:33], v100 offset:10048
	ds_read_b64 v[34:35], v101 offset:34944
	ds_read_b64 v[36:37], v117 offset:37960
	v_pk_mul_f32 v[78:79], v[38:39], v[106:107] op_sel:[0,0] op_sel_hi:[0,1]
	v_pk_mul_f32 v[80:81], v[38:39], v[106:107] op_sel:[1,0] op_sel_hi:[1,1]
	v_pk_mul_f32 v[82:83], v[40:41], v[106:107] op_sel:[0,0] op_sel_hi:[0,1]
	v_pk_mul_f32 v[84:85], v[40:41], v[106:107] op_sel:[1,0] op_sel_hi:[1,1]
	v_pk_fma_f32 v[2:3], v[2:3], v[56:57], v[78:79] op_sel:[0,1,0] op_sel_hi:[1,1,1]
	v_pk_fma_f32 v[4:5], v[4:5], v[56:57], v[80:81] op_sel:[0,1,0] op_sel_hi:[1,1,1]
	v_pk_fma_f32 v[6:7], v[6:7], v[56:57], v[82:83] op_sel:[0,1,0] op_sel_hi:[1,1,1]
	v_pk_fma_f32 v[8:9], v[8:9], v[56:57], v[84:85] op_sel:[0,1,0] op_sel_hi:[1,1,1]
	v_pk_mul_f32 v[86:87], v[42:43], v[106:107] op_sel:[0,0] op_sel_hi:[0,1]
	v_pk_mul_f32 v[88:89], v[42:43], v[106:107] op_sel:[1,0] op_sel_hi:[1,1]
	v_pk_mul_f32 v[90:91], v[44:45], v[106:107] op_sel:[0,0] op_sel_hi:[0,1]
	v_pk_mul_f32 v[92:93], v[44:45], v[106:107] op_sel:[1,0] op_sel_hi:[1,1]
	v_pk_fma_f32 v[10:11], v[10:11], v[56:57], v[86:87] op_sel:[0,1,0] op_sel_hi:[1,1,1]
	v_pk_fma_f32 v[12:13], v[12:13], v[56:57], v[88:89] op_sel:[0,1,0] op_sel_hi:[1,1,1]
	v_pk_fma_f32 v[14:15], v[14:15], v[56:57], v[90:91] op_sel:[0,1,0] op_sel_hi:[1,1,1]
	v_pk_fma_f32 v[16:17], v[16:17], v[56:57], v[92:93] op_sel:[0,1,0] op_sel_hi:[1,1,1]
	s_waitcnt lgkmcnt(7)
	v_pk_mul_f32 v[94:95], v[58:59], v[2:3] op_sel:[0,0] op_sel_hi:[0,1]
	v_pk_mul_f32 v[96:97], v[58:59], v[4:5] op_sel:[1,0] op_sel_hi:[1,1]
	v_pk_fma_f32 v[94:95], v[60:61], v[6:7], v[94:95] op_sel:[0,0,0] op_sel_hi:[0,1,1]
	v_pk_fma_f32 v[96:97], v[60:61], v[8:9], v[96:97] op_sel:[1,0,0] op_sel_hi:[1,1,1]
	v_pk_fma_f32 v[94:95], v[62:63], v[10:11], v[94:95] op_sel:[0,0,0] op_sel_hi:[0,1,1]
	v_pk_fma_f32 v[96:97], v[62:63], v[12:13], v[96:97] op_sel:[1,0,0] op_sel_hi:[1,1,1]
	v_pk_fma_f32 v[94:95], v[64:65], v[14:15], v[94:95] op_sel:[0,0,0] op_sel_hi:[0,1,1]
	v_pk_fma_f32 v[96:97], v[64:65], v[16:17], v[96:97] op_sel:[1,0,0] op_sel_hi:[1,1,1]
	v_pk_mul_f32 v[112:113], v[46:47], v[2:3] op_sel:[0,0] op_sel_hi:[0,1]
	v_pk_add_f32 v[94:95], v[94:95], v[96:97]
	v_pk_mul_f32 v[114:115], v[46:47], v[4:5] op_sel:[1,0] op_sel_hi:[1,1]
	v_pk_fma_f32 v[112:113], v[48:49], v[6:7], v[112:113] op_sel:[0,0,0] op_sel_hi:[0,1,1]
	v_add_f32_dpp v94, v94, v94 quad_perm:[1,0,3,2] row_mask:0xf bank_mask:0xf
	v_add_f32_dpp v95, v95, v95 quad_perm:[1,0,3,2] row_mask:0xf bank_mask:0xf
	v_pk_fma_f32 v[114:115], v[48:49], v[8:9], v[114:115] op_sel:[1,0,0] op_sel_hi:[1,1,1]
	v_add_f32_dpp v94, v94, v94 quad_perm:[2,3,0,1] row_mask:0xf bank_mask:0xf
	v_add_f32_dpp v95, v95, v95 quad_perm:[2,3,0,1] row_mask:0xf bank_mask:0xf
	v_pk_fma_f32 v[112:113], v[50:51], v[10:11], v[112:113] op_sel:[0,0,0] op_sel_hi:[0,1,1]
	v_add_f32_dpp v94, v94, v94 row_half_mirror row_mask:0xf bank_mask:0xf
	v_add_f32_dpp v95, v95, v95 row_half_mirror row_mask:0xf bank_mask:0xf
	v_pk_fma_f32 v[114:115], v[50:51], v[12:13], v[114:115] op_sel:[1,0,0] op_sel_hi:[1,1,1]
	v_add_f32_dpp v94, v94, v94 row_mirror row_mask:0xf bank_mask:0xf
	v_add_f32_dpp v95, v95, v95 row_mirror row_mask:0xf bank_mask:0xf
	v_pk_fma_f32 v[112:113], v[52:53], v[14:15], v[112:113] op_sel:[0,0,0] op_sel_hi:[0,1,1]
	v_pk_fma_f32 v[114:115], v[52:53], v[16:17], v[114:115] op_sel:[1,0,0] op_sel_hi:[1,1,1]
	s_nop 0
	v_pk_add_f32 v[112:113], v[112:113], v[114:115]
	v_pk_fma_f32 v[98:99], v[76:77], v[94:95], v[74:75] op_sel:[1,0,0] op_sel_hi:[1,1,1] neg_lo:[1,0,0] neg_hi:[1,0,0]
	s_nop 0
	v_pk_mul_f32 v[106:107], v[76:77], v[98:99] op_sel:[0,0] op_sel_hi:[0,1]
	ds_write_b64 v102, v[112:113] offset:14336
	ds_read_b128 v[38:41], v100 offset:10560
	ds_read_b128 v[42:45], v100 offset:10576
	ds_read_b128 v[46:49], v100 offset:11088
	ds_read_b128 v[50:53], v100 offset:11104
	ds_read_b64 v[54:55], v101 offset:35072
	ds_read_b64 v[56:57], v117 offset:37968
	v_pk_mul_f32 v[78:79], v[58:59], v[106:107] op_sel:[0,0] op_sel_hi:[0,1]
	v_pk_mul_f32 v[80:81], v[58:59], v[106:107] op_sel:[1,0] op_sel_hi:[1,1]
	v_pk_mul_f32 v[82:83], v[60:61], v[106:107] op_sel:[0,0] op_sel_hi:[0,1]
	v_pk_mul_f32 v[84:85], v[60:61], v[106:107] op_sel:[1,0] op_sel_hi:[1,1]
	v_pk_fma_f32 v[2:3], v[2:3], v[76:77], v[78:79] op_sel:[0,1,0] op_sel_hi:[1,1,1]
	v_pk_fma_f32 v[4:5], v[4:5], v[76:77], v[80:81] op_sel:[0,1,0] op_sel_hi:[1,1,1]
	v_pk_fma_f32 v[6:7], v[6:7], v[76:77], v[82:83] op_sel:[0,1,0] op_sel_hi:[1,1,1]
	v_pk_fma_f32 v[8:9], v[8:9], v[76:77], v[84:85] op_sel:[0,1,0] op_sel_hi:[1,1,1]
	v_pk_mul_f32 v[86:87], v[62:63], v[106:107] op_sel:[0,0] op_sel_hi:[0,1]
	v_pk_mul_f32 v[88:89], v[62:63], v[106:107] op_sel:[1,0] op_sel_hi:[1,1]
	v_pk_mul_f32 v[90:91], v[64:65], v[106:107] op_sel:[0,0] op_sel_hi:[0,1]
	v_pk_mul_f32 v[92:93], v[64:65], v[106:107] op_sel:[1,0] op_sel_hi:[1,1]
	v_pk_fma_f32 v[10:11], v[10:11], v[76:77], v[86:87] op_sel:[0,1,0] op_sel_hi:[1,1,1]
	v_pk_fma_f32 v[12:13], v[12:13], v[76:77], v[88:89] op_sel:[0,1,0] op_sel_hi:[1,1,1]
	v_pk_fma_f32 v[14:15], v[14:15], v[76:77], v[90:91] op_sel:[0,1,0] op_sel_hi:[1,1,1]
	v_pk_fma_f32 v[16:17], v[16:17], v[76:77], v[92:93] op_sel:[0,1,0] op_sel_hi:[1,1,1]
	s_waitcnt lgkmcnt(7)
	v_pk_mul_f32 v[94:95], v[18:19], v[2:3] op_sel:[0,0] op_sel_hi:[0,1]
	v_pk_mul_f32 v[96:97], v[18:19], v[4:5] op_sel:[1,0] op_sel_hi:[1,1]
	v_pk_fma_f32 v[94:95], v[20:21], v[6:7], v[94:95] op_sel:[0,0,0] op_sel_hi:[0,1,1]
	v_pk_fma_f32 v[96:97], v[20:21], v[8:9], v[96:97] op_sel:[1,0,0] op_sel_hi:[1,1,1]
	v_pk_fma_f32 v[94:95], v[22:23], v[10:11], v[94:95] op_sel:[0,0,0] op_sel_hi:[0,1,1]
	v_pk_fma_f32 v[96:97], v[22:23], v[12:13], v[96:97] op_sel:[1,0,0] op_sel_hi:[1,1,1]
	v_pk_fma_f32 v[94:95], v[24:25], v[14:15], v[94:95] op_sel:[0,0,0] op_sel_hi:[0,1,1]
	v_pk_fma_f32 v[96:97], v[24:25], v[16:17], v[96:97] op_sel:[1,0,0] op_sel_hi:[1,1,1]
	v_pk_mul_f32 v[108:109], v[66:67], v[2:3] op_sel:[0,0] op_sel_hi:[0,1]
	v_pk_add_f32 v[94:95], v[94:95], v[96:97]
	v_pk_mul_f32 v[110:111], v[66:67], v[4:5] op_sel:[1,0] op_sel_hi:[1,1]
	v_pk_fma_f32 v[108:109], v[68:69], v[6:7], v[108:109] op_sel:[0,0,0] op_sel_hi:[0,1,1]
	v_add_f32_dpp v94, v94, v94 quad_perm:[1,0,3,2] row_mask:0xf bank_mask:0xf
	v_add_f32_dpp v95, v95, v95 quad_perm:[1,0,3,2] row_mask:0xf bank_mask:0xf
	v_pk_fma_f32 v[110:111], v[68:69], v[8:9], v[110:111] op_sel:[1,0,0] op_sel_hi:[1,1,1]
	v_add_f32_dpp v94, v94, v94 quad_perm:[2,3,0,1] row_mask:0xf bank_mask:0xf
	v_add_f32_dpp v95, v95, v95 quad_perm:[2,3,0,1] row_mask:0xf bank_mask:0xf
	v_pk_fma_f32 v[108:109], v[70:71], v[10:11], v[108:109] op_sel:[0,0,0] op_sel_hi:[0,1,1]
	v_add_f32_dpp v94, v94, v94 row_half_mirror row_mask:0xf bank_mask:0xf
	v_add_f32_dpp v95, v95, v95 row_half_mirror row_mask:0xf bank_mask:0xf
	v_pk_fma_f32 v[110:111], v[70:71], v[12:13], v[110:111] op_sel:[1,0,0] op_sel_hi:[1,1,1]
	v_add_f32_dpp v94, v94, v94 row_mirror row_mask:0xf bank_mask:0xf
	v_add_f32_dpp v95, v95, v95 row_mirror row_mask:0xf bank_mask:0xf
	v_pk_fma_f32 v[108:109], v[72:73], v[14:15], v[108:109] op_sel:[0,0,0] op_sel_hi:[0,1,1]
	v_pk_fma_f32 v[110:111], v[72:73], v[16:17], v[110:111] op_sel:[1,0,0] op_sel_hi:[1,1,1]
	s_nop 0
	v_pk_add_f32 v[108:109], v[108:109], v[110:111]
	v_pk_fma_f32 v[98:99], v[36:37], v[94:95], v[34:35] op_sel:[1,0,0] op_sel_hi:[1,1,1] neg_lo:[1,0,0] neg_hi:[1,0,0]
	s_nop 0
	v_pk_mul_f32 v[106:107], v[36:37], v[98:99] op_sel:[0,0] op_sel_hi:[0,1]
	ds_write_b64 v102, v[108:109] offset:16384
	ds_read_b128 v[58:61], v100 offset:11616
	ds_read_b128 v[62:65], v100 offset:11632
	ds_read_b128 v[66:69], v100 offset:12144
	ds_read_b128 v[70:73], v100 offset:12160
	ds_read_b64 v[74:75], v101 offset:35200
	ds_read_b64 v[76:77], v117 offset:37976
	v_pk_mul_f32 v[78:79], v[18:19], v[106:107] op_sel:[0,0] op_sel_hi:[0,1]
	v_pk_mul_f32 v[80:81], v[18:19], v[106:107] op_sel:[1,0] op_sel_hi:[1,1]
	v_pk_mul_f32 v[82:83], v[20:21], v[106:107] op_sel:[0,0] op_sel_hi:[0,1]
	v_pk_mul_f32 v[84:85], v[20:21], v[106:107] op_sel:[1,0] op_sel_hi:[1,1]
	v_pk_fma_f32 v[2:3], v[2:3], v[36:37], v[78:79] op_sel:[0,1,0] op_sel_hi:[1,1,1]
	v_pk_fma_f32 v[4:5], v[4:5], v[36:37], v[80:81] op_sel:[0,1,0] op_sel_hi:[1,1,1]
	v_pk_fma_f32 v[6:7], v[6:7], v[36:37], v[82:83] op_sel:[0,1,0] op_sel_hi:[1,1,1]
	v_pk_fma_f32 v[8:9], v[8:9], v[36:37], v[84:85] op_sel:[0,1,0] op_sel_hi:[1,1,1]
	v_pk_mul_f32 v[86:87], v[22:23], v[106:107] op_sel:[0,0] op_sel_hi:[0,1]
	v_pk_mul_f32 v[88:89], v[22:23], v[106:107] op_sel:[1,0] op_sel_hi:[1,1]
	v_pk_mul_f32 v[90:91], v[24:25], v[106:107] op_sel:[0,0] op_sel_hi:[0,1]
	v_pk_mul_f32 v[92:93], v[24:25], v[106:107] op_sel:[1,0] op_sel_hi:[1,1]
	v_pk_fma_f32 v[10:11], v[10:11], v[36:37], v[86:87] op_sel:[0,1,0] op_sel_hi:[1,1,1]
	v_pk_fma_f32 v[12:13], v[12:13], v[36:37], v[88:89] op_sel:[0,1,0] op_sel_hi:[1,1,1]
	v_pk_fma_f32 v[14:15], v[14:15], v[36:37], v[90:91] op_sel:[0,1,0] op_sel_hi:[1,1,1]
	v_pk_fma_f32 v[16:17], v[16:17], v[36:37], v[92:93] op_sel:[0,1,0] op_sel_hi:[1,1,1]
	s_waitcnt lgkmcnt(7)
	v_pk_mul_f32 v[94:95], v[38:39], v[2:3] op_sel:[0,0] op_sel_hi:[0,1]
	v_pk_mul_f32 v[96:97], v[38:39], v[4:5] op_sel:[1,0] op_sel_hi:[1,1]
	v_pk_fma_f32 v[94:95], v[40:41], v[6:7], v[94:95] op_sel:[0,0,0] op_sel_hi:[0,1,1]
	v_pk_fma_f32 v[96:97], v[40:41], v[8:9], v[96:97] op_sel:[1,0,0] op_sel_hi:[1,1,1]
	v_pk_fma_f32 v[94:95], v[42:43], v[10:11], v[94:95] op_sel:[0,0,0] op_sel_hi:[0,1,1]
	v_pk_fma_f32 v[96:97], v[42:43], v[12:13], v[96:97] op_sel:[1,0,0] op_sel_hi:[1,1,1]
	v_pk_fma_f32 v[94:95], v[44:45], v[14:15], v[94:95] op_sel:[0,0,0] op_sel_hi:[0,1,1]
	v_pk_fma_f32 v[96:97], v[44:45], v[16:17], v[96:97] op_sel:[1,0,0] op_sel_hi:[1,1,1]
	v_pk_mul_f32 v[112:113], v[26:27], v[2:3] op_sel:[0,0] op_sel_hi:[0,1]
	v_pk_add_f32 v[94:95], v[94:95], v[96:97]
	v_pk_mul_f32 v[114:115], v[26:27], v[4:5] op_sel:[1,0] op_sel_hi:[1,1]
	v_pk_fma_f32 v[112:113], v[28:29], v[6:7], v[112:113] op_sel:[0,0,0] op_sel_hi:[0,1,1]
	v_add_f32_dpp v94, v94, v94 quad_perm:[1,0,3,2] row_mask:0xf bank_mask:0xf
	v_add_f32_dpp v95, v95, v95 quad_perm:[1,0,3,2] row_mask:0xf bank_mask:0xf
	v_pk_fma_f32 v[114:115], v[28:29], v[8:9], v[114:115] op_sel:[1,0,0] op_sel_hi:[1,1,1]
	v_add_f32_dpp v94, v94, v94 quad_perm:[2,3,0,1] row_mask:0xf bank_mask:0xf
	v_add_f32_dpp v95, v95, v95 quad_perm:[2,3,0,1] row_mask:0xf bank_mask:0xf
	v_pk_fma_f32 v[112:113], v[30:31], v[10:11], v[112:113] op_sel:[0,0,0] op_sel_hi:[0,1,1]
	v_add_f32_dpp v94, v94, v94 row_half_mirror row_mask:0xf bank_mask:0xf
	v_add_f32_dpp v95, v95, v95 row_half_mirror row_mask:0xf bank_mask:0xf
	v_pk_fma_f32 v[114:115], v[30:31], v[12:13], v[114:115] op_sel:[1,0,0] op_sel_hi:[1,1,1]
	v_add_f32_dpp v94, v94, v94 row_mirror row_mask:0xf bank_mask:0xf
	v_add_f32_dpp v95, v95, v95 row_mirror row_mask:0xf bank_mask:0xf
	v_pk_fma_f32 v[112:113], v[32:33], v[14:15], v[112:113] op_sel:[0,0,0] op_sel_hi:[0,1,1]
	v_pk_fma_f32 v[114:115], v[32:33], v[16:17], v[114:115] op_sel:[1,0,0] op_sel_hi:[1,1,1]
	s_nop 0
	v_pk_add_f32 v[112:113], v[112:113], v[114:115]
	v_pk_fma_f32 v[98:99], v[56:57], v[94:95], v[54:55] op_sel:[1,0,0] op_sel_hi:[1,1,1] neg_lo:[1,0,0] neg_hi:[1,0,0]
	s_nop 0
	v_pk_mul_f32 v[106:107], v[56:57], v[98:99] op_sel:[0,0] op_sel_hi:[0,1]
	ds_write_b64 v102, v[112:113] offset:18432
	ds_read_b128 v[18:21], v100 offset:12672
	ds_read_b128 v[22:25], v100 offset:12688
	ds_read_b128 v[26:29], v100 offset:13200
	ds_read_b128 v[30:33], v100 offset:13216
	ds_read_b64 v[34:35], v101 offset:35328
	ds_read_b64 v[36:37], v117 offset:37984
	v_pk_mul_f32 v[78:79], v[38:39], v[106:107] op_sel:[0,0] op_sel_hi:[0,1]
	v_pk_mul_f32 v[80:81], v[38:39], v[106:107] op_sel:[1,0] op_sel_hi:[1,1]
	v_pk_mul_f32 v[82:83], v[40:41], v[106:107] op_sel:[0,0] op_sel_hi:[0,1]
	v_pk_mul_f32 v[84:85], v[40:41], v[106:107] op_sel:[1,0] op_sel_hi:[1,1]
	v_pk_fma_f32 v[2:3], v[2:3], v[56:57], v[78:79] op_sel:[0,1,0] op_sel_hi:[1,1,1]
	v_pk_fma_f32 v[4:5], v[4:5], v[56:57], v[80:81] op_sel:[0,1,0] op_sel_hi:[1,1,1]
	v_pk_fma_f32 v[6:7], v[6:7], v[56:57], v[82:83] op_sel:[0,1,0] op_sel_hi:[1,1,1]
	v_pk_fma_f32 v[8:9], v[8:9], v[56:57], v[84:85] op_sel:[0,1,0] op_sel_hi:[1,1,1]
	v_pk_mul_f32 v[86:87], v[42:43], v[106:107] op_sel:[0,0] op_sel_hi:[0,1]
	v_pk_mul_f32 v[88:89], v[42:43], v[106:107] op_sel:[1,0] op_sel_hi:[1,1]
	v_pk_mul_f32 v[90:91], v[44:45], v[106:107] op_sel:[0,0] op_sel_hi:[0,1]
	v_pk_mul_f32 v[92:93], v[44:45], v[106:107] op_sel:[1,0] op_sel_hi:[1,1]
	v_pk_fma_f32 v[10:11], v[10:11], v[56:57], v[86:87] op_sel:[0,1,0] op_sel_hi:[1,1,1]
	v_pk_fma_f32 v[12:13], v[12:13], v[56:57], v[88:89] op_sel:[0,1,0] op_sel_hi:[1,1,1]
	v_pk_fma_f32 v[14:15], v[14:15], v[56:57], v[90:91] op_sel:[0,1,0] op_sel_hi:[1,1,1]
	v_pk_fma_f32 v[16:17], v[16:17], v[56:57], v[92:93] op_sel:[0,1,0] op_sel_hi:[1,1,1]
	s_waitcnt lgkmcnt(7)
	v_pk_mul_f32 v[94:95], v[58:59], v[2:3] op_sel:[0,0] op_sel_hi:[0,1]
	v_pk_mul_f32 v[96:97], v[58:59], v[4:5] op_sel:[1,0] op_sel_hi:[1,1]
	v_pk_fma_f32 v[94:95], v[60:61], v[6:7], v[94:95] op_sel:[0,0,0] op_sel_hi:[0,1,1]
	v_pk_fma_f32 v[96:97], v[60:61], v[8:9], v[96:97] op_sel:[1,0,0] op_sel_hi:[1,1,1]
	v_pk_fma_f32 v[94:95], v[62:63], v[10:11], v[94:95] op_sel:[0,0,0] op_sel_hi:[0,1,1]
	v_pk_fma_f32 v[96:97], v[62:63], v[12:13], v[96:97] op_sel:[1,0,0] op_sel_hi:[1,1,1]
	v_pk_fma_f32 v[94:95], v[64:65], v[14:15], v[94:95] op_sel:[0,0,0] op_sel_hi:[0,1,1]
	v_pk_fma_f32 v[96:97], v[64:65], v[16:17], v[96:97] op_sel:[1,0,0] op_sel_hi:[1,1,1]
	v_pk_mul_f32 v[108:109], v[46:47], v[2:3] op_sel:[0,0] op_sel_hi:[0,1]
	v_pk_add_f32 v[94:95], v[94:95], v[96:97]
	v_pk_mul_f32 v[110:111], v[46:47], v[4:5] op_sel:[1,0] op_sel_hi:[1,1]
	v_pk_fma_f32 v[108:109], v[48:49], v[6:7], v[108:109] op_sel:[0,0,0] op_sel_hi:[0,1,1]
	v_add_f32_dpp v94, v94, v94 quad_perm:[1,0,3,2] row_mask:0xf bank_mask:0xf
	v_add_f32_dpp v95, v95, v95 quad_perm:[1,0,3,2] row_mask:0xf bank_mask:0xf
	v_pk_fma_f32 v[110:111], v[48:49], v[8:9], v[110:111] op_sel:[1,0,0] op_sel_hi:[1,1,1]
	v_add_f32_dpp v94, v94, v94 quad_perm:[2,3,0,1] row_mask:0xf bank_mask:0xf
	v_add_f32_dpp v95, v95, v95 quad_perm:[2,3,0,1] row_mask:0xf bank_mask:0xf
	v_pk_fma_f32 v[108:109], v[50:51], v[10:11], v[108:109] op_sel:[0,0,0] op_sel_hi:[0,1,1]
	v_add_f32_dpp v94, v94, v94 row_half_mirror row_mask:0xf bank_mask:0xf
	v_add_f32_dpp v95, v95, v95 row_half_mirror row_mask:0xf bank_mask:0xf
	v_pk_fma_f32 v[110:111], v[50:51], v[12:13], v[110:111] op_sel:[1,0,0] op_sel_hi:[1,1,1]
	v_add_f32_dpp v94, v94, v94 row_mirror row_mask:0xf bank_mask:0xf
	v_add_f32_dpp v95, v95, v95 row_mirror row_mask:0xf bank_mask:0xf
	v_pk_fma_f32 v[108:109], v[52:53], v[14:15], v[108:109] op_sel:[0,0,0] op_sel_hi:[0,1,1]
	v_pk_fma_f32 v[110:111], v[52:53], v[16:17], v[110:111] op_sel:[1,0,0] op_sel_hi:[1,1,1]
	s_nop 0
	v_pk_add_f32 v[108:109], v[108:109], v[110:111]
	v_pk_fma_f32 v[98:99], v[76:77], v[94:95], v[74:75] op_sel:[1,0,0] op_sel_hi:[1,1,1] neg_lo:[1,0,0] neg_hi:[1,0,0]
	s_nop 0
	v_pk_mul_f32 v[106:107], v[76:77], v[98:99] op_sel:[0,0] op_sel_hi:[0,1]
	ds_write_b64 v102, v[108:109] offset:20480
	ds_read_b128 v[38:41], v100 offset:13728
	ds_read_b128 v[42:45], v100 offset:13744
	ds_read_b128 v[46:49], v100 offset:14256
	ds_read_b128 v[50:53], v100 offset:14272
	ds_read_b64 v[54:55], v101 offset:35456
	ds_read_b64 v[56:57], v117 offset:37992
	v_pk_mul_f32 v[78:79], v[58:59], v[106:107] op_sel:[0,0] op_sel_hi:[0,1]
	v_pk_mul_f32 v[80:81], v[58:59], v[106:107] op_sel:[1,0] op_sel_hi:[1,1]
	v_pk_mul_f32 v[82:83], v[60:61], v[106:107] op_sel:[0,0] op_sel_hi:[0,1]
	v_pk_mul_f32 v[84:85], v[60:61], v[106:107] op_sel:[1,0] op_sel_hi:[1,1]
	v_pk_fma_f32 v[2:3], v[2:3], v[76:77], v[78:79] op_sel:[0,1,0] op_sel_hi:[1,1,1]
	v_pk_fma_f32 v[4:5], v[4:5], v[76:77], v[80:81] op_sel:[0,1,0] op_sel_hi:[1,1,1]
	v_pk_fma_f32 v[6:7], v[6:7], v[76:77], v[82:83] op_sel:[0,1,0] op_sel_hi:[1,1,1]
	v_pk_fma_f32 v[8:9], v[8:9], v[76:77], v[84:85] op_sel:[0,1,0] op_sel_hi:[1,1,1]
	v_pk_mul_f32 v[86:87], v[62:63], v[106:107] op_sel:[0,0] op_sel_hi:[0,1]
	v_pk_mul_f32 v[88:89], v[62:63], v[106:107] op_sel:[1,0] op_sel_hi:[1,1]
	v_pk_mul_f32 v[90:91], v[64:65], v[106:107] op_sel:[0,0] op_sel_hi:[0,1]
	v_pk_mul_f32 v[92:93], v[64:65], v[106:107] op_sel:[1,0] op_sel_hi:[1,1]
	v_pk_fma_f32 v[10:11], v[10:11], v[76:77], v[86:87] op_sel:[0,1,0] op_sel_hi:[1,1,1]
	v_pk_fma_f32 v[12:13], v[12:13], v[76:77], v[88:89] op_sel:[0,1,0] op_sel_hi:[1,1,1]
	v_pk_fma_f32 v[14:15], v[14:15], v[76:77], v[90:91] op_sel:[0,1,0] op_sel_hi:[1,1,1]
	v_pk_fma_f32 v[16:17], v[16:17], v[76:77], v[92:93] op_sel:[0,1,0] op_sel_hi:[1,1,1]
	s_waitcnt lgkmcnt(7)
	v_pk_mul_f32 v[94:95], v[18:19], v[2:3] op_sel:[0,0] op_sel_hi:[0,1]
	v_pk_mul_f32 v[96:97], v[18:19], v[4:5] op_sel:[1,0] op_sel_hi:[1,1]
	v_pk_fma_f32 v[94:95], v[20:21], v[6:7], v[94:95] op_sel:[0,0,0] op_sel_hi:[0,1,1]
	v_pk_fma_f32 v[96:97], v[20:21], v[8:9], v[96:97] op_sel:[1,0,0] op_sel_hi:[1,1,1]
	v_pk_fma_f32 v[94:95], v[22:23], v[10:11], v[94:95] op_sel:[0,0,0] op_sel_hi:[0,1,1]
	v_pk_fma_f32 v[96:97], v[22:23], v[12:13], v[96:97] op_sel:[1,0,0] op_sel_hi:[1,1,1]
	v_pk_fma_f32 v[94:95], v[24:25], v[14:15], v[94:95] op_sel:[0,0,0] op_sel_hi:[0,1,1]
	v_pk_fma_f32 v[96:97], v[24:25], v[16:17], v[96:97] op_sel:[1,0,0] op_sel_hi:[1,1,1]
	v_pk_mul_f32 v[112:113], v[66:67], v[2:3] op_sel:[0,0] op_sel_hi:[0,1]
	v_pk_add_f32 v[94:95], v[94:95], v[96:97]
	v_pk_mul_f32 v[114:115], v[66:67], v[4:5] op_sel:[1,0] op_sel_hi:[1,1]
	v_pk_fma_f32 v[112:113], v[68:69], v[6:7], v[112:113] op_sel:[0,0,0] op_sel_hi:[0,1,1]
	v_add_f32_dpp v94, v94, v94 quad_perm:[1,0,3,2] row_mask:0xf bank_mask:0xf
	v_add_f32_dpp v95, v95, v95 quad_perm:[1,0,3,2] row_mask:0xf bank_mask:0xf
	v_pk_fma_f32 v[114:115], v[68:69], v[8:9], v[114:115] op_sel:[1,0,0] op_sel_hi:[1,1,1]
	v_add_f32_dpp v94, v94, v94 quad_perm:[2,3,0,1] row_mask:0xf bank_mask:0xf
	v_add_f32_dpp v95, v95, v95 quad_perm:[2,3,0,1] row_mask:0xf bank_mask:0xf
	v_pk_fma_f32 v[112:113], v[70:71], v[10:11], v[112:113] op_sel:[0,0,0] op_sel_hi:[0,1,1]
	v_add_f32_dpp v94, v94, v94 row_half_mirror row_mask:0xf bank_mask:0xf
	v_add_f32_dpp v95, v95, v95 row_half_mirror row_mask:0xf bank_mask:0xf
	v_pk_fma_f32 v[114:115], v[70:71], v[12:13], v[114:115] op_sel:[1,0,0] op_sel_hi:[1,1,1]
	v_add_f32_dpp v94, v94, v94 row_mirror row_mask:0xf bank_mask:0xf
	v_add_f32_dpp v95, v95, v95 row_mirror row_mask:0xf bank_mask:0xf
	v_pk_fma_f32 v[112:113], v[72:73], v[14:15], v[112:113] op_sel:[0,0,0] op_sel_hi:[0,1,1]
	v_pk_fma_f32 v[114:115], v[72:73], v[16:17], v[114:115] op_sel:[1,0,0] op_sel_hi:[1,1,1]
	s_nop 0
	v_pk_add_f32 v[112:113], v[112:113], v[114:115]
	v_pk_fma_f32 v[98:99], v[36:37], v[94:95], v[34:35] op_sel:[1,0,0] op_sel_hi:[1,1,1] neg_lo:[1,0,0] neg_hi:[1,0,0]
	s_nop 0
	v_pk_mul_f32 v[106:107], v[36:37], v[98:99] op_sel:[0,0] op_sel_hi:[0,1]
	ds_write_b64 v102, v[112:113] offset:22528
	ds_read_b128 v[58:61], v100 offset:14784
	ds_read_b128 v[62:65], v100 offset:14800
	ds_read_b128 v[66:69], v100 offset:15312
	ds_read_b128 v[70:73], v100 offset:15328
	ds_read_b64 v[74:75], v101 offset:35584
	ds_read_b64 v[76:77], v117 offset:38000
	v_pk_mul_f32 v[78:79], v[18:19], v[106:107] op_sel:[0,0] op_sel_hi:[0,1]
	v_pk_mul_f32 v[80:81], v[18:19], v[106:107] op_sel:[1,0] op_sel_hi:[1,1]
	v_pk_mul_f32 v[82:83], v[20:21], v[106:107] op_sel:[0,0] op_sel_hi:[0,1]
	v_pk_mul_f32 v[84:85], v[20:21], v[106:107] op_sel:[1,0] op_sel_hi:[1,1]
	v_pk_fma_f32 v[2:3], v[2:3], v[36:37], v[78:79] op_sel:[0,1,0] op_sel_hi:[1,1,1]
	v_pk_fma_f32 v[4:5], v[4:5], v[36:37], v[80:81] op_sel:[0,1,0] op_sel_hi:[1,1,1]
	v_pk_fma_f32 v[6:7], v[6:7], v[36:37], v[82:83] op_sel:[0,1,0] op_sel_hi:[1,1,1]
	v_pk_fma_f32 v[8:9], v[8:9], v[36:37], v[84:85] op_sel:[0,1,0] op_sel_hi:[1,1,1]
	v_pk_mul_f32 v[86:87], v[22:23], v[106:107] op_sel:[0,0] op_sel_hi:[0,1]
	v_pk_mul_f32 v[88:89], v[22:23], v[106:107] op_sel:[1,0] op_sel_hi:[1,1]
	v_pk_mul_f32 v[90:91], v[24:25], v[106:107] op_sel:[0,0] op_sel_hi:[0,1]
	v_pk_mul_f32 v[92:93], v[24:25], v[106:107] op_sel:[1,0] op_sel_hi:[1,1]
	v_pk_fma_f32 v[10:11], v[10:11], v[36:37], v[86:87] op_sel:[0,1,0] op_sel_hi:[1,1,1]
	v_pk_fma_f32 v[12:13], v[12:13], v[36:37], v[88:89] op_sel:[0,1,0] op_sel_hi:[1,1,1]
	v_pk_fma_f32 v[14:15], v[14:15], v[36:37], v[90:91] op_sel:[0,1,0] op_sel_hi:[1,1,1]
	v_pk_fma_f32 v[16:17], v[16:17], v[36:37], v[92:93] op_sel:[0,1,0] op_sel_hi:[1,1,1]
	s_waitcnt lgkmcnt(7)
	v_pk_mul_f32 v[94:95], v[38:39], v[2:3] op_sel:[0,0] op_sel_hi:[0,1]
	v_pk_mul_f32 v[96:97], v[38:39], v[4:5] op_sel:[1,0] op_sel_hi:[1,1]
	v_pk_fma_f32 v[94:95], v[40:41], v[6:7], v[94:95] op_sel:[0,0,0] op_sel_hi:[0,1,1]
	v_pk_fma_f32 v[96:97], v[40:41], v[8:9], v[96:97] op_sel:[1,0,0] op_sel_hi:[1,1,1]
	v_pk_fma_f32 v[94:95], v[42:43], v[10:11], v[94:95] op_sel:[0,0,0] op_sel_hi:[0,1,1]
	v_pk_fma_f32 v[96:97], v[42:43], v[12:13], v[96:97] op_sel:[1,0,0] op_sel_hi:[1,1,1]
	v_pk_fma_f32 v[94:95], v[44:45], v[14:15], v[94:95] op_sel:[0,0,0] op_sel_hi:[0,1,1]
	v_pk_fma_f32 v[96:97], v[44:45], v[16:17], v[96:97] op_sel:[1,0,0] op_sel_hi:[1,1,1]
	v_pk_mul_f32 v[108:109], v[26:27], v[2:3] op_sel:[0,0] op_sel_hi:[0,1]
	v_pk_add_f32 v[94:95], v[94:95], v[96:97]
	v_pk_mul_f32 v[110:111], v[26:27], v[4:5] op_sel:[1,0] op_sel_hi:[1,1]
	v_pk_fma_f32 v[108:109], v[28:29], v[6:7], v[108:109] op_sel:[0,0,0] op_sel_hi:[0,1,1]
	v_add_f32_dpp v94, v94, v94 quad_perm:[1,0,3,2] row_mask:0xf bank_mask:0xf
	v_add_f32_dpp v95, v95, v95 quad_perm:[1,0,3,2] row_mask:0xf bank_mask:0xf
	v_pk_fma_f32 v[110:111], v[28:29], v[8:9], v[110:111] op_sel:[1,0,0] op_sel_hi:[1,1,1]
	v_add_f32_dpp v94, v94, v94 quad_perm:[2,3,0,1] row_mask:0xf bank_mask:0xf
	v_add_f32_dpp v95, v95, v95 quad_perm:[2,3,0,1] row_mask:0xf bank_mask:0xf
	v_pk_fma_f32 v[108:109], v[30:31], v[10:11], v[108:109] op_sel:[0,0,0] op_sel_hi:[0,1,1]
	v_add_f32_dpp v94, v94, v94 row_half_mirror row_mask:0xf bank_mask:0xf
	v_add_f32_dpp v95, v95, v95 row_half_mirror row_mask:0xf bank_mask:0xf
	v_pk_fma_f32 v[110:111], v[30:31], v[12:13], v[110:111] op_sel:[1,0,0] op_sel_hi:[1,1,1]
	v_add_f32_dpp v94, v94, v94 row_mirror row_mask:0xf bank_mask:0xf
	v_add_f32_dpp v95, v95, v95 row_mirror row_mask:0xf bank_mask:0xf
	v_pk_fma_f32 v[108:109], v[32:33], v[14:15], v[108:109] op_sel:[0,0,0] op_sel_hi:[0,1,1]
	v_pk_fma_f32 v[110:111], v[32:33], v[16:17], v[110:111] op_sel:[1,0,0] op_sel_hi:[1,1,1]
	s_nop 0
	v_pk_add_f32 v[108:109], v[108:109], v[110:111]
	v_pk_fma_f32 v[98:99], v[56:57], v[94:95], v[54:55] op_sel:[1,0,0] op_sel_hi:[1,1,1] neg_lo:[1,0,0] neg_hi:[1,0,0]
	s_nop 0
	v_pk_mul_f32 v[106:107], v[56:57], v[98:99] op_sel:[0,0] op_sel_hi:[0,1]
	ds_write_b64 v102, v[108:109] offset:24576
	ds_read_b128 v[18:21], v100 offset:15840
	ds_read_b128 v[22:25], v100 offset:15856
	ds_read_b128 v[26:29], v100 offset:16368
	ds_read_b128 v[30:33], v100 offset:16384
	ds_read_b64 v[34:35], v101 offset:35712
	ds_read_b64 v[36:37], v117 offset:38008
	v_pk_mul_f32 v[78:79], v[38:39], v[106:107] op_sel:[0,0] op_sel_hi:[0,1]
	v_pk_mul_f32 v[80:81], v[38:39], v[106:107] op_sel:[1,0] op_sel_hi:[1,1]
	v_pk_mul_f32 v[82:83], v[40:41], v[106:107] op_sel:[0,0] op_sel_hi:[0,1]
	v_pk_mul_f32 v[84:85], v[40:41], v[106:107] op_sel:[1,0] op_sel_hi:[1,1]
	v_pk_fma_f32 v[2:3], v[2:3], v[56:57], v[78:79] op_sel:[0,1,0] op_sel_hi:[1,1,1]
	v_pk_fma_f32 v[4:5], v[4:5], v[56:57], v[80:81] op_sel:[0,1,0] op_sel_hi:[1,1,1]
	v_pk_fma_f32 v[6:7], v[6:7], v[56:57], v[82:83] op_sel:[0,1,0] op_sel_hi:[1,1,1]
	v_pk_fma_f32 v[8:9], v[8:9], v[56:57], v[84:85] op_sel:[0,1,0] op_sel_hi:[1,1,1]
	v_pk_mul_f32 v[86:87], v[42:43], v[106:107] op_sel:[0,0] op_sel_hi:[0,1]
	v_pk_mul_f32 v[88:89], v[42:43], v[106:107] op_sel:[1,0] op_sel_hi:[1,1]
	v_pk_mul_f32 v[90:91], v[44:45], v[106:107] op_sel:[0,0] op_sel_hi:[0,1]
	v_pk_mul_f32 v[92:93], v[44:45], v[106:107] op_sel:[1,0] op_sel_hi:[1,1]
	v_pk_fma_f32 v[10:11], v[10:11], v[56:57], v[86:87] op_sel:[0,1,0] op_sel_hi:[1,1,1]
	v_pk_fma_f32 v[12:13], v[12:13], v[56:57], v[88:89] op_sel:[0,1,0] op_sel_hi:[1,1,1]
	v_pk_fma_f32 v[14:15], v[14:15], v[56:57], v[90:91] op_sel:[0,1,0] op_sel_hi:[1,1,1]
	v_pk_fma_f32 v[16:17], v[16:17], v[56:57], v[92:93] op_sel:[0,1,0] op_sel_hi:[1,1,1]
	s_waitcnt lgkmcnt(7)
	v_pk_mul_f32 v[94:95], v[58:59], v[2:3] op_sel:[0,0] op_sel_hi:[0,1]
	v_pk_mul_f32 v[96:97], v[58:59], v[4:5] op_sel:[1,0] op_sel_hi:[1,1]
	v_pk_fma_f32 v[94:95], v[60:61], v[6:7], v[94:95] op_sel:[0,0,0] op_sel_hi:[0,1,1]
	v_pk_fma_f32 v[96:97], v[60:61], v[8:9], v[96:97] op_sel:[1,0,0] op_sel_hi:[1,1,1]
	v_pk_fma_f32 v[94:95], v[62:63], v[10:11], v[94:95] op_sel:[0,0,0] op_sel_hi:[0,1,1]
	v_pk_fma_f32 v[96:97], v[62:63], v[12:13], v[96:97] op_sel:[1,0,0] op_sel_hi:[1,1,1]
	v_pk_fma_f32 v[94:95], v[64:65], v[14:15], v[94:95] op_sel:[0,0,0] op_sel_hi:[0,1,1]
	v_pk_fma_f32 v[96:97], v[64:65], v[16:17], v[96:97] op_sel:[1,0,0] op_sel_hi:[1,1,1]
	v_pk_mul_f32 v[112:113], v[46:47], v[2:3] op_sel:[0,0] op_sel_hi:[0,1]
	v_pk_add_f32 v[94:95], v[94:95], v[96:97]
	v_pk_mul_f32 v[114:115], v[46:47], v[4:5] op_sel:[1,0] op_sel_hi:[1,1]
	v_pk_fma_f32 v[112:113], v[48:49], v[6:7], v[112:113] op_sel:[0,0,0] op_sel_hi:[0,1,1]
	v_add_f32_dpp v94, v94, v94 quad_perm:[1,0,3,2] row_mask:0xf bank_mask:0xf
	v_add_f32_dpp v95, v95, v95 quad_perm:[1,0,3,2] row_mask:0xf bank_mask:0xf
	v_pk_fma_f32 v[114:115], v[48:49], v[8:9], v[114:115] op_sel:[1,0,0] op_sel_hi:[1,1,1]
	v_add_f32_dpp v94, v94, v94 quad_perm:[2,3,0,1] row_mask:0xf bank_mask:0xf
	v_add_f32_dpp v95, v95, v95 quad_perm:[2,3,0,1] row_mask:0xf bank_mask:0xf
	v_pk_fma_f32 v[112:113], v[50:51], v[10:11], v[112:113] op_sel:[0,0,0] op_sel_hi:[0,1,1]
	v_add_f32_dpp v94, v94, v94 row_half_mirror row_mask:0xf bank_mask:0xf
	v_add_f32_dpp v95, v95, v95 row_half_mirror row_mask:0xf bank_mask:0xf
	v_pk_fma_f32 v[114:115], v[50:51], v[12:13], v[114:115] op_sel:[1,0,0] op_sel_hi:[1,1,1]
	v_add_f32_dpp v94, v94, v94 row_mirror row_mask:0xf bank_mask:0xf
	v_add_f32_dpp v95, v95, v95 row_mirror row_mask:0xf bank_mask:0xf
	v_pk_fma_f32 v[112:113], v[52:53], v[14:15], v[112:113] op_sel:[0,0,0] op_sel_hi:[0,1,1]
	v_pk_fma_f32 v[114:115], v[52:53], v[16:17], v[114:115] op_sel:[1,0,0] op_sel_hi:[1,1,1]
	s_nop 0
	v_pk_add_f32 v[112:113], v[112:113], v[114:115]
	v_pk_fma_f32 v[98:99], v[76:77], v[94:95], v[74:75] op_sel:[1,0,0] op_sel_hi:[1,1,1] neg_lo:[1,0,0] neg_hi:[1,0,0]
	s_nop 0
	v_pk_mul_f32 v[106:107], v[76:77], v[98:99] op_sel:[0,0] op_sel_hi:[0,1]
	ds_write_b64 v102, v[112:113] offset:26624
	v_pk_mul_f32 v[78:79], v[58:59], v[106:107] op_sel:[0,0] op_sel_hi:[0,1]
	v_pk_mul_f32 v[80:81], v[58:59], v[106:107] op_sel:[1,0] op_sel_hi:[1,1]
	v_pk_mul_f32 v[82:83], v[60:61], v[106:107] op_sel:[0,0] op_sel_hi:[0,1]
	v_pk_mul_f32 v[84:85], v[60:61], v[106:107] op_sel:[1,0] op_sel_hi:[1,1]
	v_pk_fma_f32 v[2:3], v[2:3], v[76:77], v[78:79] op_sel:[0,1,0] op_sel_hi:[1,1,1]
	v_pk_fma_f32 v[4:5], v[4:5], v[76:77], v[80:81] op_sel:[0,1,0] op_sel_hi:[1,1,1]
	v_pk_fma_f32 v[6:7], v[6:7], v[76:77], v[82:83] op_sel:[0,1,0] op_sel_hi:[1,1,1]
	v_pk_fma_f32 v[8:9], v[8:9], v[76:77], v[84:85] op_sel:[0,1,0] op_sel_hi:[1,1,1]
	v_pk_mul_f32 v[86:87], v[62:63], v[106:107] op_sel:[0,0] op_sel_hi:[0,1]
	v_pk_mul_f32 v[88:89], v[62:63], v[106:107] op_sel:[1,0] op_sel_hi:[1,1]
	v_pk_mul_f32 v[90:91], v[64:65], v[106:107] op_sel:[0,0] op_sel_hi:[0,1]
	v_pk_mul_f32 v[92:93], v[64:65], v[106:107] op_sel:[1,0] op_sel_hi:[1,1]
	v_pk_fma_f32 v[10:11], v[10:11], v[76:77], v[86:87] op_sel:[0,1,0] op_sel_hi:[1,1,1]
	v_pk_fma_f32 v[12:13], v[12:13], v[76:77], v[88:89] op_sel:[0,1,0] op_sel_hi:[1,1,1]
	v_pk_fma_f32 v[14:15], v[14:15], v[76:77], v[90:91] op_sel:[0,1,0] op_sel_hi:[1,1,1]
	v_pk_fma_f32 v[16:17], v[16:17], v[76:77], v[92:93] op_sel:[0,1,0] op_sel_hi:[1,1,1]
	s_waitcnt lgkmcnt(1)
	v_pk_mul_f32 v[94:95], v[18:19], v[2:3] op_sel:[0,0] op_sel_hi:[0,1]
	v_pk_mul_f32 v[96:97], v[18:19], v[4:5] op_sel:[1,0] op_sel_hi:[1,1]
	v_pk_fma_f32 v[94:95], v[20:21], v[6:7], v[94:95] op_sel:[0,0,0] op_sel_hi:[0,1,1]
	v_pk_fma_f32 v[96:97], v[20:21], v[8:9], v[96:97] op_sel:[1,0,0] op_sel_hi:[1,1,1]
	v_pk_fma_f32 v[94:95], v[22:23], v[10:11], v[94:95] op_sel:[0,0,0] op_sel_hi:[0,1,1]
	v_pk_fma_f32 v[96:97], v[22:23], v[12:13], v[96:97] op_sel:[1,0,0] op_sel_hi:[1,1,1]
	v_pk_fma_f32 v[94:95], v[24:25], v[14:15], v[94:95] op_sel:[0,0,0] op_sel_hi:[0,1,1]
	v_pk_fma_f32 v[96:97], v[24:25], v[16:17], v[96:97] op_sel:[1,0,0] op_sel_hi:[1,1,1]
	v_pk_mul_f32 v[108:109], v[66:67], v[2:3] op_sel:[0,0] op_sel_hi:[0,1]
	v_pk_add_f32 v[94:95], v[94:95], v[96:97]
	v_pk_mul_f32 v[110:111], v[66:67], v[4:5] op_sel:[1,0] op_sel_hi:[1,1]
	v_pk_fma_f32 v[108:109], v[68:69], v[6:7], v[108:109] op_sel:[0,0,0] op_sel_hi:[0,1,1]
	v_add_f32_dpp v94, v94, v94 quad_perm:[1,0,3,2] row_mask:0xf bank_mask:0xf
	v_add_f32_dpp v95, v95, v95 quad_perm:[1,0,3,2] row_mask:0xf bank_mask:0xf
	v_pk_fma_f32 v[110:111], v[68:69], v[8:9], v[110:111] op_sel:[1,0,0] op_sel_hi:[1,1,1]
	v_add_f32_dpp v94, v94, v94 quad_perm:[2,3,0,1] row_mask:0xf bank_mask:0xf
	v_add_f32_dpp v95, v95, v95 quad_perm:[2,3,0,1] row_mask:0xf bank_mask:0xf
	v_pk_fma_f32 v[108:109], v[70:71], v[10:11], v[108:109] op_sel:[0,0,0] op_sel_hi:[0,1,1]
	v_add_f32_dpp v94, v94, v94 row_half_mirror row_mask:0xf bank_mask:0xf
	v_add_f32_dpp v95, v95, v95 row_half_mirror row_mask:0xf bank_mask:0xf
	v_pk_fma_f32 v[110:111], v[70:71], v[12:13], v[110:111] op_sel:[1,0,0] op_sel_hi:[1,1,1]
	v_add_f32_dpp v94, v94, v94 row_mirror row_mask:0xf bank_mask:0xf
	v_add_f32_dpp v95, v95, v95 row_mirror row_mask:0xf bank_mask:0xf
	v_pk_fma_f32 v[108:109], v[72:73], v[14:15], v[108:109] op_sel:[0,0,0] op_sel_hi:[0,1,1]
	v_pk_fma_f32 v[110:111], v[72:73], v[16:17], v[110:111] op_sel:[1,0,0] op_sel_hi:[1,1,1]
	s_nop 0
	v_pk_add_f32 v[108:109], v[108:109], v[110:111]
	v_pk_fma_f32 v[98:99], v[36:37], v[94:95], v[34:35] op_sel:[1,0,0] op_sel_hi:[1,1,1] neg_lo:[1,0,0] neg_hi:[1,0,0]
	s_nop 0
	v_pk_mul_f32 v[106:107], v[36:37], v[98:99] op_sel:[0,0] op_sel_hi:[0,1]
	ds_write_b64 v102, v[108:109] offset:28672
	v_pk_mul_f32 v[78:79], v[18:19], v[106:107] op_sel:[0,0] op_sel_hi:[0,1]
	v_pk_mul_f32 v[80:81], v[18:19], v[106:107] op_sel:[1,0] op_sel_hi:[1,1]
	v_pk_mul_f32 v[82:83], v[20:21], v[106:107] op_sel:[0,0] op_sel_hi:[0,1]
	v_pk_mul_f32 v[84:85], v[20:21], v[106:107] op_sel:[1,0] op_sel_hi:[1,1]
	v_pk_fma_f32 v[2:3], v[2:3], v[36:37], v[78:79] op_sel:[0,1,0] op_sel_hi:[1,1,1]
	v_pk_fma_f32 v[4:5], v[4:5], v[36:37], v[80:81] op_sel:[0,1,0] op_sel_hi:[1,1,1]
	v_pk_fma_f32 v[6:7], v[6:7], v[36:37], v[82:83] op_sel:[0,1,0] op_sel_hi:[1,1,1]
	v_pk_fma_f32 v[8:9], v[8:9], v[36:37], v[84:85] op_sel:[0,1,0] op_sel_hi:[1,1,1]
	v_pk_mul_f32 v[86:87], v[22:23], v[106:107] op_sel:[0,0] op_sel_hi:[0,1]
	v_pk_mul_f32 v[88:89], v[22:23], v[106:107] op_sel:[1,0] op_sel_hi:[1,1]
	v_pk_mul_f32 v[90:91], v[24:25], v[106:107] op_sel:[0,0] op_sel_hi:[0,1]
	v_pk_mul_f32 v[92:93], v[24:25], v[106:107] op_sel:[1,0] op_sel_hi:[1,1]
	v_pk_fma_f32 v[10:11], v[10:11], v[36:37], v[86:87] op_sel:[0,1,0] op_sel_hi:[1,1,1]
	v_pk_fma_f32 v[12:13], v[12:13], v[36:37], v[88:89] op_sel:[0,1,0] op_sel_hi:[1,1,1]
	v_pk_fma_f32 v[14:15], v[14:15], v[36:37], v[90:91] op_sel:[0,1,0] op_sel_hi:[1,1,1]
	v_pk_fma_f32 v[16:17], v[16:17], v[36:37], v[92:93] op_sel:[0,1,0] op_sel_hi:[1,1,1]
	v_pk_mul_f32 v[112:113], v[26:27], v[2:3] op_sel:[0,0] op_sel_hi:[0,1]
	v_pk_mul_f32 v[114:115], v[26:27], v[4:5] op_sel:[1,0] op_sel_hi:[1,1]
	v_pk_fma_f32 v[112:113], v[28:29], v[6:7], v[112:113] op_sel:[0,0,0] op_sel_hi:[0,1,1]
	v_pk_fma_f32 v[114:115], v[28:29], v[8:9], v[114:115] op_sel:[1,0,0] op_sel_hi:[1,1,1]
	v_pk_fma_f32 v[112:113], v[30:31], v[10:11], v[112:113] op_sel:[0,0,0] op_sel_hi:[0,1,1]
	v_pk_fma_f32 v[114:115], v[30:31], v[12:13], v[114:115] op_sel:[1,0,0] op_sel_hi:[1,1,1]
	v_pk_fma_f32 v[112:113], v[32:33], v[14:15], v[112:113] op_sel:[0,0,0] op_sel_hi:[0,1,1]
	v_pk_fma_f32 v[114:115], v[32:33], v[16:17], v[114:115] op_sel:[1,0,0] op_sel_hi:[1,1,1]
	s_nop 0
	v_pk_add_f32 v[112:113], v[112:113], v[114:115]
	s_nop 0
	ds_write_b64 v102, v[112:113] offset:30720
	s_waitcnt lgkmcnt(0)
	s_barrier
	ds_read_b128 v[18:21], v100 offset:16896
	ds_read_b128 v[22:25], v100 offset:16912
	ds_read_b128 v[26:29], v100 offset:17424
	ds_read_b128 v[30:33], v100 offset:17440
	ds_read_b64 v[34:35], v101 offset:35840
	ds_read_b64 v[36:37], v117 offset:38016
	ds_read_b128 v[38:41], v100 offset:17952
	ds_read_b128 v[42:45], v100 offset:17968
	ds_read_b128 v[46:49], v100 offset:18480
	ds_read_b128 v[50:53], v100 offset:18496
	ds_read_b64 v[54:55], v101 offset:35968
	ds_read_b64 v[56:57], v117 offset:38024
	s_waitcnt lgkmcnt(6)
	v_pk_mul_f32 v[94:95], v[18:19], v[2:3] op_sel:[0,0] op_sel_hi:[0,1]
	v_pk_mul_f32 v[96:97], v[18:19], v[4:5] op_sel:[1,0] op_sel_hi:[1,1]
	v_pk_fma_f32 v[94:95], v[20:21], v[6:7], v[94:95] op_sel:[0,0,0] op_sel_hi:[0,1,1]
	v_pk_fma_f32 v[96:97], v[20:21], v[8:9], v[96:97] op_sel:[1,0,0] op_sel_hi:[1,1,1]
	v_pk_fma_f32 v[94:95], v[22:23], v[10:11], v[94:95] op_sel:[0,0,0] op_sel_hi:[0,1,1]
	v_pk_fma_f32 v[96:97], v[22:23], v[12:13], v[96:97] op_sel:[1,0,0] op_sel_hi:[1,1,1]
	v_pk_fma_f32 v[94:95], v[24:25], v[14:15], v[94:95] op_sel:[0,0,0] op_sel_hi:[0,1,1]
	v_pk_fma_f32 v[96:97], v[24:25], v[16:17], v[96:97] op_sel:[1,0,0] op_sel_hi:[1,1,1]
	s_nop 0
	v_pk_add_f32 v[94:95], v[94:95], v[96:97]
	s_nop 1
	v_add_f32_dpp v94, v94, v94 quad_perm:[1,0,3,2] row_mask:0xf bank_mask:0xf
	v_add_f32_dpp v95, v95, v95 quad_perm:[1,0,3,2] row_mask:0xf bank_mask:0xf
	s_nop 0
	v_add_f32_dpp v94, v94, v94 quad_perm:[2,3,0,1] row_mask:0xf bank_mask:0xf
	v_add_f32_dpp v95, v95, v95 quad_perm:[2,3,0,1] row_mask:0xf bank_mask:0xf
	s_nop 0
	v_add_f32_dpp v94, v94, v94 row_half_mirror row_mask:0xf bank_mask:0xf
	v_add_f32_dpp v95, v95, v95 row_half_mirror row_mask:0xf bank_mask:0xf
	s_nop 0
	v_add_f32_dpp v94, v94, v94 row_mirror row_mask:0xf bank_mask:0xf
	v_add_f32_dpp v95, v95, v95 row_mirror row_mask:0xf bank_mask:0xf
	v_pk_fma_f32 v[98:99], v[36:37], v[94:95], v[34:35] op_sel:[1,0,0] op_sel_hi:[1,1,1] neg_lo:[1,0,0] neg_hi:[1,0,0]
	s_nop 0
	v_pk_mul_f32 v[106:107], v[36:37], v[98:99] op_sel:[0,0] op_sel_hi:[0,1]
	ds_read_b128 v[58:61], v100 offset:19008
	ds_read_b128 v[62:65], v100 offset:19024
	ds_read_b128 v[66:69], v100 offset:19536
	ds_read_b128 v[70:73], v100 offset:19552
	ds_read_b64 v[74:75], v101 offset:36096
	ds_read_b64 v[76:77], v117 offset:38032
	v_pk_mul_f32 v[78:79], v[18:19], v[106:107] op_sel:[0,0] op_sel_hi:[0,1]
	v_pk_mul_f32 v[80:81], v[18:19], v[106:107] op_sel:[1,0] op_sel_hi:[1,1]
	v_pk_mul_f32 v[82:83], v[20:21], v[106:107] op_sel:[0,0] op_sel_hi:[0,1]
	v_pk_mul_f32 v[84:85], v[20:21], v[106:107] op_sel:[1,0] op_sel_hi:[1,1]
	v_pk_fma_f32 v[2:3], v[2:3], v[36:37], v[78:79] op_sel:[0,1,0] op_sel_hi:[1,1,1]
	v_pk_fma_f32 v[4:5], v[4:5], v[36:37], v[80:81] op_sel:[0,1,0] op_sel_hi:[1,1,1]
	v_pk_fma_f32 v[6:7], v[6:7], v[36:37], v[82:83] op_sel:[0,1,0] op_sel_hi:[1,1,1]
	v_pk_fma_f32 v[8:9], v[8:9], v[36:37], v[84:85] op_sel:[0,1,0] op_sel_hi:[1,1,1]
	v_pk_mul_f32 v[86:87], v[22:23], v[106:107] op_sel:[0,0] op_sel_hi:[0,1]
	v_pk_mul_f32 v[88:89], v[22:23], v[106:107] op_sel:[1,0] op_sel_hi:[1,1]
	v_pk_mul_f32 v[90:91], v[24:25], v[106:107] op_sel:[0,0] op_sel_hi:[0,1]
	v_pk_mul_f32 v[92:93], v[24:25], v[106:107] op_sel:[1,0] op_sel_hi:[1,1]
	v_pk_fma_f32 v[10:11], v[10:11], v[36:37], v[86:87] op_sel:[0,1,0] op_sel_hi:[1,1,1]
	v_pk_fma_f32 v[12:13], v[12:13], v[36:37], v[88:89] op_sel:[0,1,0] op_sel_hi:[1,1,1]
	v_pk_fma_f32 v[14:15], v[14:15], v[36:37], v[90:91] op_sel:[0,1,0] op_sel_hi:[1,1,1]
	v_pk_fma_f32 v[16:17], v[16:17], v[36:37], v[92:93] op_sel:[0,1,0] op_sel_hi:[1,1,1]
	s_waitcnt lgkmcnt(6)
	v_pk_mul_f32 v[94:95], v[38:39], v[2:3] op_sel:[0,0] op_sel_hi:[0,1]
	v_pk_mul_f32 v[96:97], v[38:39], v[4:5] op_sel:[1,0] op_sel_hi:[1,1]
	v_pk_fma_f32 v[94:95], v[40:41], v[6:7], v[94:95] op_sel:[0,0,0] op_sel_hi:[0,1,1]
	v_pk_fma_f32 v[96:97], v[40:41], v[8:9], v[96:97] op_sel:[1,0,0] op_sel_hi:[1,1,1]
	v_pk_fma_f32 v[94:95], v[42:43], v[10:11], v[94:95] op_sel:[0,0,0] op_sel_hi:[0,1,1]
	v_pk_fma_f32 v[96:97], v[42:43], v[12:13], v[96:97] op_sel:[1,0,0] op_sel_hi:[1,1,1]
	v_pk_fma_f32 v[94:95], v[44:45], v[14:15], v[94:95] op_sel:[0,0,0] op_sel_hi:[0,1,1]
	v_pk_fma_f32 v[96:97], v[44:45], v[16:17], v[96:97] op_sel:[1,0,0] op_sel_hi:[1,1,1]
	v_pk_mul_f32 v[108:109], v[26:27], v[2:3] op_sel:[0,0] op_sel_hi:[0,1]
	v_pk_add_f32 v[94:95], v[94:95], v[96:97]
	v_pk_mul_f32 v[110:111], v[26:27], v[4:5] op_sel:[1,0] op_sel_hi:[1,1]
	v_pk_fma_f32 v[108:109], v[28:29], v[6:7], v[108:109] op_sel:[0,0,0] op_sel_hi:[0,1,1]
	v_add_f32_dpp v94, v94, v94 quad_perm:[1,0,3,2] row_mask:0xf bank_mask:0xf
	v_add_f32_dpp v95, v95, v95 quad_perm:[1,0,3,2] row_mask:0xf bank_mask:0xf
	v_pk_fma_f32 v[110:111], v[28:29], v[8:9], v[110:111] op_sel:[1,0,0] op_sel_hi:[1,1,1]
	v_add_f32_dpp v94, v94, v94 quad_perm:[2,3,0,1] row_mask:0xf bank_mask:0xf
	v_add_f32_dpp v95, v95, v95 quad_perm:[2,3,0,1] row_mask:0xf bank_mask:0xf
	v_pk_fma_f32 v[108:109], v[30:31], v[10:11], v[108:109] op_sel:[0,0,0] op_sel_hi:[0,1,1]
	v_add_f32_dpp v94, v94, v94 row_half_mirror row_mask:0xf bank_mask:0xf
	v_add_f32_dpp v95, v95, v95 row_half_mirror row_mask:0xf bank_mask:0xf
	v_pk_fma_f32 v[110:111], v[30:31], v[12:13], v[110:111] op_sel:[1,0,0] op_sel_hi:[1,1,1]
	v_add_f32_dpp v94, v94, v94 row_mirror row_mask:0xf bank_mask:0xf
	v_add_f32_dpp v95, v95, v95 row_mirror row_mask:0xf bank_mask:0xf
	v_pk_fma_f32 v[108:109], v[32:33], v[14:15], v[108:109] op_sel:[0,0,0] op_sel_hi:[0,1,1]
	v_pk_fma_f32 v[110:111], v[32:33], v[16:17], v[110:111] op_sel:[1,0,0] op_sel_hi:[1,1,1]
	s_nop 0
	v_pk_add_f32 v[108:109], v[108:109], v[110:111]
	v_pk_fma_f32 v[98:99], v[56:57], v[94:95], v[54:55] op_sel:[1,0,0] op_sel_hi:[1,1,1] neg_lo:[1,0,0] neg_hi:[1,0,0]
	s_nop 0
	v_pk_mul_f32 v[106:107], v[56:57], v[98:99] op_sel:[0,0] op_sel_hi:[0,1]
	ds_write_b64 v102, v[108:109] offset:32768
	ds_read_b128 v[18:21], v100 offset:20064
	ds_read_b128 v[22:25], v100 offset:20080
	ds_read_b128 v[26:29], v100 offset:20592
	ds_read_b128 v[30:33], v100 offset:20608
	ds_read_b64 v[34:35], v101 offset:36224
	ds_read_b64 v[36:37], v117 offset:38040
	v_pk_mul_f32 v[78:79], v[38:39], v[106:107] op_sel:[0,0] op_sel_hi:[0,1]
	v_pk_mul_f32 v[80:81], v[38:39], v[106:107] op_sel:[1,0] op_sel_hi:[1,1]
	v_pk_mul_f32 v[82:83], v[40:41], v[106:107] op_sel:[0,0] op_sel_hi:[0,1]
	v_pk_mul_f32 v[84:85], v[40:41], v[106:107] op_sel:[1,0] op_sel_hi:[1,1]
	v_pk_fma_f32 v[2:3], v[2:3], v[56:57], v[78:79] op_sel:[0,1,0] op_sel_hi:[1,1,1]
	v_pk_fma_f32 v[4:5], v[4:5], v[56:57], v[80:81] op_sel:[0,1,0] op_sel_hi:[1,1,1]
	v_pk_fma_f32 v[6:7], v[6:7], v[56:57], v[82:83] op_sel:[0,1,0] op_sel_hi:[1,1,1]
	v_pk_fma_f32 v[8:9], v[8:9], v[56:57], v[84:85] op_sel:[0,1,0] op_sel_hi:[1,1,1]
	v_pk_mul_f32 v[86:87], v[42:43], v[106:107] op_sel:[0,0] op_sel_hi:[0,1]
	v_pk_mul_f32 v[88:89], v[42:43], v[106:107] op_sel:[1,0] op_sel_hi:[1,1]
	v_pk_mul_f32 v[90:91], v[44:45], v[106:107] op_sel:[0,0] op_sel_hi:[0,1]
	v_pk_mul_f32 v[92:93], v[44:45], v[106:107] op_sel:[1,0] op_sel_hi:[1,1]
	v_pk_fma_f32 v[10:11], v[10:11], v[56:57], v[86:87] op_sel:[0,1,0] op_sel_hi:[1,1,1]
	v_pk_fma_f32 v[12:13], v[12:13], v[56:57], v[88:89] op_sel:[0,1,0] op_sel_hi:[1,1,1]
	v_pk_fma_f32 v[14:15], v[14:15], v[56:57], v[90:91] op_sel:[0,1,0] op_sel_hi:[1,1,1]
	v_pk_fma_f32 v[16:17], v[16:17], v[56:57], v[92:93] op_sel:[0,1,0] op_sel_hi:[1,1,1]
	s_waitcnt lgkmcnt(7)
	v_pk_mul_f32 v[94:95], v[58:59], v[2:3] op_sel:[0,0] op_sel_hi:[0,1]
	v_pk_mul_f32 v[96:97], v[58:59], v[4:5] op_sel:[1,0] op_sel_hi:[1,1]
	v_pk_fma_f32 v[94:95], v[60:61], v[6:7], v[94:95] op_sel:[0,0,0] op_sel_hi:[0,1,1]
	v_pk_fma_f32 v[96:97], v[60:61], v[8:9], v[96:97] op_sel:[1,0,0] op_sel_hi:[1,1,1]
	v_pk_fma_f32 v[94:95], v[62:63], v[10:11], v[94:95] op_sel:[0,0,0] op_sel_hi:[0,1,1]
	v_pk_fma_f32 v[96:97], v[62:63], v[12:13], v[96:97] op_sel:[1,0,0] op_sel_hi:[1,1,1]
	v_pk_fma_f32 v[94:95], v[64:65], v[14:15], v[94:95] op_sel:[0,0,0] op_sel_hi:[0,1,1]
	v_pk_fma_f32 v[96:97], v[64:65], v[16:17], v[96:97] op_sel:[1,0,0] op_sel_hi:[1,1,1]
	v_pk_mul_f32 v[112:113], v[46:47], v[2:3] op_sel:[0,0] op_sel_hi:[0,1]
	v_pk_add_f32 v[94:95], v[94:95], v[96:97]
	v_pk_mul_f32 v[114:115], v[46:47], v[4:5] op_sel:[1,0] op_sel_hi:[1,1]
	v_pk_fma_f32 v[112:113], v[48:49], v[6:7], v[112:113] op_sel:[0,0,0] op_sel_hi:[0,1,1]
	v_add_f32_dpp v94, v94, v94 quad_perm:[1,0,3,2] row_mask:0xf bank_mask:0xf
	v_add_f32_dpp v95, v95, v95 quad_perm:[1,0,3,2] row_mask:0xf bank_mask:0xf
	v_pk_fma_f32 v[114:115], v[48:49], v[8:9], v[114:115] op_sel:[1,0,0] op_sel_hi:[1,1,1]
	v_add_f32_dpp v94, v94, v94 quad_perm:[2,3,0,1] row_mask:0xf bank_mask:0xf
	v_add_f32_dpp v95, v95, v95 quad_perm:[2,3,0,1] row_mask:0xf bank_mask:0xf
	v_pk_fma_f32 v[112:113], v[50:51], v[10:11], v[112:113] op_sel:[0,0,0] op_sel_hi:[0,1,1]
	v_add_f32_dpp v94, v94, v94 row_half_mirror row_mask:0xf bank_mask:0xf
	v_add_f32_dpp v95, v95, v95 row_half_mirror row_mask:0xf bank_mask:0xf
	v_pk_fma_f32 v[114:115], v[50:51], v[12:13], v[114:115] op_sel:[1,0,0] op_sel_hi:[1,1,1]
	v_add_f32_dpp v94, v94, v94 row_mirror row_mask:0xf bank_mask:0xf
	v_add_f32_dpp v95, v95, v95 row_mirror row_mask:0xf bank_mask:0xf
	v_pk_fma_f32 v[112:113], v[52:53], v[14:15], v[112:113] op_sel:[0,0,0] op_sel_hi:[0,1,1]
	v_pk_fma_f32 v[114:115], v[52:53], v[16:17], v[114:115] op_sel:[1,0,0] op_sel_hi:[1,1,1]
	s_nop 0
	v_pk_add_f32 v[112:113], v[112:113], v[114:115]
	v_pk_fma_f32 v[98:99], v[76:77], v[94:95], v[74:75] op_sel:[1,0,0] op_sel_hi:[1,1,1] neg_lo:[1,0,0] neg_hi:[1,0,0]
	s_nop 0
	v_pk_mul_f32 v[106:107], v[76:77], v[98:99] op_sel:[0,0] op_sel_hi:[0,1]
	ds_write_b64 v102, v[112:113] offset:34816
	ds_read_b128 v[38:41], v100 offset:21120
	ds_read_b128 v[42:45], v100 offset:21136
	ds_read_b128 v[46:49], v100 offset:21648
	ds_read_b128 v[50:53], v100 offset:21664
	ds_read_b64 v[54:55], v101 offset:36352
	ds_read_b64 v[56:57], v117 offset:38048
	v_pk_mul_f32 v[78:79], v[58:59], v[106:107] op_sel:[0,0] op_sel_hi:[0,1]
	v_pk_mul_f32 v[80:81], v[58:59], v[106:107] op_sel:[1,0] op_sel_hi:[1,1]
	v_pk_mul_f32 v[82:83], v[60:61], v[106:107] op_sel:[0,0] op_sel_hi:[0,1]
	v_pk_mul_f32 v[84:85], v[60:61], v[106:107] op_sel:[1,0] op_sel_hi:[1,1]
	v_pk_fma_f32 v[2:3], v[2:3], v[76:77], v[78:79] op_sel:[0,1,0] op_sel_hi:[1,1,1]
	v_pk_fma_f32 v[4:5], v[4:5], v[76:77], v[80:81] op_sel:[0,1,0] op_sel_hi:[1,1,1]
	v_pk_fma_f32 v[6:7], v[6:7], v[76:77], v[82:83] op_sel:[0,1,0] op_sel_hi:[1,1,1]
	v_pk_fma_f32 v[8:9], v[8:9], v[76:77], v[84:85] op_sel:[0,1,0] op_sel_hi:[1,1,1]
	v_pk_mul_f32 v[86:87], v[62:63], v[106:107] op_sel:[0,0] op_sel_hi:[0,1]
	v_pk_mul_f32 v[88:89], v[62:63], v[106:107] op_sel:[1,0] op_sel_hi:[1,1]
	v_pk_mul_f32 v[90:91], v[64:65], v[106:107] op_sel:[0,0] op_sel_hi:[0,1]
	v_pk_mul_f32 v[92:93], v[64:65], v[106:107] op_sel:[1,0] op_sel_hi:[1,1]
	v_pk_fma_f32 v[10:11], v[10:11], v[76:77], v[86:87] op_sel:[0,1,0] op_sel_hi:[1,1,1]
	v_pk_fma_f32 v[12:13], v[12:13], v[76:77], v[88:89] op_sel:[0,1,0] op_sel_hi:[1,1,1]
	v_pk_fma_f32 v[14:15], v[14:15], v[76:77], v[90:91] op_sel:[0,1,0] op_sel_hi:[1,1,1]
	v_pk_fma_f32 v[16:17], v[16:17], v[76:77], v[92:93] op_sel:[0,1,0] op_sel_hi:[1,1,1]
	s_waitcnt lgkmcnt(7)
	v_pk_mul_f32 v[94:95], v[18:19], v[2:3] op_sel:[0,0] op_sel_hi:[0,1]
	v_pk_mul_f32 v[96:97], v[18:19], v[4:5] op_sel:[1,0] op_sel_hi:[1,1]
	v_pk_fma_f32 v[94:95], v[20:21], v[6:7], v[94:95] op_sel:[0,0,0] op_sel_hi:[0,1,1]
	v_pk_fma_f32 v[96:97], v[20:21], v[8:9], v[96:97] op_sel:[1,0,0] op_sel_hi:[1,1,1]
	v_pk_fma_f32 v[94:95], v[22:23], v[10:11], v[94:95] op_sel:[0,0,0] op_sel_hi:[0,1,1]
	v_pk_fma_f32 v[96:97], v[22:23], v[12:13], v[96:97] op_sel:[1,0,0] op_sel_hi:[1,1,1]
	v_pk_fma_f32 v[94:95], v[24:25], v[14:15], v[94:95] op_sel:[0,0,0] op_sel_hi:[0,1,1]
	v_pk_fma_f32 v[96:97], v[24:25], v[16:17], v[96:97] op_sel:[1,0,0] op_sel_hi:[1,1,1]
	v_pk_mul_f32 v[108:109], v[66:67], v[2:3] op_sel:[0,0] op_sel_hi:[0,1]
	v_pk_add_f32 v[94:95], v[94:95], v[96:97]
	v_pk_mul_f32 v[110:111], v[66:67], v[4:5] op_sel:[1,0] op_sel_hi:[1,1]
	v_pk_fma_f32 v[108:109], v[68:69], v[6:7], v[108:109] op_sel:[0,0,0] op_sel_hi:[0,1,1]
	v_add_f32_dpp v94, v94, v94 quad_perm:[1,0,3,2] row_mask:0xf bank_mask:0xf
	v_add_f32_dpp v95, v95, v95 quad_perm:[1,0,3,2] row_mask:0xf bank_mask:0xf
	v_pk_fma_f32 v[110:111], v[68:69], v[8:9], v[110:111] op_sel:[1,0,0] op_sel_hi:[1,1,1]
	v_add_f32_dpp v94, v94, v94 quad_perm:[2,3,0,1] row_mask:0xf bank_mask:0xf
	v_add_f32_dpp v95, v95, v95 quad_perm:[2,3,0,1] row_mask:0xf bank_mask:0xf
	v_pk_fma_f32 v[108:109], v[70:71], v[10:11], v[108:109] op_sel:[0,0,0] op_sel_hi:[0,1,1]
	v_add_f32_dpp v94, v94, v94 row_half_mirror row_mask:0xf bank_mask:0xf
	v_add_f32_dpp v95, v95, v95 row_half_mirror row_mask:0xf bank_mask:0xf
	v_pk_fma_f32 v[110:111], v[70:71], v[12:13], v[110:111] op_sel:[1,0,0] op_sel_hi:[1,1,1]
	v_add_f32_dpp v94, v94, v94 row_mirror row_mask:0xf bank_mask:0xf
	v_add_f32_dpp v95, v95, v95 row_mirror row_mask:0xf bank_mask:0xf
	v_pk_fma_f32 v[108:109], v[72:73], v[14:15], v[108:109] op_sel:[0,0,0] op_sel_hi:[0,1,1]
	v_pk_fma_f32 v[110:111], v[72:73], v[16:17], v[110:111] op_sel:[1,0,0] op_sel_hi:[1,1,1]
	s_nop 0
	v_pk_add_f32 v[108:109], v[108:109], v[110:111]
	v_pk_fma_f32 v[98:99], v[36:37], v[94:95], v[34:35] op_sel:[1,0,0] op_sel_hi:[1,1,1] neg_lo:[1,0,0] neg_hi:[1,0,0]
	s_nop 0
	v_pk_mul_f32 v[106:107], v[36:37], v[98:99] op_sel:[0,0] op_sel_hi:[0,1]
	ds_write_b64 v102, v[108:109] offset:36864
	ds_read_b128 v[58:61], v100 offset:22176
	ds_read_b128 v[62:65], v100 offset:22192
	ds_read_b128 v[66:69], v100 offset:22704
	ds_read_b128 v[70:73], v100 offset:22720
	ds_read_b64 v[74:75], v101 offset:36480
	ds_read_b64 v[76:77], v117 offset:38056
	v_pk_mul_f32 v[78:79], v[18:19], v[106:107] op_sel:[0,0] op_sel_hi:[0,1]
	v_pk_mul_f32 v[80:81], v[18:19], v[106:107] op_sel:[1,0] op_sel_hi:[1,1]
	v_pk_mul_f32 v[82:83], v[20:21], v[106:107] op_sel:[0,0] op_sel_hi:[0,1]
	v_pk_mul_f32 v[84:85], v[20:21], v[106:107] op_sel:[1,0] op_sel_hi:[1,1]
	v_pk_fma_f32 v[2:3], v[2:3], v[36:37], v[78:79] op_sel:[0,1,0] op_sel_hi:[1,1,1]
	v_pk_fma_f32 v[4:5], v[4:5], v[36:37], v[80:81] op_sel:[0,1,0] op_sel_hi:[1,1,1]
	v_pk_fma_f32 v[6:7], v[6:7], v[36:37], v[82:83] op_sel:[0,1,0] op_sel_hi:[1,1,1]
	v_pk_fma_f32 v[8:9], v[8:9], v[36:37], v[84:85] op_sel:[0,1,0] op_sel_hi:[1,1,1]
	v_pk_mul_f32 v[86:87], v[22:23], v[106:107] op_sel:[0,0] op_sel_hi:[0,1]
	v_pk_mul_f32 v[88:89], v[22:23], v[106:107] op_sel:[1,0] op_sel_hi:[1,1]
	v_pk_mul_f32 v[90:91], v[24:25], v[106:107] op_sel:[0,0] op_sel_hi:[0,1]
	v_pk_mul_f32 v[92:93], v[24:25], v[106:107] op_sel:[1,0] op_sel_hi:[1,1]
	v_pk_fma_f32 v[10:11], v[10:11], v[36:37], v[86:87] op_sel:[0,1,0] op_sel_hi:[1,1,1]
	v_pk_fma_f32 v[12:13], v[12:13], v[36:37], v[88:89] op_sel:[0,1,0] op_sel_hi:[1,1,1]
	v_pk_fma_f32 v[14:15], v[14:15], v[36:37], v[90:91] op_sel:[0,1,0] op_sel_hi:[1,1,1]
	v_pk_fma_f32 v[16:17], v[16:17], v[36:37], v[92:93] op_sel:[0,1,0] op_sel_hi:[1,1,1]
	s_waitcnt lgkmcnt(7)
	v_pk_mul_f32 v[94:95], v[38:39], v[2:3] op_sel:[0,0] op_sel_hi:[0,1]
	v_pk_mul_f32 v[96:97], v[38:39], v[4:5] op_sel:[1,0] op_sel_hi:[1,1]
	v_pk_fma_f32 v[94:95], v[40:41], v[6:7], v[94:95] op_sel:[0,0,0] op_sel_hi:[0,1,1]
	v_pk_fma_f32 v[96:97], v[40:41], v[8:9], v[96:97] op_sel:[1,0,0] op_sel_hi:[1,1,1]
	v_pk_fma_f32 v[94:95], v[42:43], v[10:11], v[94:95] op_sel:[0,0,0] op_sel_hi:[0,1,1]
	v_pk_fma_f32 v[96:97], v[42:43], v[12:13], v[96:97] op_sel:[1,0,0] op_sel_hi:[1,1,1]
	v_pk_fma_f32 v[94:95], v[44:45], v[14:15], v[94:95] op_sel:[0,0,0] op_sel_hi:[0,1,1]
	v_pk_fma_f32 v[96:97], v[44:45], v[16:17], v[96:97] op_sel:[1,0,0] op_sel_hi:[1,1,1]
	v_pk_mul_f32 v[112:113], v[26:27], v[2:3] op_sel:[0,0] op_sel_hi:[0,1]
	v_pk_add_f32 v[94:95], v[94:95], v[96:97]
	v_pk_mul_f32 v[114:115], v[26:27], v[4:5] op_sel:[1,0] op_sel_hi:[1,1]
	v_pk_fma_f32 v[112:113], v[28:29], v[6:7], v[112:113] op_sel:[0,0,0] op_sel_hi:[0,1,1]
	v_add_f32_dpp v94, v94, v94 quad_perm:[1,0,3,2] row_mask:0xf bank_mask:0xf
	v_add_f32_dpp v95, v95, v95 quad_perm:[1,0,3,2] row_mask:0xf bank_mask:0xf
	v_pk_fma_f32 v[114:115], v[28:29], v[8:9], v[114:115] op_sel:[1,0,0] op_sel_hi:[1,1,1]
	v_add_f32_dpp v94, v94, v94 quad_perm:[2,3,0,1] row_mask:0xf bank_mask:0xf
	v_add_f32_dpp v95, v95, v95 quad_perm:[2,3,0,1] row_mask:0xf bank_mask:0xf
	v_pk_fma_f32 v[112:113], v[30:31], v[10:11], v[112:113] op_sel:[0,0,0] op_sel_hi:[0,1,1]
	v_add_f32_dpp v94, v94, v94 row_half_mirror row_mask:0xf bank_mask:0xf
	v_add_f32_dpp v95, v95, v95 row_half_mirror row_mask:0xf bank_mask:0xf
	v_pk_fma_f32 v[114:115], v[30:31], v[12:13], v[114:115] op_sel:[1,0,0] op_sel_hi:[1,1,1]
	v_add_f32_dpp v94, v94, v94 row_mirror row_mask:0xf bank_mask:0xf
	v_add_f32_dpp v95, v95, v95 row_mirror row_mask:0xf bank_mask:0xf
	v_pk_fma_f32 v[112:113], v[32:33], v[14:15], v[112:113] op_sel:[0,0,0] op_sel_hi:[0,1,1]
	v_pk_fma_f32 v[114:115], v[32:33], v[16:17], v[114:115] op_sel:[1,0,0] op_sel_hi:[1,1,1]
	s_nop 0
	v_pk_add_f32 v[112:113], v[112:113], v[114:115]
	v_pk_fma_f32 v[98:99], v[56:57], v[94:95], v[54:55] op_sel:[1,0,0] op_sel_hi:[1,1,1] neg_lo:[1,0,0] neg_hi:[1,0,0]
	s_nop 0
	v_pk_mul_f32 v[106:107], v[56:57], v[98:99] op_sel:[0,0] op_sel_hi:[0,1]
	ds_write_b64 v102, v[112:113] offset:38912
	ds_read_b128 v[18:21], v100 offset:23232
	ds_read_b128 v[22:25], v100 offset:23248
	ds_read_b128 v[26:29], v100 offset:23760
	ds_read_b128 v[30:33], v100 offset:23776
	ds_read_b64 v[34:35], v101 offset:36608
	ds_read_b64 v[36:37], v117 offset:38064
	v_pk_mul_f32 v[78:79], v[38:39], v[106:107] op_sel:[0,0] op_sel_hi:[0,1]
	v_pk_mul_f32 v[80:81], v[38:39], v[106:107] op_sel:[1,0] op_sel_hi:[1,1]
	v_pk_mul_f32 v[82:83], v[40:41], v[106:107] op_sel:[0,0] op_sel_hi:[0,1]
	v_pk_mul_f32 v[84:85], v[40:41], v[106:107] op_sel:[1,0] op_sel_hi:[1,1]
	v_pk_fma_f32 v[2:3], v[2:3], v[56:57], v[78:79] op_sel:[0,1,0] op_sel_hi:[1,1,1]
	v_pk_fma_f32 v[4:5], v[4:5], v[56:57], v[80:81] op_sel:[0,1,0] op_sel_hi:[1,1,1]
	v_pk_fma_f32 v[6:7], v[6:7], v[56:57], v[82:83] op_sel:[0,1,0] op_sel_hi:[1,1,1]
	v_pk_fma_f32 v[8:9], v[8:9], v[56:57], v[84:85] op_sel:[0,1,0] op_sel_hi:[1,1,1]
	v_pk_mul_f32 v[86:87], v[42:43], v[106:107] op_sel:[0,0] op_sel_hi:[0,1]
	v_pk_mul_f32 v[88:89], v[42:43], v[106:107] op_sel:[1,0] op_sel_hi:[1,1]
	v_pk_mul_f32 v[90:91], v[44:45], v[106:107] op_sel:[0,0] op_sel_hi:[0,1]
	v_pk_mul_f32 v[92:93], v[44:45], v[106:107] op_sel:[1,0] op_sel_hi:[1,1]
	v_pk_fma_f32 v[10:11], v[10:11], v[56:57], v[86:87] op_sel:[0,1,0] op_sel_hi:[1,1,1]
	v_pk_fma_f32 v[12:13], v[12:13], v[56:57], v[88:89] op_sel:[0,1,0] op_sel_hi:[1,1,1]
	v_pk_fma_f32 v[14:15], v[14:15], v[56:57], v[90:91] op_sel:[0,1,0] op_sel_hi:[1,1,1]
	v_pk_fma_f32 v[16:17], v[16:17], v[56:57], v[92:93] op_sel:[0,1,0] op_sel_hi:[1,1,1]
	s_waitcnt lgkmcnt(7)
	v_pk_mul_f32 v[94:95], v[58:59], v[2:3] op_sel:[0,0] op_sel_hi:[0,1]
	v_pk_mul_f32 v[96:97], v[58:59], v[4:5] op_sel:[1,0] op_sel_hi:[1,1]
	v_pk_fma_f32 v[94:95], v[60:61], v[6:7], v[94:95] op_sel:[0,0,0] op_sel_hi:[0,1,1]
	v_pk_fma_f32 v[96:97], v[60:61], v[8:9], v[96:97] op_sel:[1,0,0] op_sel_hi:[1,1,1]
	v_pk_fma_f32 v[94:95], v[62:63], v[10:11], v[94:95] op_sel:[0,0,0] op_sel_hi:[0,1,1]
	v_pk_fma_f32 v[96:97], v[62:63], v[12:13], v[96:97] op_sel:[1,0,0] op_sel_hi:[1,1,1]
	v_pk_fma_f32 v[94:95], v[64:65], v[14:15], v[94:95] op_sel:[0,0,0] op_sel_hi:[0,1,1]
	v_pk_fma_f32 v[96:97], v[64:65], v[16:17], v[96:97] op_sel:[1,0,0] op_sel_hi:[1,1,1]
	v_pk_mul_f32 v[108:109], v[46:47], v[2:3] op_sel:[0,0] op_sel_hi:[0,1]
	v_pk_add_f32 v[94:95], v[94:95], v[96:97]
	v_pk_mul_f32 v[110:111], v[46:47], v[4:5] op_sel:[1,0] op_sel_hi:[1,1]
	v_pk_fma_f32 v[108:109], v[48:49], v[6:7], v[108:109] op_sel:[0,0,0] op_sel_hi:[0,1,1]
	v_add_f32_dpp v94, v94, v94 quad_perm:[1,0,3,2] row_mask:0xf bank_mask:0xf
	v_add_f32_dpp v95, v95, v95 quad_perm:[1,0,3,2] row_mask:0xf bank_mask:0xf
	v_pk_fma_f32 v[110:111], v[48:49], v[8:9], v[110:111] op_sel:[1,0,0] op_sel_hi:[1,1,1]
	v_add_f32_dpp v94, v94, v94 quad_perm:[2,3,0,1] row_mask:0xf bank_mask:0xf
	v_add_f32_dpp v95, v95, v95 quad_perm:[2,3,0,1] row_mask:0xf bank_mask:0xf
	v_pk_fma_f32 v[108:109], v[50:51], v[10:11], v[108:109] op_sel:[0,0,0] op_sel_hi:[0,1,1]
	v_add_f32_dpp v94, v94, v94 row_half_mirror row_mask:0xf bank_mask:0xf
	v_add_f32_dpp v95, v95, v95 row_half_mirror row_mask:0xf bank_mask:0xf
	v_pk_fma_f32 v[110:111], v[50:51], v[12:13], v[110:111] op_sel:[1,0,0] op_sel_hi:[1,1,1]
	v_add_f32_dpp v94, v94, v94 row_mirror row_mask:0xf bank_mask:0xf
	v_add_f32_dpp v95, v95, v95 row_mirror row_mask:0xf bank_mask:0xf
	v_pk_fma_f32 v[108:109], v[52:53], v[14:15], v[108:109] op_sel:[0,0,0] op_sel_hi:[0,1,1]
	v_pk_fma_f32 v[110:111], v[52:53], v[16:17], v[110:111] op_sel:[1,0,0] op_sel_hi:[1,1,1]
	s_nop 0
	v_pk_add_f32 v[108:109], v[108:109], v[110:111]
	v_pk_fma_f32 v[98:99], v[76:77], v[94:95], v[74:75] op_sel:[1,0,0] op_sel_hi:[1,1,1] neg_lo:[1,0,0] neg_hi:[1,0,0]
	s_nop 0
	v_pk_mul_f32 v[106:107], v[76:77], v[98:99] op_sel:[0,0] op_sel_hi:[0,1]
	ds_write_b64 v102, v[108:109] offset:40960
	ds_read_b128 v[38:41], v100 offset:24288
	ds_read_b128 v[42:45], v100 offset:24304
	ds_read_b128 v[46:49], v100 offset:24816
	ds_read_b128 v[50:53], v100 offset:24832
	ds_read_b64 v[54:55], v101 offset:36736
	ds_read_b64 v[56:57], v117 offset:38072
	v_pk_mul_f32 v[78:79], v[58:59], v[106:107] op_sel:[0,0] op_sel_hi:[0,1]
	v_pk_mul_f32 v[80:81], v[58:59], v[106:107] op_sel:[1,0] op_sel_hi:[1,1]
	v_pk_mul_f32 v[82:83], v[60:61], v[106:107] op_sel:[0,0] op_sel_hi:[0,1]
	v_pk_mul_f32 v[84:85], v[60:61], v[106:107] op_sel:[1,0] op_sel_hi:[1,1]
	v_pk_fma_f32 v[2:3], v[2:3], v[76:77], v[78:79] op_sel:[0,1,0] op_sel_hi:[1,1,1]
	v_pk_fma_f32 v[4:5], v[4:5], v[76:77], v[80:81] op_sel:[0,1,0] op_sel_hi:[1,1,1]
	v_pk_fma_f32 v[6:7], v[6:7], v[76:77], v[82:83] op_sel:[0,1,0] op_sel_hi:[1,1,1]
	v_pk_fma_f32 v[8:9], v[8:9], v[76:77], v[84:85] op_sel:[0,1,0] op_sel_hi:[1,1,1]
	v_pk_mul_f32 v[86:87], v[62:63], v[106:107] op_sel:[0,0] op_sel_hi:[0,1]
	v_pk_mul_f32 v[88:89], v[62:63], v[106:107] op_sel:[1,0] op_sel_hi:[1,1]
	v_pk_mul_f32 v[90:91], v[64:65], v[106:107] op_sel:[0,0] op_sel_hi:[0,1]
	v_pk_mul_f32 v[92:93], v[64:65], v[106:107] op_sel:[1,0] op_sel_hi:[1,1]
	v_pk_fma_f32 v[10:11], v[10:11], v[76:77], v[86:87] op_sel:[0,1,0] op_sel_hi:[1,1,1]
	v_pk_fma_f32 v[12:13], v[12:13], v[76:77], v[88:89] op_sel:[0,1,0] op_sel_hi:[1,1,1]
	v_pk_fma_f32 v[14:15], v[14:15], v[76:77], v[90:91] op_sel:[0,1,0] op_sel_hi:[1,1,1]
	v_pk_fma_f32 v[16:17], v[16:17], v[76:77], v[92:93] op_sel:[0,1,0] op_sel_hi:[1,1,1]
	s_waitcnt lgkmcnt(7)
	v_pk_mul_f32 v[94:95], v[18:19], v[2:3] op_sel:[0,0] op_sel_hi:[0,1]
	v_pk_mul_f32 v[96:97], v[18:19], v[4:5] op_sel:[1,0] op_sel_hi:[1,1]
	v_pk_fma_f32 v[94:95], v[20:21], v[6:7], v[94:95] op_sel:[0,0,0] op_sel_hi:[0,1,1]
	v_pk_fma_f32 v[96:97], v[20:21], v[8:9], v[96:97] op_sel:[1,0,0] op_sel_hi:[1,1,1]
	v_pk_fma_f32 v[94:95], v[22:23], v[10:11], v[94:95] op_sel:[0,0,0] op_sel_hi:[0,1,1]
	v_pk_fma_f32 v[96:97], v[22:23], v[12:13], v[96:97] op_sel:[1,0,0] op_sel_hi:[1,1,1]
	v_pk_fma_f32 v[94:95], v[24:25], v[14:15], v[94:95] op_sel:[0,0,0] op_sel_hi:[0,1,1]
	v_pk_fma_f32 v[96:97], v[24:25], v[16:17], v[96:97] op_sel:[1,0,0] op_sel_hi:[1,1,1]
	v_pk_mul_f32 v[112:113], v[66:67], v[2:3] op_sel:[0,0] op_sel_hi:[0,1]
	v_pk_add_f32 v[94:95], v[94:95], v[96:97]
	v_pk_mul_f32 v[114:115], v[66:67], v[4:5] op_sel:[1,0] op_sel_hi:[1,1]
	v_pk_fma_f32 v[112:113], v[68:69], v[6:7], v[112:113] op_sel:[0,0,0] op_sel_hi:[0,1,1]
	v_add_f32_dpp v94, v94, v94 quad_perm:[1,0,3,2] row_mask:0xf bank_mask:0xf
	v_add_f32_dpp v95, v95, v95 quad_perm:[1,0,3,2] row_mask:0xf bank_mask:0xf
	v_pk_fma_f32 v[114:115], v[68:69], v[8:9], v[114:115] op_sel:[1,0,0] op_sel_hi:[1,1,1]
	v_add_f32_dpp v94, v94, v94 quad_perm:[2,3,0,1] row_mask:0xf bank_mask:0xf
	v_add_f32_dpp v95, v95, v95 quad_perm:[2,3,0,1] row_mask:0xf bank_mask:0xf
	v_pk_fma_f32 v[112:113], v[70:71], v[10:11], v[112:113] op_sel:[0,0,0] op_sel_hi:[0,1,1]
	v_add_f32_dpp v94, v94, v94 row_half_mirror row_mask:0xf bank_mask:0xf
	v_add_f32_dpp v95, v95, v95 row_half_mirror row_mask:0xf bank_mask:0xf
	v_pk_fma_f32 v[114:115], v[70:71], v[12:13], v[114:115] op_sel:[1,0,0] op_sel_hi:[1,1,1]
	v_add_f32_dpp v94, v94, v94 row_mirror row_mask:0xf bank_mask:0xf
	v_add_f32_dpp v95, v95, v95 row_mirror row_mask:0xf bank_mask:0xf
	v_pk_fma_f32 v[112:113], v[72:73], v[14:15], v[112:113] op_sel:[0,0,0] op_sel_hi:[0,1,1]
	v_pk_fma_f32 v[114:115], v[72:73], v[16:17], v[114:115] op_sel:[1,0,0] op_sel_hi:[1,1,1]
	s_nop 0
	v_pk_add_f32 v[112:113], v[112:113], v[114:115]
	v_pk_fma_f32 v[98:99], v[36:37], v[94:95], v[34:35] op_sel:[1,0,0] op_sel_hi:[1,1,1] neg_lo:[1,0,0] neg_hi:[1,0,0]
	s_nop 0
	v_pk_mul_f32 v[106:107], v[36:37], v[98:99] op_sel:[0,0] op_sel_hi:[0,1]
	ds_write_b64 v102, v[112:113] offset:43008
	ds_read_b128 v[58:61], v100 offset:25344
	ds_read_b128 v[62:65], v100 offset:25360
	ds_read_b128 v[66:69], v100 offset:25872
	ds_read_b128 v[70:73], v100 offset:25888
	ds_read_b64 v[74:75], v101 offset:36864
	ds_read_b64 v[76:77], v117 offset:38080
	v_pk_mul_f32 v[78:79], v[18:19], v[106:107] op_sel:[0,0] op_sel_hi:[0,1]
	v_pk_mul_f32 v[80:81], v[18:19], v[106:107] op_sel:[1,0] op_sel_hi:[1,1]
	v_pk_mul_f32 v[82:83], v[20:21], v[106:107] op_sel:[0,0] op_sel_hi:[0,1]
	v_pk_mul_f32 v[84:85], v[20:21], v[106:107] op_sel:[1,0] op_sel_hi:[1,1]
	v_pk_fma_f32 v[2:3], v[2:3], v[36:37], v[78:79] op_sel:[0,1,0] op_sel_hi:[1,1,1]
	v_pk_fma_f32 v[4:5], v[4:5], v[36:37], v[80:81] op_sel:[0,1,0] op_sel_hi:[1,1,1]
	v_pk_fma_f32 v[6:7], v[6:7], v[36:37], v[82:83] op_sel:[0,1,0] op_sel_hi:[1,1,1]
	v_pk_fma_f32 v[8:9], v[8:9], v[36:37], v[84:85] op_sel:[0,1,0] op_sel_hi:[1,1,1]
	v_pk_mul_f32 v[86:87], v[22:23], v[106:107] op_sel:[0,0] op_sel_hi:[0,1]
	v_pk_mul_f32 v[88:89], v[22:23], v[106:107] op_sel:[1,0] op_sel_hi:[1,1]
	v_pk_mul_f32 v[90:91], v[24:25], v[106:107] op_sel:[0,0] op_sel_hi:[0,1]
	v_pk_mul_f32 v[92:93], v[24:25], v[106:107] op_sel:[1,0] op_sel_hi:[1,1]
	v_pk_fma_f32 v[10:11], v[10:11], v[36:37], v[86:87] op_sel:[0,1,0] op_sel_hi:[1,1,1]
	v_pk_fma_f32 v[12:13], v[12:13], v[36:37], v[88:89] op_sel:[0,1,0] op_sel_hi:[1,1,1]
	v_pk_fma_f32 v[14:15], v[14:15], v[36:37], v[90:91] op_sel:[0,1,0] op_sel_hi:[1,1,1]
	v_pk_fma_f32 v[16:17], v[16:17], v[36:37], v[92:93] op_sel:[0,1,0] op_sel_hi:[1,1,1]
	s_waitcnt lgkmcnt(7)
	v_pk_mul_f32 v[94:95], v[38:39], v[2:3] op_sel:[0,0] op_sel_hi:[0,1]
	v_pk_mul_f32 v[96:97], v[38:39], v[4:5] op_sel:[1,0] op_sel_hi:[1,1]
	v_pk_fma_f32 v[94:95], v[40:41], v[6:7], v[94:95] op_sel:[0,0,0] op_sel_hi:[0,1,1]
	v_pk_fma_f32 v[96:97], v[40:41], v[8:9], v[96:97] op_sel:[1,0,0] op_sel_hi:[1,1,1]
	v_pk_fma_f32 v[94:95], v[42:43], v[10:11], v[94:95] op_sel:[0,0,0] op_sel_hi:[0,1,1]
	v_pk_fma_f32 v[96:97], v[42:43], v[12:13], v[96:97] op_sel:[1,0,0] op_sel_hi:[1,1,1]
	v_pk_fma_f32 v[94:95], v[44:45], v[14:15], v[94:95] op_sel:[0,0,0] op_sel_hi:[0,1,1]
	v_pk_fma_f32 v[96:97], v[44:45], v[16:17], v[96:97] op_sel:[1,0,0] op_sel_hi:[1,1,1]
	v_pk_mul_f32 v[108:109], v[26:27], v[2:3] op_sel:[0,0] op_sel_hi:[0,1]
	v_pk_add_f32 v[94:95], v[94:95], v[96:97]
	v_pk_mul_f32 v[110:111], v[26:27], v[4:5] op_sel:[1,0] op_sel_hi:[1,1]
	v_pk_fma_f32 v[108:109], v[28:29], v[6:7], v[108:109] op_sel:[0,0,0] op_sel_hi:[0,1,1]
	v_add_f32_dpp v94, v94, v94 quad_perm:[1,0,3,2] row_mask:0xf bank_mask:0xf
	v_add_f32_dpp v95, v95, v95 quad_perm:[1,0,3,2] row_mask:0xf bank_mask:0xf
	v_pk_fma_f32 v[110:111], v[28:29], v[8:9], v[110:111] op_sel:[1,0,0] op_sel_hi:[1,1,1]
	v_add_f32_dpp v94, v94, v94 quad_perm:[2,3,0,1] row_mask:0xf bank_mask:0xf
	v_add_f32_dpp v95, v95, v95 quad_perm:[2,3,0,1] row_mask:0xf bank_mask:0xf
	v_pk_fma_f32 v[108:109], v[30:31], v[10:11], v[108:109] op_sel:[0,0,0] op_sel_hi:[0,1,1]
	v_add_f32_dpp v94, v94, v94 row_half_mirror row_mask:0xf bank_mask:0xf
	v_add_f32_dpp v95, v95, v95 row_half_mirror row_mask:0xf bank_mask:0xf
	v_pk_fma_f32 v[110:111], v[30:31], v[12:13], v[110:111] op_sel:[1,0,0] op_sel_hi:[1,1,1]
	v_add_f32_dpp v94, v94, v94 row_mirror row_mask:0xf bank_mask:0xf
	v_add_f32_dpp v95, v95, v95 row_mirror row_mask:0xf bank_mask:0xf
	v_pk_fma_f32 v[108:109], v[32:33], v[14:15], v[108:109] op_sel:[0,0,0] op_sel_hi:[0,1,1]
	v_pk_fma_f32 v[110:111], v[32:33], v[16:17], v[110:111] op_sel:[1,0,0] op_sel_hi:[1,1,1]
	s_nop 0
	v_pk_add_f32 v[108:109], v[108:109], v[110:111]
	v_pk_fma_f32 v[98:99], v[56:57], v[94:95], v[54:55] op_sel:[1,0,0] op_sel_hi:[1,1,1] neg_lo:[1,0,0] neg_hi:[1,0,0]
	s_nop 0
	v_pk_mul_f32 v[106:107], v[56:57], v[98:99] op_sel:[0,0] op_sel_hi:[0,1]
	ds_write_b64 v102, v[108:109] offset:45056
	ds_read_b128 v[18:21], v100 offset:26400
	ds_read_b128 v[22:25], v100 offset:26416
	ds_read_b128 v[26:29], v100 offset:26928
	ds_read_b128 v[30:33], v100 offset:26944
	ds_read_b64 v[34:35], v101 offset:36992
	ds_read_b64 v[36:37], v117 offset:38088
	v_pk_mul_f32 v[78:79], v[38:39], v[106:107] op_sel:[0,0] op_sel_hi:[0,1]
	v_pk_mul_f32 v[80:81], v[38:39], v[106:107] op_sel:[1,0] op_sel_hi:[1,1]
	v_pk_mul_f32 v[82:83], v[40:41], v[106:107] op_sel:[0,0] op_sel_hi:[0,1]
	v_pk_mul_f32 v[84:85], v[40:41], v[106:107] op_sel:[1,0] op_sel_hi:[1,1]
	v_pk_fma_f32 v[2:3], v[2:3], v[56:57], v[78:79] op_sel:[0,1,0] op_sel_hi:[1,1,1]
	v_pk_fma_f32 v[4:5], v[4:5], v[56:57], v[80:81] op_sel:[0,1,0] op_sel_hi:[1,1,1]
	v_pk_fma_f32 v[6:7], v[6:7], v[56:57], v[82:83] op_sel:[0,1,0] op_sel_hi:[1,1,1]
	v_pk_fma_f32 v[8:9], v[8:9], v[56:57], v[84:85] op_sel:[0,1,0] op_sel_hi:[1,1,1]
	v_pk_mul_f32 v[86:87], v[42:43], v[106:107] op_sel:[0,0] op_sel_hi:[0,1]
	v_pk_mul_f32 v[88:89], v[42:43], v[106:107] op_sel:[1,0] op_sel_hi:[1,1]
	v_pk_mul_f32 v[90:91], v[44:45], v[106:107] op_sel:[0,0] op_sel_hi:[0,1]
	v_pk_mul_f32 v[92:93], v[44:45], v[106:107] op_sel:[1,0] op_sel_hi:[1,1]
	v_pk_fma_f32 v[10:11], v[10:11], v[56:57], v[86:87] op_sel:[0,1,0] op_sel_hi:[1,1,1]
	v_pk_fma_f32 v[12:13], v[12:13], v[56:57], v[88:89] op_sel:[0,1,0] op_sel_hi:[1,1,1]
	v_pk_fma_f32 v[14:15], v[14:15], v[56:57], v[90:91] op_sel:[0,1,0] op_sel_hi:[1,1,1]
	v_pk_fma_f32 v[16:17], v[16:17], v[56:57], v[92:93] op_sel:[0,1,0] op_sel_hi:[1,1,1]
	s_waitcnt lgkmcnt(7)
	v_pk_mul_f32 v[94:95], v[58:59], v[2:3] op_sel:[0,0] op_sel_hi:[0,1]
	v_pk_mul_f32 v[96:97], v[58:59], v[4:5] op_sel:[1,0] op_sel_hi:[1,1]
	v_pk_fma_f32 v[94:95], v[60:61], v[6:7], v[94:95] op_sel:[0,0,0] op_sel_hi:[0,1,1]
	v_pk_fma_f32 v[96:97], v[60:61], v[8:9], v[96:97] op_sel:[1,0,0] op_sel_hi:[1,1,1]
	v_pk_fma_f32 v[94:95], v[62:63], v[10:11], v[94:95] op_sel:[0,0,0] op_sel_hi:[0,1,1]
	v_pk_fma_f32 v[96:97], v[62:63], v[12:13], v[96:97] op_sel:[1,0,0] op_sel_hi:[1,1,1]
	v_pk_fma_f32 v[94:95], v[64:65], v[14:15], v[94:95] op_sel:[0,0,0] op_sel_hi:[0,1,1]
	v_pk_fma_f32 v[96:97], v[64:65], v[16:17], v[96:97] op_sel:[1,0,0] op_sel_hi:[1,1,1]
	v_pk_mul_f32 v[112:113], v[46:47], v[2:3] op_sel:[0,0] op_sel_hi:[0,1]
	v_pk_add_f32 v[94:95], v[94:95], v[96:97]
	v_pk_mul_f32 v[114:115], v[46:47], v[4:5] op_sel:[1,0] op_sel_hi:[1,1]
	v_pk_fma_f32 v[112:113], v[48:49], v[6:7], v[112:113] op_sel:[0,0,0] op_sel_hi:[0,1,1]
	v_add_f32_dpp v94, v94, v94 quad_perm:[1,0,3,2] row_mask:0xf bank_mask:0xf
	v_add_f32_dpp v95, v95, v95 quad_perm:[1,0,3,2] row_mask:0xf bank_mask:0xf
	v_pk_fma_f32 v[114:115], v[48:49], v[8:9], v[114:115] op_sel:[1,0,0] op_sel_hi:[1,1,1]
	v_add_f32_dpp v94, v94, v94 quad_perm:[2,3,0,1] row_mask:0xf bank_mask:0xf
	v_add_f32_dpp v95, v95, v95 quad_perm:[2,3,0,1] row_mask:0xf bank_mask:0xf
	v_pk_fma_f32 v[112:113], v[50:51], v[10:11], v[112:113] op_sel:[0,0,0] op_sel_hi:[0,1,1]
	v_add_f32_dpp v94, v94, v94 row_half_mirror row_mask:0xf bank_mask:0xf
	v_add_f32_dpp v95, v95, v95 row_half_mirror row_mask:0xf bank_mask:0xf
	v_pk_fma_f32 v[114:115], v[50:51], v[12:13], v[114:115] op_sel:[1,0,0] op_sel_hi:[1,1,1]
	v_add_f32_dpp v94, v94, v94 row_mirror row_mask:0xf bank_mask:0xf
	v_add_f32_dpp v95, v95, v95 row_mirror row_mask:0xf bank_mask:0xf
	v_pk_fma_f32 v[112:113], v[52:53], v[14:15], v[112:113] op_sel:[0,0,0] op_sel_hi:[0,1,1]
	v_pk_fma_f32 v[114:115], v[52:53], v[16:17], v[114:115] op_sel:[1,0,0] op_sel_hi:[1,1,1]
	s_nop 0
	v_pk_add_f32 v[112:113], v[112:113], v[114:115]
	v_pk_fma_f32 v[98:99], v[76:77], v[94:95], v[74:75] op_sel:[1,0,0] op_sel_hi:[1,1,1] neg_lo:[1,0,0] neg_hi:[1,0,0]
	s_nop 0
	v_pk_mul_f32 v[106:107], v[76:77], v[98:99] op_sel:[0,0] op_sel_hi:[0,1]
	ds_write_b64 v102, v[112:113] offset:47104
	ds_read_b128 v[38:41], v100 offset:27456
	ds_read_b128 v[42:45], v100 offset:27472
	ds_read_b128 v[46:49], v100 offset:27984
	ds_read_b128 v[50:53], v100 offset:28000
	ds_read_b64 v[54:55], v101 offset:37120
	ds_read_b64 v[56:57], v117 offset:38096
	v_pk_mul_f32 v[78:79], v[58:59], v[106:107] op_sel:[0,0] op_sel_hi:[0,1]
	v_pk_mul_f32 v[80:81], v[58:59], v[106:107] op_sel:[1,0] op_sel_hi:[1,1]
	v_pk_mul_f32 v[82:83], v[60:61], v[106:107] op_sel:[0,0] op_sel_hi:[0,1]
	v_pk_mul_f32 v[84:85], v[60:61], v[106:107] op_sel:[1,0] op_sel_hi:[1,1]
	v_pk_fma_f32 v[2:3], v[2:3], v[76:77], v[78:79] op_sel:[0,1,0] op_sel_hi:[1,1,1]
	v_pk_fma_f32 v[4:5], v[4:5], v[76:77], v[80:81] op_sel:[0,1,0] op_sel_hi:[1,1,1]
	v_pk_fma_f32 v[6:7], v[6:7], v[76:77], v[82:83] op_sel:[0,1,0] op_sel_hi:[1,1,1]
	v_pk_fma_f32 v[8:9], v[8:9], v[76:77], v[84:85] op_sel:[0,1,0] op_sel_hi:[1,1,1]
	v_pk_mul_f32 v[86:87], v[62:63], v[106:107] op_sel:[0,0] op_sel_hi:[0,1]
	v_pk_mul_f32 v[88:89], v[62:63], v[106:107] op_sel:[1,0] op_sel_hi:[1,1]
	v_pk_mul_f32 v[90:91], v[64:65], v[106:107] op_sel:[0,0] op_sel_hi:[0,1]
	v_pk_mul_f32 v[92:93], v[64:65], v[106:107] op_sel:[1,0] op_sel_hi:[1,1]
	v_pk_fma_f32 v[10:11], v[10:11], v[76:77], v[86:87] op_sel:[0,1,0] op_sel_hi:[1,1,1]
	v_pk_fma_f32 v[12:13], v[12:13], v[76:77], v[88:89] op_sel:[0,1,0] op_sel_hi:[1,1,1]
	v_pk_fma_f32 v[14:15], v[14:15], v[76:77], v[90:91] op_sel:[0,1,0] op_sel_hi:[1,1,1]
	v_pk_fma_f32 v[16:17], v[16:17], v[76:77], v[92:93] op_sel:[0,1,0] op_sel_hi:[1,1,1]
	s_waitcnt lgkmcnt(7)
	v_pk_mul_f32 v[94:95], v[18:19], v[2:3] op_sel:[0,0] op_sel_hi:[0,1]
	v_pk_mul_f32 v[96:97], v[18:19], v[4:5] op_sel:[1,0] op_sel_hi:[1,1]
	v_pk_fma_f32 v[94:95], v[20:21], v[6:7], v[94:95] op_sel:[0,0,0] op_sel_hi:[0,1,1]
	v_pk_fma_f32 v[96:97], v[20:21], v[8:9], v[96:97] op_sel:[1,0,0] op_sel_hi:[1,1,1]
	v_pk_fma_f32 v[94:95], v[22:23], v[10:11], v[94:95] op_sel:[0,0,0] op_sel_hi:[0,1,1]
	v_pk_fma_f32 v[96:97], v[22:23], v[12:13], v[96:97] op_sel:[1,0,0] op_sel_hi:[1,1,1]
	v_pk_fma_f32 v[94:95], v[24:25], v[14:15], v[94:95] op_sel:[0,0,0] op_sel_hi:[0,1,1]
	v_pk_fma_f32 v[96:97], v[24:25], v[16:17], v[96:97] op_sel:[1,0,0] op_sel_hi:[1,1,1]
	v_pk_mul_f32 v[108:109], v[66:67], v[2:3] op_sel:[0,0] op_sel_hi:[0,1]
	v_pk_add_f32 v[94:95], v[94:95], v[96:97]
	v_pk_mul_f32 v[110:111], v[66:67], v[4:5] op_sel:[1,0] op_sel_hi:[1,1]
	v_pk_fma_f32 v[108:109], v[68:69], v[6:7], v[108:109] op_sel:[0,0,0] op_sel_hi:[0,1,1]
	v_add_f32_dpp v94, v94, v94 quad_perm:[1,0,3,2] row_mask:0xf bank_mask:0xf
	v_add_f32_dpp v95, v95, v95 quad_perm:[1,0,3,2] row_mask:0xf bank_mask:0xf
	v_pk_fma_f32 v[110:111], v[68:69], v[8:9], v[110:111] op_sel:[1,0,0] op_sel_hi:[1,1,1]
	v_add_f32_dpp v94, v94, v94 quad_perm:[2,3,0,1] row_mask:0xf bank_mask:0xf
	v_add_f32_dpp v95, v95, v95 quad_perm:[2,3,0,1] row_mask:0xf bank_mask:0xf
	v_pk_fma_f32 v[108:109], v[70:71], v[10:11], v[108:109] op_sel:[0,0,0] op_sel_hi:[0,1,1]
	v_add_f32_dpp v94, v94, v94 row_half_mirror row_mask:0xf bank_mask:0xf
	v_add_f32_dpp v95, v95, v95 row_half_mirror row_mask:0xf bank_mask:0xf
	v_pk_fma_f32 v[110:111], v[70:71], v[12:13], v[110:111] op_sel:[1,0,0] op_sel_hi:[1,1,1]
	v_add_f32_dpp v94, v94, v94 row_mirror row_mask:0xf bank_mask:0xf
	v_add_f32_dpp v95, v95, v95 row_mirror row_mask:0xf bank_mask:0xf
	v_pk_fma_f32 v[108:109], v[72:73], v[14:15], v[108:109] op_sel:[0,0,0] op_sel_hi:[0,1,1]
	v_pk_fma_f32 v[110:111], v[72:73], v[16:17], v[110:111] op_sel:[1,0,0] op_sel_hi:[1,1,1]
	s_nop 0
	v_pk_add_f32 v[108:109], v[108:109], v[110:111]
	v_pk_fma_f32 v[98:99], v[36:37], v[94:95], v[34:35] op_sel:[1,0,0] op_sel_hi:[1,1,1] neg_lo:[1,0,0] neg_hi:[1,0,0]
	s_nop 0
	v_pk_mul_f32 v[106:107], v[36:37], v[98:99] op_sel:[0,0] op_sel_hi:[0,1]
	ds_write_b64 v102, v[108:109] offset:49152
	ds_read_b128 v[58:61], v100 offset:28512
	ds_read_b128 v[62:65], v100 offset:28528
	ds_read_b128 v[66:69], v100 offset:29040
	ds_read_b128 v[70:73], v100 offset:29056
	ds_read_b64 v[74:75], v101 offset:37248
	ds_read_b64 v[76:77], v117 offset:38104
	v_pk_mul_f32 v[78:79], v[18:19], v[106:107] op_sel:[0,0] op_sel_hi:[0,1]
	v_pk_mul_f32 v[80:81], v[18:19], v[106:107] op_sel:[1,0] op_sel_hi:[1,1]
	v_pk_mul_f32 v[82:83], v[20:21], v[106:107] op_sel:[0,0] op_sel_hi:[0,1]
	v_pk_mul_f32 v[84:85], v[20:21], v[106:107] op_sel:[1,0] op_sel_hi:[1,1]
	v_pk_fma_f32 v[2:3], v[2:3], v[36:37], v[78:79] op_sel:[0,1,0] op_sel_hi:[1,1,1]
	v_pk_fma_f32 v[4:5], v[4:5], v[36:37], v[80:81] op_sel:[0,1,0] op_sel_hi:[1,1,1]
	v_pk_fma_f32 v[6:7], v[6:7], v[36:37], v[82:83] op_sel:[0,1,0] op_sel_hi:[1,1,1]
	v_pk_fma_f32 v[8:9], v[8:9], v[36:37], v[84:85] op_sel:[0,1,0] op_sel_hi:[1,1,1]
	v_pk_mul_f32 v[86:87], v[22:23], v[106:107] op_sel:[0,0] op_sel_hi:[0,1]
	v_pk_mul_f32 v[88:89], v[22:23], v[106:107] op_sel:[1,0] op_sel_hi:[1,1]
	v_pk_mul_f32 v[90:91], v[24:25], v[106:107] op_sel:[0,0] op_sel_hi:[0,1]
	v_pk_mul_f32 v[92:93], v[24:25], v[106:107] op_sel:[1,0] op_sel_hi:[1,1]
	v_pk_fma_f32 v[10:11], v[10:11], v[36:37], v[86:87] op_sel:[0,1,0] op_sel_hi:[1,1,1]
	v_pk_fma_f32 v[12:13], v[12:13], v[36:37], v[88:89] op_sel:[0,1,0] op_sel_hi:[1,1,1]
	v_pk_fma_f32 v[14:15], v[14:15], v[36:37], v[90:91] op_sel:[0,1,0] op_sel_hi:[1,1,1]
	v_pk_fma_f32 v[16:17], v[16:17], v[36:37], v[92:93] op_sel:[0,1,0] op_sel_hi:[1,1,1]
	s_waitcnt lgkmcnt(7)
	v_pk_mul_f32 v[94:95], v[38:39], v[2:3] op_sel:[0,0] op_sel_hi:[0,1]
	v_pk_mul_f32 v[96:97], v[38:39], v[4:5] op_sel:[1,0] op_sel_hi:[1,1]
	v_pk_fma_f32 v[94:95], v[40:41], v[6:7], v[94:95] op_sel:[0,0,0] op_sel_hi:[0,1,1]
	v_pk_fma_f32 v[96:97], v[40:41], v[8:9], v[96:97] op_sel:[1,0,0] op_sel_hi:[1,1,1]
	v_pk_fma_f32 v[94:95], v[42:43], v[10:11], v[94:95] op_sel:[0,0,0] op_sel_hi:[0,1,1]
	v_pk_fma_f32 v[96:97], v[42:43], v[12:13], v[96:97] op_sel:[1,0,0] op_sel_hi:[1,1,1]
	v_pk_fma_f32 v[94:95], v[44:45], v[14:15], v[94:95] op_sel:[0,0,0] op_sel_hi:[0,1,1]
	v_pk_fma_f32 v[96:97], v[44:45], v[16:17], v[96:97] op_sel:[1,0,0] op_sel_hi:[1,1,1]
	v_pk_mul_f32 v[112:113], v[26:27], v[2:3] op_sel:[0,0] op_sel_hi:[0,1]
	v_pk_add_f32 v[94:95], v[94:95], v[96:97]
	v_pk_mul_f32 v[114:115], v[26:27], v[4:5] op_sel:[1,0] op_sel_hi:[1,1]
	v_pk_fma_f32 v[112:113], v[28:29], v[6:7], v[112:113] op_sel:[0,0,0] op_sel_hi:[0,1,1]
	v_add_f32_dpp v94, v94, v94 quad_perm:[1,0,3,2] row_mask:0xf bank_mask:0xf
	v_add_f32_dpp v95, v95, v95 quad_perm:[1,0,3,2] row_mask:0xf bank_mask:0xf
	v_pk_fma_f32 v[114:115], v[28:29], v[8:9], v[114:115] op_sel:[1,0,0] op_sel_hi:[1,1,1]
	v_add_f32_dpp v94, v94, v94 quad_perm:[2,3,0,1] row_mask:0xf bank_mask:0xf
	v_add_f32_dpp v95, v95, v95 quad_perm:[2,3,0,1] row_mask:0xf bank_mask:0xf
	v_pk_fma_f32 v[112:113], v[30:31], v[10:11], v[112:113] op_sel:[0,0,0] op_sel_hi:[0,1,1]
	v_add_f32_dpp v94, v94, v94 row_half_mirror row_mask:0xf bank_mask:0xf
	v_add_f32_dpp v95, v95, v95 row_half_mirror row_mask:0xf bank_mask:0xf
	v_pk_fma_f32 v[114:115], v[30:31], v[12:13], v[114:115] op_sel:[1,0,0] op_sel_hi:[1,1,1]
	v_add_f32_dpp v94, v94, v94 row_mirror row_mask:0xf bank_mask:0xf
	v_add_f32_dpp v95, v95, v95 row_mirror row_mask:0xf bank_mask:0xf
	v_pk_fma_f32 v[112:113], v[32:33], v[14:15], v[112:113] op_sel:[0,0,0] op_sel_hi:[0,1,1]
	v_pk_fma_f32 v[114:115], v[32:33], v[16:17], v[114:115] op_sel:[1,0,0] op_sel_hi:[1,1,1]
	s_nop 0
	v_pk_add_f32 v[112:113], v[112:113], v[114:115]
	v_pk_fma_f32 v[98:99], v[56:57], v[94:95], v[54:55] op_sel:[1,0,0] op_sel_hi:[1,1,1] neg_lo:[1,0,0] neg_hi:[1,0,0]
	s_nop 0
	v_pk_mul_f32 v[106:107], v[56:57], v[98:99] op_sel:[0,0] op_sel_hi:[0,1]
	ds_write_b64 v102, v[112:113] offset:51200
	ds_read_b128 v[18:21], v100 offset:29568
	ds_read_b128 v[22:25], v100 offset:29584
	ds_read_b128 v[26:29], v100 offset:30096
	ds_read_b128 v[30:33], v100 offset:30112
	ds_read_b64 v[34:35], v101 offset:37376
	ds_read_b64 v[36:37], v117 offset:38112
	v_pk_mul_f32 v[78:79], v[38:39], v[106:107] op_sel:[0,0] op_sel_hi:[0,1]
	v_pk_mul_f32 v[80:81], v[38:39], v[106:107] op_sel:[1,0] op_sel_hi:[1,1]
	v_pk_mul_f32 v[82:83], v[40:41], v[106:107] op_sel:[0,0] op_sel_hi:[0,1]
	v_pk_mul_f32 v[84:85], v[40:41], v[106:107] op_sel:[1,0] op_sel_hi:[1,1]
	v_pk_fma_f32 v[2:3], v[2:3], v[56:57], v[78:79] op_sel:[0,1,0] op_sel_hi:[1,1,1]
	v_pk_fma_f32 v[4:5], v[4:5], v[56:57], v[80:81] op_sel:[0,1,0] op_sel_hi:[1,1,1]
	v_pk_fma_f32 v[6:7], v[6:7], v[56:57], v[82:83] op_sel:[0,1,0] op_sel_hi:[1,1,1]
	v_pk_fma_f32 v[8:9], v[8:9], v[56:57], v[84:85] op_sel:[0,1,0] op_sel_hi:[1,1,1]
	v_pk_mul_f32 v[86:87], v[42:43], v[106:107] op_sel:[0,0] op_sel_hi:[0,1]
	v_pk_mul_f32 v[88:89], v[42:43], v[106:107] op_sel:[1,0] op_sel_hi:[1,1]
	v_pk_mul_f32 v[90:91], v[44:45], v[106:107] op_sel:[0,0] op_sel_hi:[0,1]
	v_pk_mul_f32 v[92:93], v[44:45], v[106:107] op_sel:[1,0] op_sel_hi:[1,1]
	v_pk_fma_f32 v[10:11], v[10:11], v[56:57], v[86:87] op_sel:[0,1,0] op_sel_hi:[1,1,1]
	v_pk_fma_f32 v[12:13], v[12:13], v[56:57], v[88:89] op_sel:[0,1,0] op_sel_hi:[1,1,1]
	v_pk_fma_f32 v[14:15], v[14:15], v[56:57], v[90:91] op_sel:[0,1,0] op_sel_hi:[1,1,1]
	v_pk_fma_f32 v[16:17], v[16:17], v[56:57], v[92:93] op_sel:[0,1,0] op_sel_hi:[1,1,1]
	s_waitcnt lgkmcnt(7)
	v_pk_mul_f32 v[94:95], v[58:59], v[2:3] op_sel:[0,0] op_sel_hi:[0,1]
	v_pk_mul_f32 v[96:97], v[58:59], v[4:5] op_sel:[1,0] op_sel_hi:[1,1]
	v_pk_fma_f32 v[94:95], v[60:61], v[6:7], v[94:95] op_sel:[0,0,0] op_sel_hi:[0,1,1]
	v_pk_fma_f32 v[96:97], v[60:61], v[8:9], v[96:97] op_sel:[1,0,0] op_sel_hi:[1,1,1]
	v_pk_fma_f32 v[94:95], v[62:63], v[10:11], v[94:95] op_sel:[0,0,0] op_sel_hi:[0,1,1]
	v_pk_fma_f32 v[96:97], v[62:63], v[12:13], v[96:97] op_sel:[1,0,0] op_sel_hi:[1,1,1]
	v_pk_fma_f32 v[94:95], v[64:65], v[14:15], v[94:95] op_sel:[0,0,0] op_sel_hi:[0,1,1]
	v_pk_fma_f32 v[96:97], v[64:65], v[16:17], v[96:97] op_sel:[1,0,0] op_sel_hi:[1,1,1]
	v_pk_mul_f32 v[108:109], v[46:47], v[2:3] op_sel:[0,0] op_sel_hi:[0,1]
	v_pk_add_f32 v[94:95], v[94:95], v[96:97]
	v_pk_mul_f32 v[110:111], v[46:47], v[4:5] op_sel:[1,0] op_sel_hi:[1,1]
	v_pk_fma_f32 v[108:109], v[48:49], v[6:7], v[108:109] op_sel:[0,0,0] op_sel_hi:[0,1,1]
	v_add_f32_dpp v94, v94, v94 quad_perm:[1,0,3,2] row_mask:0xf bank_mask:0xf
	v_add_f32_dpp v95, v95, v95 quad_perm:[1,0,3,2] row_mask:0xf bank_mask:0xf
	v_pk_fma_f32 v[110:111], v[48:49], v[8:9], v[110:111] op_sel:[1,0,0] op_sel_hi:[1,1,1]
	v_add_f32_dpp v94, v94, v94 quad_perm:[2,3,0,1] row_mask:0xf bank_mask:0xf
	v_add_f32_dpp v95, v95, v95 quad_perm:[2,3,0,1] row_mask:0xf bank_mask:0xf
	v_pk_fma_f32 v[108:109], v[50:51], v[10:11], v[108:109] op_sel:[0,0,0] op_sel_hi:[0,1,1]
	v_add_f32_dpp v94, v94, v94 row_half_mirror row_mask:0xf bank_mask:0xf
	v_add_f32_dpp v95, v95, v95 row_half_mirror row_mask:0xf bank_mask:0xf
	v_pk_fma_f32 v[110:111], v[50:51], v[12:13], v[110:111] op_sel:[1,0,0] op_sel_hi:[1,1,1]
	v_add_f32_dpp v94, v94, v94 row_mirror row_mask:0xf bank_mask:0xf
	v_add_f32_dpp v95, v95, v95 row_mirror row_mask:0xf bank_mask:0xf
	v_pk_fma_f32 v[108:109], v[52:53], v[14:15], v[108:109] op_sel:[0,0,0] op_sel_hi:[0,1,1]
	v_pk_fma_f32 v[110:111], v[52:53], v[16:17], v[110:111] op_sel:[1,0,0] op_sel_hi:[1,1,1]
	s_nop 0
	v_pk_add_f32 v[108:109], v[108:109], v[110:111]
	v_pk_fma_f32 v[98:99], v[76:77], v[94:95], v[74:75] op_sel:[1,0,0] op_sel_hi:[1,1,1] neg_lo:[1,0,0] neg_hi:[1,0,0]
	s_nop 0
	v_pk_mul_f32 v[106:107], v[76:77], v[98:99] op_sel:[0,0] op_sel_hi:[0,1]
	ds_write_b64 v102, v[108:109] offset:53248
	ds_read_b128 v[38:41], v100 offset:30624
	ds_read_b128 v[42:45], v100 offset:30640
	ds_read_b128 v[46:49], v100 offset:31152
	ds_read_b128 v[50:53], v100 offset:31168
	ds_read_b64 v[54:55], v101 offset:37504
	ds_read_b64 v[56:57], v117 offset:38120
	v_pk_mul_f32 v[78:79], v[58:59], v[106:107] op_sel:[0,0] op_sel_hi:[0,1]
	v_pk_mul_f32 v[80:81], v[58:59], v[106:107] op_sel:[1,0] op_sel_hi:[1,1]
	v_pk_mul_f32 v[82:83], v[60:61], v[106:107] op_sel:[0,0] op_sel_hi:[0,1]
	v_pk_mul_f32 v[84:85], v[60:61], v[106:107] op_sel:[1,0] op_sel_hi:[1,1]
	v_pk_fma_f32 v[2:3], v[2:3], v[76:77], v[78:79] op_sel:[0,1,0] op_sel_hi:[1,1,1]
	v_pk_fma_f32 v[4:5], v[4:5], v[76:77], v[80:81] op_sel:[0,1,0] op_sel_hi:[1,1,1]
	v_pk_fma_f32 v[6:7], v[6:7], v[76:77], v[82:83] op_sel:[0,1,0] op_sel_hi:[1,1,1]
	v_pk_fma_f32 v[8:9], v[8:9], v[76:77], v[84:85] op_sel:[0,1,0] op_sel_hi:[1,1,1]
	v_pk_mul_f32 v[86:87], v[62:63], v[106:107] op_sel:[0,0] op_sel_hi:[0,1]
	v_pk_mul_f32 v[88:89], v[62:63], v[106:107] op_sel:[1,0] op_sel_hi:[1,1]
	v_pk_mul_f32 v[90:91], v[64:65], v[106:107] op_sel:[0,0] op_sel_hi:[0,1]
	v_pk_mul_f32 v[92:93], v[64:65], v[106:107] op_sel:[1,0] op_sel_hi:[1,1]
	v_pk_fma_f32 v[10:11], v[10:11], v[76:77], v[86:87] op_sel:[0,1,0] op_sel_hi:[1,1,1]
	v_pk_fma_f32 v[12:13], v[12:13], v[76:77], v[88:89] op_sel:[0,1,0] op_sel_hi:[1,1,1]
	v_pk_fma_f32 v[14:15], v[14:15], v[76:77], v[90:91] op_sel:[0,1,0] op_sel_hi:[1,1,1]
	v_pk_fma_f32 v[16:17], v[16:17], v[76:77], v[92:93] op_sel:[0,1,0] op_sel_hi:[1,1,1]
	s_waitcnt lgkmcnt(7)
	v_pk_mul_f32 v[94:95], v[18:19], v[2:3] op_sel:[0,0] op_sel_hi:[0,1]
	v_pk_mul_f32 v[96:97], v[18:19], v[4:5] op_sel:[1,0] op_sel_hi:[1,1]
	v_pk_fma_f32 v[94:95], v[20:21], v[6:7], v[94:95] op_sel:[0,0,0] op_sel_hi:[0,1,1]
	v_pk_fma_f32 v[96:97], v[20:21], v[8:9], v[96:97] op_sel:[1,0,0] op_sel_hi:[1,1,1]
	v_pk_fma_f32 v[94:95], v[22:23], v[10:11], v[94:95] op_sel:[0,0,0] op_sel_hi:[0,1,1]
	v_pk_fma_f32 v[96:97], v[22:23], v[12:13], v[96:97] op_sel:[1,0,0] op_sel_hi:[1,1,1]
	v_pk_fma_f32 v[94:95], v[24:25], v[14:15], v[94:95] op_sel:[0,0,0] op_sel_hi:[0,1,1]
	v_pk_fma_f32 v[96:97], v[24:25], v[16:17], v[96:97] op_sel:[1,0,0] op_sel_hi:[1,1,1]
	v_pk_mul_f32 v[112:113], v[66:67], v[2:3] op_sel:[0,0] op_sel_hi:[0,1]
	v_pk_add_f32 v[94:95], v[94:95], v[96:97]
	v_pk_mul_f32 v[114:115], v[66:67], v[4:5] op_sel:[1,0] op_sel_hi:[1,1]
	v_pk_fma_f32 v[112:113], v[68:69], v[6:7], v[112:113] op_sel:[0,0,0] op_sel_hi:[0,1,1]
	v_add_f32_dpp v94, v94, v94 quad_perm:[1,0,3,2] row_mask:0xf bank_mask:0xf
	v_add_f32_dpp v95, v95, v95 quad_perm:[1,0,3,2] row_mask:0xf bank_mask:0xf
	v_pk_fma_f32 v[114:115], v[68:69], v[8:9], v[114:115] op_sel:[1,0,0] op_sel_hi:[1,1,1]
	v_add_f32_dpp v94, v94, v94 quad_perm:[2,3,0,1] row_mask:0xf bank_mask:0xf
	v_add_f32_dpp v95, v95, v95 quad_perm:[2,3,0,1] row_mask:0xf bank_mask:0xf
	v_pk_fma_f32 v[112:113], v[70:71], v[10:11], v[112:113] op_sel:[0,0,0] op_sel_hi:[0,1,1]
	v_add_f32_dpp v94, v94, v94 row_half_mirror row_mask:0xf bank_mask:0xf
	v_add_f32_dpp v95, v95, v95 row_half_mirror row_mask:0xf bank_mask:0xf
	v_pk_fma_f32 v[114:115], v[70:71], v[12:13], v[114:115] op_sel:[1,0,0] op_sel_hi:[1,1,1]
	v_add_f32_dpp v94, v94, v94 row_mirror row_mask:0xf bank_mask:0xf
	v_add_f32_dpp v95, v95, v95 row_mirror row_mask:0xf bank_mask:0xf
	v_pk_fma_f32 v[112:113], v[72:73], v[14:15], v[112:113] op_sel:[0,0,0] op_sel_hi:[0,1,1]
	v_pk_fma_f32 v[114:115], v[72:73], v[16:17], v[114:115] op_sel:[1,0,0] op_sel_hi:[1,1,1]
	s_nop 0
	v_pk_add_f32 v[112:113], v[112:113], v[114:115]
	v_pk_fma_f32 v[98:99], v[36:37], v[94:95], v[34:35] op_sel:[1,0,0] op_sel_hi:[1,1,1] neg_lo:[1,0,0] neg_hi:[1,0,0]
	s_nop 0
	v_pk_mul_f32 v[106:107], v[36:37], v[98:99] op_sel:[0,0] op_sel_hi:[0,1]
	ds_write_b64 v102, v[112:113] offset:55296
	ds_read_b128 v[58:61], v100 offset:31680
	ds_read_b128 v[62:65], v100 offset:31696
	ds_read_b128 v[66:69], v100 offset:32208
	ds_read_b128 v[70:73], v100 offset:32224
	ds_read_b64 v[74:75], v101 offset:37632
	ds_read_b64 v[76:77], v117 offset:38128
	v_pk_mul_f32 v[78:79], v[18:19], v[106:107] op_sel:[0,0] op_sel_hi:[0,1]
	v_pk_mul_f32 v[80:81], v[18:19], v[106:107] op_sel:[1,0] op_sel_hi:[1,1]
	v_pk_mul_f32 v[82:83], v[20:21], v[106:107] op_sel:[0,0] op_sel_hi:[0,1]
	v_pk_mul_f32 v[84:85], v[20:21], v[106:107] op_sel:[1,0] op_sel_hi:[1,1]
	v_pk_fma_f32 v[2:3], v[2:3], v[36:37], v[78:79] op_sel:[0,1,0] op_sel_hi:[1,1,1]
	v_pk_fma_f32 v[4:5], v[4:5], v[36:37], v[80:81] op_sel:[0,1,0] op_sel_hi:[1,1,1]
	v_pk_fma_f32 v[6:7], v[6:7], v[36:37], v[82:83] op_sel:[0,1,0] op_sel_hi:[1,1,1]
	v_pk_fma_f32 v[8:9], v[8:9], v[36:37], v[84:85] op_sel:[0,1,0] op_sel_hi:[1,1,1]
	v_pk_mul_f32 v[86:87], v[22:23], v[106:107] op_sel:[0,0] op_sel_hi:[0,1]
	v_pk_mul_f32 v[88:89], v[22:23], v[106:107] op_sel:[1,0] op_sel_hi:[1,1]
	v_pk_mul_f32 v[90:91], v[24:25], v[106:107] op_sel:[0,0] op_sel_hi:[0,1]
	v_pk_mul_f32 v[92:93], v[24:25], v[106:107] op_sel:[1,0] op_sel_hi:[1,1]
	v_pk_fma_f32 v[10:11], v[10:11], v[36:37], v[86:87] op_sel:[0,1,0] op_sel_hi:[1,1,1]
	v_pk_fma_f32 v[12:13], v[12:13], v[36:37], v[88:89] op_sel:[0,1,0] op_sel_hi:[1,1,1]
	v_pk_fma_f32 v[14:15], v[14:15], v[36:37], v[90:91] op_sel:[0,1,0] op_sel_hi:[1,1,1]
	v_pk_fma_f32 v[16:17], v[16:17], v[36:37], v[92:93] op_sel:[0,1,0] op_sel_hi:[1,1,1]
	s_waitcnt lgkmcnt(7)
	v_pk_mul_f32 v[94:95], v[38:39], v[2:3] op_sel:[0,0] op_sel_hi:[0,1]
	v_pk_mul_f32 v[96:97], v[38:39], v[4:5] op_sel:[1,0] op_sel_hi:[1,1]
	v_pk_fma_f32 v[94:95], v[40:41], v[6:7], v[94:95] op_sel:[0,0,0] op_sel_hi:[0,1,1]
	v_pk_fma_f32 v[96:97], v[40:41], v[8:9], v[96:97] op_sel:[1,0,0] op_sel_hi:[1,1,1]
	v_pk_fma_f32 v[94:95], v[42:43], v[10:11], v[94:95] op_sel:[0,0,0] op_sel_hi:[0,1,1]
	v_pk_fma_f32 v[96:97], v[42:43], v[12:13], v[96:97] op_sel:[1,0,0] op_sel_hi:[1,1,1]
	v_pk_fma_f32 v[94:95], v[44:45], v[14:15], v[94:95] op_sel:[0,0,0] op_sel_hi:[0,1,1]
	v_pk_fma_f32 v[96:97], v[44:45], v[16:17], v[96:97] op_sel:[1,0,0] op_sel_hi:[1,1,1]
	v_pk_mul_f32 v[108:109], v[26:27], v[2:3] op_sel:[0,0] op_sel_hi:[0,1]
	v_pk_add_f32 v[94:95], v[94:95], v[96:97]
	v_pk_mul_f32 v[110:111], v[26:27], v[4:5] op_sel:[1,0] op_sel_hi:[1,1]
	v_pk_fma_f32 v[108:109], v[28:29], v[6:7], v[108:109] op_sel:[0,0,0] op_sel_hi:[0,1,1]
	v_add_f32_dpp v94, v94, v94 quad_perm:[1,0,3,2] row_mask:0xf bank_mask:0xf
	v_add_f32_dpp v95, v95, v95 quad_perm:[1,0,3,2] row_mask:0xf bank_mask:0xf
	v_pk_fma_f32 v[110:111], v[28:29], v[8:9], v[110:111] op_sel:[1,0,0] op_sel_hi:[1,1,1]
	v_add_f32_dpp v94, v94, v94 quad_perm:[2,3,0,1] row_mask:0xf bank_mask:0xf
	v_add_f32_dpp v95, v95, v95 quad_perm:[2,3,0,1] row_mask:0xf bank_mask:0xf
	v_pk_fma_f32 v[108:109], v[30:31], v[10:11], v[108:109] op_sel:[0,0,0] op_sel_hi:[0,1,1]
	v_add_f32_dpp v94, v94, v94 row_half_mirror row_mask:0xf bank_mask:0xf
	v_add_f32_dpp v95, v95, v95 row_half_mirror row_mask:0xf bank_mask:0xf
	v_pk_fma_f32 v[110:111], v[30:31], v[12:13], v[110:111] op_sel:[1,0,0] op_sel_hi:[1,1,1]
	v_add_f32_dpp v94, v94, v94 row_mirror row_mask:0xf bank_mask:0xf
	v_add_f32_dpp v95, v95, v95 row_mirror row_mask:0xf bank_mask:0xf
	v_pk_fma_f32 v[108:109], v[32:33], v[14:15], v[108:109] op_sel:[0,0,0] op_sel_hi:[0,1,1]
	v_pk_fma_f32 v[110:111], v[32:33], v[16:17], v[110:111] op_sel:[1,0,0] op_sel_hi:[1,1,1]
	s_nop 0
	v_pk_add_f32 v[108:109], v[108:109], v[110:111]
	v_pk_fma_f32 v[98:99], v[56:57], v[94:95], v[54:55] op_sel:[1,0,0] op_sel_hi:[1,1,1] neg_lo:[1,0,0] neg_hi:[1,0,0]
	s_nop 0
	v_pk_mul_f32 v[106:107], v[56:57], v[98:99] op_sel:[0,0] op_sel_hi:[0,1]
	ds_write_b64 v102, v[108:109] offset:57344
	ds_read_b128 v[18:21], v100 offset:32736
	ds_read_b128 v[22:25], v100 offset:32752
	ds_read_b128 v[26:29], v100 offset:33264
	ds_read_b128 v[30:33], v100 offset:33280
	ds_read_b64 v[34:35], v101 offset:37760
	ds_read_b64 v[36:37], v117 offset:38136
	v_pk_mul_f32 v[78:79], v[38:39], v[106:107] op_sel:[0,0] op_sel_hi:[0,1]
	v_pk_mul_f32 v[80:81], v[38:39], v[106:107] op_sel:[1,0] op_sel_hi:[1,1]
	v_pk_mul_f32 v[82:83], v[40:41], v[106:107] op_sel:[0,0] op_sel_hi:[0,1]
	v_pk_mul_f32 v[84:85], v[40:41], v[106:107] op_sel:[1,0] op_sel_hi:[1,1]
	v_pk_fma_f32 v[2:3], v[2:3], v[56:57], v[78:79] op_sel:[0,1,0] op_sel_hi:[1,1,1]
	v_pk_fma_f32 v[4:5], v[4:5], v[56:57], v[80:81] op_sel:[0,1,0] op_sel_hi:[1,1,1]
	v_pk_fma_f32 v[6:7], v[6:7], v[56:57], v[82:83] op_sel:[0,1,0] op_sel_hi:[1,1,1]
	v_pk_fma_f32 v[8:9], v[8:9], v[56:57], v[84:85] op_sel:[0,1,0] op_sel_hi:[1,1,1]
	v_pk_mul_f32 v[86:87], v[42:43], v[106:107] op_sel:[0,0] op_sel_hi:[0,1]
	v_pk_mul_f32 v[88:89], v[42:43], v[106:107] op_sel:[1,0] op_sel_hi:[1,1]
	v_pk_mul_f32 v[90:91], v[44:45], v[106:107] op_sel:[0,0] op_sel_hi:[0,1]
	v_pk_mul_f32 v[92:93], v[44:45], v[106:107] op_sel:[1,0] op_sel_hi:[1,1]
	v_pk_fma_f32 v[10:11], v[10:11], v[56:57], v[86:87] op_sel:[0,1,0] op_sel_hi:[1,1,1]
	v_pk_fma_f32 v[12:13], v[12:13], v[56:57], v[88:89] op_sel:[0,1,0] op_sel_hi:[1,1,1]
	v_pk_fma_f32 v[14:15], v[14:15], v[56:57], v[90:91] op_sel:[0,1,0] op_sel_hi:[1,1,1]
	v_pk_fma_f32 v[16:17], v[16:17], v[56:57], v[92:93] op_sel:[0,1,0] op_sel_hi:[1,1,1]
	s_waitcnt lgkmcnt(7)
	v_pk_mul_f32 v[94:95], v[58:59], v[2:3] op_sel:[0,0] op_sel_hi:[0,1]
	v_pk_mul_f32 v[96:97], v[58:59], v[4:5] op_sel:[1,0] op_sel_hi:[1,1]
	v_pk_fma_f32 v[94:95], v[60:61], v[6:7], v[94:95] op_sel:[0,0,0] op_sel_hi:[0,1,1]
	v_pk_fma_f32 v[96:97], v[60:61], v[8:9], v[96:97] op_sel:[1,0,0] op_sel_hi:[1,1,1]
	v_pk_fma_f32 v[94:95], v[62:63], v[10:11], v[94:95] op_sel:[0,0,0] op_sel_hi:[0,1,1]
	v_pk_fma_f32 v[96:97], v[62:63], v[12:13], v[96:97] op_sel:[1,0,0] op_sel_hi:[1,1,1]
	v_pk_fma_f32 v[94:95], v[64:65], v[14:15], v[94:95] op_sel:[0,0,0] op_sel_hi:[0,1,1]
	v_pk_fma_f32 v[96:97], v[64:65], v[16:17], v[96:97] op_sel:[1,0,0] op_sel_hi:[1,1,1]
	v_pk_mul_f32 v[112:113], v[46:47], v[2:3] op_sel:[0,0] op_sel_hi:[0,1]
	v_pk_add_f32 v[94:95], v[94:95], v[96:97]
	v_pk_mul_f32 v[114:115], v[46:47], v[4:5] op_sel:[1,0] op_sel_hi:[1,1]
	v_pk_fma_f32 v[112:113], v[48:49], v[6:7], v[112:113] op_sel:[0,0,0] op_sel_hi:[0,1,1]
	v_add_f32_dpp v94, v94, v94 quad_perm:[1,0,3,2] row_mask:0xf bank_mask:0xf
	v_add_f32_dpp v95, v95, v95 quad_perm:[1,0,3,2] row_mask:0xf bank_mask:0xf
	v_pk_fma_f32 v[114:115], v[48:49], v[8:9], v[114:115] op_sel:[1,0,0] op_sel_hi:[1,1,1]
	v_add_f32_dpp v94, v94, v94 quad_perm:[2,3,0,1] row_mask:0xf bank_mask:0xf
	v_add_f32_dpp v95, v95, v95 quad_perm:[2,3,0,1] row_mask:0xf bank_mask:0xf
	v_pk_fma_f32 v[112:113], v[50:51], v[10:11], v[112:113] op_sel:[0,0,0] op_sel_hi:[0,1,1]
	v_add_f32_dpp v94, v94, v94 row_half_mirror row_mask:0xf bank_mask:0xf
	v_add_f32_dpp v95, v95, v95 row_half_mirror row_mask:0xf bank_mask:0xf
	v_pk_fma_f32 v[114:115], v[50:51], v[12:13], v[114:115] op_sel:[1,0,0] op_sel_hi:[1,1,1]
	v_add_f32_dpp v94, v94, v94 row_mirror row_mask:0xf bank_mask:0xf
	v_add_f32_dpp v95, v95, v95 row_mirror row_mask:0xf bank_mask:0xf
	v_pk_fma_f32 v[112:113], v[52:53], v[14:15], v[112:113] op_sel:[0,0,0] op_sel_hi:[0,1,1]
	v_pk_fma_f32 v[114:115], v[52:53], v[16:17], v[114:115] op_sel:[1,0,0] op_sel_hi:[1,1,1]
	s_nop 0
	v_pk_add_f32 v[112:113], v[112:113], v[114:115]
	v_pk_fma_f32 v[98:99], v[76:77], v[94:95], v[74:75] op_sel:[1,0,0] op_sel_hi:[1,1,1] neg_lo:[1,0,0] neg_hi:[1,0,0]
	s_nop 0
	v_pk_mul_f32 v[106:107], v[76:77], v[98:99] op_sel:[0,0] op_sel_hi:[0,1]
	ds_write_b64 v102, v[112:113] offset:59392
	v_pk_mul_f32 v[78:79], v[58:59], v[106:107] op_sel:[0,0] op_sel_hi:[0,1]
	v_pk_mul_f32 v[80:81], v[58:59], v[106:107] op_sel:[1,0] op_sel_hi:[1,1]
	v_pk_mul_f32 v[82:83], v[60:61], v[106:107] op_sel:[0,0] op_sel_hi:[0,1]
	v_pk_mul_f32 v[84:85], v[60:61], v[106:107] op_sel:[1,0] op_sel_hi:[1,1]
	v_pk_fma_f32 v[2:3], v[2:3], v[76:77], v[78:79] op_sel:[0,1,0] op_sel_hi:[1,1,1]
	v_pk_fma_f32 v[4:5], v[4:5], v[76:77], v[80:81] op_sel:[0,1,0] op_sel_hi:[1,1,1]
	v_pk_fma_f32 v[6:7], v[6:7], v[76:77], v[82:83] op_sel:[0,1,0] op_sel_hi:[1,1,1]
	v_pk_fma_f32 v[8:9], v[8:9], v[76:77], v[84:85] op_sel:[0,1,0] op_sel_hi:[1,1,1]
	v_pk_mul_f32 v[86:87], v[62:63], v[106:107] op_sel:[0,0] op_sel_hi:[0,1]
	v_pk_mul_f32 v[88:89], v[62:63], v[106:107] op_sel:[1,0] op_sel_hi:[1,1]
	v_pk_mul_f32 v[90:91], v[64:65], v[106:107] op_sel:[0,0] op_sel_hi:[0,1]
	v_pk_mul_f32 v[92:93], v[64:65], v[106:107] op_sel:[1,0] op_sel_hi:[1,1]
	v_pk_fma_f32 v[10:11], v[10:11], v[76:77], v[86:87] op_sel:[0,1,0] op_sel_hi:[1,1,1]
	v_pk_fma_f32 v[12:13], v[12:13], v[76:77], v[88:89] op_sel:[0,1,0] op_sel_hi:[1,1,1]
	v_pk_fma_f32 v[14:15], v[14:15], v[76:77], v[90:91] op_sel:[0,1,0] op_sel_hi:[1,1,1]
	v_pk_fma_f32 v[16:17], v[16:17], v[76:77], v[92:93] op_sel:[0,1,0] op_sel_hi:[1,1,1]
	s_waitcnt lgkmcnt(1)
	v_pk_mul_f32 v[94:95], v[18:19], v[2:3] op_sel:[0,0] op_sel_hi:[0,1]
	v_pk_mul_f32 v[96:97], v[18:19], v[4:5] op_sel:[1,0] op_sel_hi:[1,1]
	v_pk_fma_f32 v[94:95], v[20:21], v[6:7], v[94:95] op_sel:[0,0,0] op_sel_hi:[0,1,1]
	v_pk_fma_f32 v[96:97], v[20:21], v[8:9], v[96:97] op_sel:[1,0,0] op_sel_hi:[1,1,1]
	v_pk_fma_f32 v[94:95], v[22:23], v[10:11], v[94:95] op_sel:[0,0,0] op_sel_hi:[0,1,1]
	v_pk_fma_f32 v[96:97], v[22:23], v[12:13], v[96:97] op_sel:[1,0,0] op_sel_hi:[1,1,1]
	v_pk_fma_f32 v[94:95], v[24:25], v[14:15], v[94:95] op_sel:[0,0,0] op_sel_hi:[0,1,1]
	v_pk_fma_f32 v[96:97], v[24:25], v[16:17], v[96:97] op_sel:[1,0,0] op_sel_hi:[1,1,1]
	v_pk_mul_f32 v[108:109], v[66:67], v[2:3] op_sel:[0,0] op_sel_hi:[0,1]
	v_pk_add_f32 v[94:95], v[94:95], v[96:97]
	v_pk_mul_f32 v[110:111], v[66:67], v[4:5] op_sel:[1,0] op_sel_hi:[1,1]
	v_pk_fma_f32 v[108:109], v[68:69], v[6:7], v[108:109] op_sel:[0,0,0] op_sel_hi:[0,1,1]
	v_add_f32_dpp v94, v94, v94 quad_perm:[1,0,3,2] row_mask:0xf bank_mask:0xf
	v_add_f32_dpp v95, v95, v95 quad_perm:[1,0,3,2] row_mask:0xf bank_mask:0xf
	v_pk_fma_f32 v[110:111], v[68:69], v[8:9], v[110:111] op_sel:[1,0,0] op_sel_hi:[1,1,1]
	v_add_f32_dpp v94, v94, v94 quad_perm:[2,3,0,1] row_mask:0xf bank_mask:0xf
	v_add_f32_dpp v95, v95, v95 quad_perm:[2,3,0,1] row_mask:0xf bank_mask:0xf
	v_pk_fma_f32 v[108:109], v[70:71], v[10:11], v[108:109] op_sel:[0,0,0] op_sel_hi:[0,1,1]
	v_add_f32_dpp v94, v94, v94 row_half_mirror row_mask:0xf bank_mask:0xf
	v_add_f32_dpp v95, v95, v95 row_half_mirror row_mask:0xf bank_mask:0xf
	v_pk_fma_f32 v[110:111], v[70:71], v[12:13], v[110:111] op_sel:[1,0,0] op_sel_hi:[1,1,1]
	v_add_f32_dpp v94, v94, v94 row_mirror row_mask:0xf bank_mask:0xf
	v_add_f32_dpp v95, v95, v95 row_mirror row_mask:0xf bank_mask:0xf
	v_pk_fma_f32 v[108:109], v[72:73], v[14:15], v[108:109] op_sel:[0,0,0] op_sel_hi:[0,1,1]
	v_pk_fma_f32 v[110:111], v[72:73], v[16:17], v[110:111] op_sel:[1,0,0] op_sel_hi:[1,1,1]
	s_nop 0
	v_pk_add_f32 v[108:109], v[108:109], v[110:111]
	v_pk_fma_f32 v[98:99], v[36:37], v[94:95], v[34:35] op_sel:[1,0,0] op_sel_hi:[1,1,1] neg_lo:[1,0,0] neg_hi:[1,0,0]
	s_nop 0
	v_pk_mul_f32 v[106:107], v[36:37], v[98:99] op_sel:[0,0] op_sel_hi:[0,1]
	ds_write_b64 v102, v[108:109] offset:61440
	v_pk_mul_f32 v[78:79], v[18:19], v[106:107] op_sel:[0,0] op_sel_hi:[0,1]
	v_pk_mul_f32 v[80:81], v[18:19], v[106:107] op_sel:[1,0] op_sel_hi:[1,1]
	v_pk_mul_f32 v[82:83], v[20:21], v[106:107] op_sel:[0,0] op_sel_hi:[0,1]
	v_pk_mul_f32 v[84:85], v[20:21], v[106:107] op_sel:[1,0] op_sel_hi:[1,1]
	v_pk_fma_f32 v[2:3], v[2:3], v[36:37], v[78:79] op_sel:[0,1,0] op_sel_hi:[1,1,1]
	v_pk_fma_f32 v[4:5], v[4:5], v[36:37], v[80:81] op_sel:[0,1,0] op_sel_hi:[1,1,1]
	v_pk_fma_f32 v[6:7], v[6:7], v[36:37], v[82:83] op_sel:[0,1,0] op_sel_hi:[1,1,1]
	v_pk_fma_f32 v[8:9], v[8:9], v[36:37], v[84:85] op_sel:[0,1,0] op_sel_hi:[1,1,1]
	v_pk_mul_f32 v[86:87], v[22:23], v[106:107] op_sel:[0,0] op_sel_hi:[0,1]
	v_pk_mul_f32 v[88:89], v[22:23], v[106:107] op_sel:[1,0] op_sel_hi:[1,1]
	v_pk_mul_f32 v[90:91], v[24:25], v[106:107] op_sel:[0,0] op_sel_hi:[0,1]
	v_pk_mul_f32 v[92:93], v[24:25], v[106:107] op_sel:[1,0] op_sel_hi:[1,1]
	v_pk_fma_f32 v[10:11], v[10:11], v[36:37], v[86:87] op_sel:[0,1,0] op_sel_hi:[1,1,1]
	v_pk_fma_f32 v[12:13], v[12:13], v[36:37], v[88:89] op_sel:[0,1,0] op_sel_hi:[1,1,1]
	v_pk_fma_f32 v[14:15], v[14:15], v[36:37], v[90:91] op_sel:[0,1,0] op_sel_hi:[1,1,1]
	v_pk_fma_f32 v[16:17], v[16:17], v[36:37], v[92:93] op_sel:[0,1,0] op_sel_hi:[1,1,1]
	v_pk_mul_f32 v[112:113], v[26:27], v[2:3] op_sel:[0,0] op_sel_hi:[0,1]
	v_pk_mul_f32 v[114:115], v[26:27], v[4:5] op_sel:[1,0] op_sel_hi:[1,1]
	v_pk_fma_f32 v[112:113], v[28:29], v[6:7], v[112:113] op_sel:[0,0,0] op_sel_hi:[0,1,1]
	v_pk_fma_f32 v[114:115], v[28:29], v[8:9], v[114:115] op_sel:[1,0,0] op_sel_hi:[1,1,1]
	v_pk_fma_f32 v[112:113], v[30:31], v[10:11], v[112:113] op_sel:[0,0,0] op_sel_hi:[0,1,1]
	v_pk_fma_f32 v[114:115], v[30:31], v[12:13], v[114:115] op_sel:[1,0,0] op_sel_hi:[1,1,1]
	v_pk_fma_f32 v[112:113], v[32:33], v[14:15], v[112:113] op_sel:[0,0,0] op_sel_hi:[0,1,1]
	v_pk_fma_f32 v[114:115], v[32:33], v[16:17], v[114:115] op_sel:[1,0,0] op_sel_hi:[1,1,1]
	s_nop 0
	v_pk_add_f32 v[112:113], v[112:113], v[114:115]
	s_nop 0
	ds_write_b64 v102, v[112:113] offset:63488
	s_waitcnt lgkmcnt(0)
	s_barrier
	s_add_i32 s16, s16, 2
	s_cmp_lt_u32 s16, 0x100
	s_cbranch_scc1 .Lgc_loop
	s_waitcnt vmcnt(0) lgkmcnt(0)
	s_setprio 0
.LBB0_473:
	s_andn2_saveexec_b64 s[12:13], s[6:7]
	s_cbranch_execz .LBB0_507
	s_lshr_b32 s8, s2, 6
	s_bfe_u32 s9, s2, 0x20004
	s_bfe_u32 s11, s2, 0x20002
	s_and_b32 s14, s2, 3
	s_add_u32 s16, s28, 0xac00000
	s_addc_u32 s17, s29, 0
	s_add_u32 s18, s28, 0xfd00000
	s_addc_u32 s19, s29, 0
	s_add_u32 s22, s28, 0xdc00000
	s_addc_u32 s23, s29, 0
	s_mov_b32 s46, 0xc000
	s_mov_b32 s47, 0
	s_mov_b32 s48, 0x400
	s_mov_b32 s49, 0
	s_mov_b32 s50, 0x8000
	s_mov_b32 s51, 0
	s_mov_b32 s57, 1
	s_lshl_b32 s56, s9, 12
	s_cmp_eq_u32 s8, 0
	s_cbranch_scc1 .Lgs_fwd
	s_mov_b32 s22, s26
	s_mov_b32 s23, s27
	s_mov_b32 s46, 0xffff4000
	s_mov_b32 s47, -1
	s_mov_b32 s48, 0xfffffc00
	s_mov_b32 s49, -1
	s_mov_b32 s50, 0xffff8000
	s_mov_b32 s51, -1
	s_mov_b32 s57, -1
	s_add_u32 s56, s56, 0xfff
.Lgs_fwd:
	s_movk_i32 s15, 0xc00
	s_lshl_b32 s58, s11, 7
	s_lshl_b32 s59, s14, 5
	v_and_b32_e32 v125, 15, v164
	v_bfe_u32 v126, v164, 4, 4
	v_cmp_gt_u32_e64 s[52:53], 4, v125
	v_cmp_eq_u32_e64 s[54:55], 4, v125
	v_mul_lo_u32 v127, v126, s57
	v_add_u32_e32 v127, s56, v127
	v_mul_lo_u32 v78, v127, s15
	v_lshl_add_u32 v76, v125, 3, s58
	v_lshl_add_u32 v78, v76, 1, v78
	v_mov_b32_e32 v76, 0
	v_mov_b32_e32 v77, 0
	v_mov_b32_e32 v76, v78
	v_lshl_add_u64 v[112:113], v[76:77], 0, s[16:17]
	s_lshl_b32 s59, s59, 1
	s_add_u32 s20, s59, 0x800
	s_mov_b32 s21, 0
	v_lshl_add_u64 v[114:115], v[112:113], 0, s[20:21]
	v_lshlrev_b32_e32 v76, 6, v127
	s_lshl_b32 s20, s11, 4
	v_add_u32_e32 v76, s20, v76
	v_lshl_add_u64 v[116:117], v[76:77], 0, s[18:19]
	s_lshl_b32 s20, s14, 5
	s_add_u32 s20, s20, s58
	s_add_u32 s20, s20, 0x200
	v_lshl_add_u32 v79, v125, 1, s20
	v_lshlrev_b32_e32 v76, 11, v127
	v_lshl_add_u32 v76, v79, 1, v76
	v_lshl_add_u64 v[118:119], v[76:77], 0, s[22:23]
	v_mul_u32_u24_e32 v120, 0x420, v126
	v_lshl_add_u32 v120, v125, 5, v120
	v_lshrrev_b32_e32 v121, 3, v125
	v_lshl_add_u32 v120, v121, 4, v120
	v_lshlrev_b32_e32 v121, 7, v126
	v_lshl_add_u32 v121, v125, 5, v121
	v_add_u32_e32 v121, 0x8400, v121
	v_lshlrev_b32_e32 v122, 3, v126
	v_add_u32_e32 v122, 0x9400, v122
	v_and_b32_e32 v123, 0xff, v164
	v_bfe_u32 v124, v164, 1, 3
	v_lshlrev_b32_e32 v123, 7, v123
	v_add_u32_e32 v123, 38144, v123
	v_lshl_or_b32 v123, v124, 4, v123
	global_load_dwordx4 v[4:7], v[112:113], off
	global_load_dwordx4 v[8:11], v[112:113], off offset:1024
	s_mov_b64 exec, s[52:53]
	global_load_dwordx4 v[12:15], v[114:115], off
	s_mov_b64 exec, s[54:55]
	global_load_dwordx4 v[16:19], v[116:117], off
	s_mov_b64 exec, -1
	v_lshl_add_u64 v[112:113], v[112:113], 0, s[46:47]
	v_lshl_add_u64 v[114:115], v[114:115], 0, s[46:47]
	v_lshl_add_u64 v[116:117], v[116:117], 0, s[48:49]
	global_load_dwordx4 v[20:23], v[112:113], off
	global_load_dwordx4 v[24:27], v[112:113], off offset:1024
	s_mov_b64 exec, s[52:53]
	global_load_dwordx4 v[28:31], v[114:115], off
	s_mov_b64 exec, s[54:55]
	global_load_dwordx4 v[32:35], v[116:117], off
	s_mov_b64 exec, -1
	v_lshl_add_u64 v[112:113], v[112:113], 0, s[46:47]
	v_lshl_add_u64 v[114:115], v[114:115], 0, s[46:47]
	v_lshl_add_u64 v[116:117], v[116:117], 0, s[48:49]
	global_load_dwordx4 v[36:39], v[112:113], off
	global_load_dwordx4 v[40:43], v[112:113], off offset:1024
	s_mov_b64 exec, s[52:53]
	global_load_dwordx4 v[44:47], v[114:115], off
	s_mov_b64 exec, s[54:55]
	global_load_dwordx4 v[48:51], v[116:117], off
	s_mov_b64 exec, -1
	v_lshl_add_u64 v[112:113], v[112:113], 0, s[46:47]
	v_lshl_add_u64 v[114:115], v[114:115], 0, s[46:47]
	v_lshl_add_u64 v[116:117], v[116:117], 0, s[48:49]
	s_waitcnt vmcnt(8)
	v_lshlrev_b32_e32 v52, 16, v8
	v_and_b32_e32 v53, 0xffff0000, v8
	v_lshlrev_b32_e32 v54, 16, v9
	v_and_b32_e32 v55, 0xffff0000, v9
	v_lshlrev_b32_e32 v56, 16, v10
	v_and_b32_e32 v57, 0xffff0000, v10
	v_lshlrev_b32_e32 v58, 16, v11
	v_and_b32_e32 v59, 0xffff0000, v11
	v_lshlrev_b32_e32 v60, 16, v4
	v_and_b32_e32 v61, 0xffff0000, v4
	v_lshlrev_b32_e32 v62, 16, v5
	v_and_b32_e32 v63, 0xffff0000, v5
	v_lshlrev_b32_e32 v64, 16, v6
	v_and_b32_e32 v65, 0xffff0000, v6
	v_lshlrev_b32_e32 v66, 16, v7
	v_and_b32_e32 v67, 0xffff0000, v7
	v_lshlrev_b32_e32 v68, 16, v12
	v_and_b32_e32 v69, 0xffff0000, v12
	v_lshlrev_b32_e32 v70, 16, v13
	v_and_b32_e32 v71, 0xffff0000, v13
	v_lshlrev_b32_e32 v72, 16, v14
	v_and_b32_e32 v73, 0xffff0000, v14
	v_lshlrev_b32_e32 v74, 16, v15
	v_and_b32_e32 v75, 0xffff0000, v15
	s_cmp_eq_u32 s8, 0
	v_mov_b32_e32 v76, v16
	v_mov_b32_e32 v77, v17
	s_cmp_eq_u32 s8, 0
	s_cbranch_scc1 .Lgs_g0_1
	v_mov_b32_e32 v77, v18
.Lgs_g0_1:
	ds_write_b128 v120, v[52:55] offset:0
	ds_write_b128 v120, v[56:59] offset:16
	ds_write_b128 v120, v[60:63] offset:528
	ds_write_b128 v120, v[64:67] offset:544
	s_mov_b64 exec, s[52:53]
	ds_write_b128 v121, v[68:71] offset:0
	ds_write_b128 v121, v[72:75] offset:16
	s_mov_b64 exec, s[54:55]
	ds_write_b64 v122, v[76:77] offset:0
	s_mov_b64 exec, -1
	global_load_dwordx4 v[4:7], v[112:113], off
	global_load_dwordx4 v[8:11], v[112:113], off offset:1024
	s_mov_b64 exec, s[52:53]
	global_load_dwordx4 v[12:15], v[114:115], off
	s_mov_b64 exec, s[54:55]
	global_load_dwordx4 v[16:19], v[116:117], off
	s_mov_b64 exec, -1
	v_lshl_add_u64 v[112:113], v[112:113], 0, s[46:47]
	v_lshl_add_u64 v[114:115], v[114:115], 0, s[46:47]
	v_lshl_add_u64 v[116:117], v[116:117], 0, s[48:49]
	s_waitcnt lgkmcnt(0)
	s_barrier
	s_mov_b32 s44, 0
.Lgs_loop:
	ds_read_b128 v[80:83], v123 offset:32768
	v_xor_b32_e32 v124, 16, v123
	ds_read_b128 v[84:87], v124 offset:32768
	v_xor_b32_e32 v124, 32, v123
	ds_read_b128 v[88:91], v124 offset:32768
	v_xor_b32_e32 v124, 48, v123
	ds_read_b128 v[92:95], v124 offset:32768
	v_xor_b32_e32 v124, 64, v123
	ds_read_b128 v[96:99], v124 offset:32768
	v_xor_b32_e32 v124, 80, v123
	ds_read_b128 v[100:103], v124 offset:32768
	v_xor_b32_e32 v124, 96, v123
	ds_read_b128 v[104:107], v124 offset:32768
	v_xor_b32_e32 v124, 112, v123
	ds_read_b128 v[108:111], v124 offset:32768
	s_waitcnt lgkmcnt(0)
	v_pk_add_f32 v[80:81], v[80:81], v[82:83]
	v_pk_add_f32 v[84:85], v[84:85], v[86:87]
	v_pk_add_f32 v[88:89], v[88:89], v[90:91]
	v_pk_add_f32 v[92:93], v[92:93], v[94:95]
	v_pk_add_f32 v[96:97], v[96:97], v[98:99]
	v_pk_add_f32 v[100:101], v[100:101], v[102:103]
	v_pk_add_f32 v[104:105], v[104:105], v[106:107]
	v_pk_add_f32 v[108:109], v[108:109], v[110:111]
	v_pk_add_f32 v[80:81], v[80:81], v[84:85]
	v_pk_add_f32 v[88:89], v[88:89], v[92:93]
	v_pk_add_f32 v[96:97], v[96:97], v[100:101]
	v_pk_add_f32 v[104:105], v[104:105], v[108:109]
	v_pk_add_f32 v[80:81], v[80:81], v[88:89]
	v_pk_add_f32 v[96:97], v[96:97], v[104:105]
	s_nop 0
	v_pk_add_f32 v[80:81], v[80:81], v[96:97]
	s_nop 0
	v_cvt_pk_bf16_f32 v82, v80, v81
	s_cmp_eq_u32 s44, 0
	s_cselect_b64 s[22:23], 0, -1
	s_cselect_b64 s[58:59], 0, s[50:51]
	s_mov_b64 exec, s[22:23]
	global_store_dword v[118:119], v82, off
	s_mov_b64 exec, -1
	v_lshl_add_u64 v[118:119], v[118:119], 0, s[58:59]
	s_waitcnt vmcnt(9)
	v_lshlrev_b32_e32 v52, 16, v24
	v_and_b32_e32 v53, 0xffff0000, v24
	v_lshlrev_b32_e32 v54, 16, v25
	v_and_b32_e32 v55, 0xffff0000, v25
	v_lshlrev_b32_e32 v56, 16, v26
	v_and_b32_e32 v57, 0xffff0000, v26
	v_lshlrev_b32_e32 v58, 16, v27
	v_and_b32_e32 v59, 0xffff0000, v27
	v_lshlrev_b32_e32 v60, 16, v20
	v_and_b32_e32 v61, 0xffff0000, v20
	v_lshlrev_b32_e32 v62, 16, v21
	v_and_b32_e32 v63, 0xffff0000, v21
	v_lshlrev_b32_e32 v64, 16, v22
	v_and_b32_e32 v65, 0xffff0000, v22
	v_lshlrev_b32_e32 v66, 16, v23
	v_and_b32_e32 v67, 0xffff0000, v23
	v_lshlrev_b32_e32 v68, 16, v28
	v_and_b32_e32 v69, 0xffff0000, v28
	v_lshlrev_b32_e32 v70, 16, v29
	v_and_b32_e32 v71, 0xffff0000, v29
	v_lshlrev_b32_e32 v72, 16, v30
	v_and_b32_e32 v73, 0xffff0000, v30
	v_lshlrev_b32_e32 v74, 16, v31
	v_and_b32_e32 v75, 0xffff0000, v31
	s_cmp_eq_u32 s8, 0
	v_mov_b32_e32 v76, v32
	v_mov_b32_e32 v77, v33
	s_cmp_eq_u32 s8, 0
	s_cbranch_scc1 .Lgs_g0_2
	v_mov_b32_e32 v77, v34
.Lgs_g0_2:
	ds_write_b128 v120, v[52:55] offset:16896
	ds_write_b128 v120, v[56:59] offset:16912
	ds_write_b128 v120, v[60:63] offset:17424
	ds_write_b128 v120, v[64:67] offset:17440
	s_mov_b64 exec, s[52:53]
	ds_write_b128 v121, v[68:71] offset:2048
	ds_write_b128 v121, v[72:75] offset:2064
	s_mov_b64 exec, s[54:55]
	ds_write_b64 v122, v[76:77] offset:128
	s_mov_b64 exec, -1
	global_load_dwordx4 v[20:23], v[112:113], off
	global_load_dwordx4 v[24:27], v[112:113], off offset:1024
	s_mov_b64 exec, s[52:53]
	global_load_dwordx4 v[28:31], v[114:115], off
	s_mov_b64 exec, s[54:55]
	global_load_dwordx4 v[32:35], v[116:117], off
	s_mov_b64 exec, -1
	v_lshl_add_u64 v[112:113], v[112:113], 0, s[46:47]
	v_lshl_add_u64 v[114:115], v[114:115], 0, s[46:47]
	v_lshl_add_u64 v[116:117], v[116:117], 0, s[48:49]
	s_waitcnt lgkmcnt(0)
	s_barrier
	ds_read_b128 v[80:83], v123 offset:0
	v_xor_b32_e32 v124, 16, v123
	ds_read_b128 v[84:87], v124 offset:0
	v_xor_b32_e32 v124, 32, v123
	ds_read_b128 v[88:91], v124 offset:0
	v_xor_b32_e32 v124, 48, v123
	ds_read_b128 v[92:95], v124 offset:0
	v_xor_b32_e32 v124, 64, v123
	ds_read_b128 v[96:99], v124 offset:0
	v_xor_b32_e32 v124, 80, v123
	ds_read_b128 v[100:103], v124 offset:0
	v_xor_b32_e32 v124, 96, v123
	ds_read_b128 v[104:107], v124 offset:0
	v_xor_b32_e32 v124, 112, v123
	ds_read_b128 v[108:111], v124 offset:0
	s_waitcnt lgkmcnt(0)
	v_pk_add_f32 v[80:81], v[80:81], v[82:83]
	v_pk_add_f32 v[84:85], v[84:85], v[86:87]
	v_pk_add_f32 v[88:89], v[88:89], v[90:91]
	v_pk_add_f32 v[92:93], v[92:93], v[94:95]
	v_pk_add_f32 v[96:97], v[96:97], v[98:99]
	v_pk_add_f32 v[100:101], v[100:101], v[102:103]
	v_pk_add_f32 v[104:105], v[104:105], v[106:107]
	v_pk_add_f32 v[108:109], v[108:109], v[110:111]
	v_pk_add_f32 v[80:81], v[80:81], v[84:85]
	v_pk_add_f32 v[88:89], v[88:89], v[92:93]
	v_pk_add_f32 v[96:97], v[96:97], v[100:101]
	v_pk_add_f32 v[104:105], v[104:105], v[108:109]
	v_pk_add_f32 v[80:81], v[80:81], v[88:89]
	v_pk_add_f32 v[96:97], v[96:97], v[104:105]
	s_nop 0
	v_pk_add_f32 v[80:81], v[80:81], v[96:97]
	s_nop 0
	v_cvt_pk_bf16_f32 v82, v80, v81
	global_store_dword v[118:119], v82, off
	v_lshl_add_u64 v[118:119], v[118:119], 0, s[50:51]
	s_waitcnt vmcnt(9)
	v_lshlrev_b32_e32 v52, 16, v40
	v_and_b32_e32 v53, 0xffff0000, v40
	v_lshlrev_b32_e32 v54, 16, v41
	v_and_b32_e32 v55, 0xffff0000, v41
	v_lshlrev_b32_e32 v56, 16, v42
	v_and_b32_e32 v57, 0xffff0000, v42
	v_lshlrev_b32_e32 v58, 16, v43
	v_and_b32_e32 v59, 0xffff0000, v43
	v_lshlrev_b32_e32 v60, 16, v36
	v_and_b32_e32 v61, 0xffff0000, v36
	v_lshlrev_b32_e32 v62, 16, v37
	v_and_b32_e32 v63, 0xffff0000, v37
	v_lshlrev_b32_e32 v64, 16, v38
	v_and_b32_e32 v65, 0xffff0000, v38
	v_lshlrev_b32_e32 v66, 16, v39
	v_and_b32_e32 v67, 0xffff0000, v39
	v_lshlrev_b32_e32 v68, 16, v44
	v_and_b32_e32 v69, 0xffff0000, v44
	v_lshlrev_b32_e32 v70, 16, v45
	v_and_b32_e32 v71, 0xffff0000, v45
	v_lshlrev_b32_e32 v72, 16, v46
	v_and_b32_e32 v73, 0xffff0000, v46
	v_lshlrev_b32_e32 v74, 16, v47
	v_and_b32_e32 v75, 0xffff0000, v47
	s_cmp_eq_u32 s8, 0
	v_mov_b32_e32 v76, v48
	v_mov_b32_e32 v77, v49
	s_cmp_eq_u32 s8, 0
	s_cbranch_scc1 .Lgs_g0_3
	v_mov_b32_e32 v77, v50
.Lgs_g0_3:
	ds_write_b128 v120, v[52:55] offset:0
	ds_write_b128 v120, v[56:59] offset:16
	ds_write_b128 v120, v[60:63] offset:528
	ds_write_b128 v120, v[64:67] offset:544
	s_mov_b64 exec, s[52:53]
	ds_write_b128 v121, v[68:71] offset:0
	ds_write_b128 v121, v[72:75] offset:16
	s_mov_b64 exec, s[54:55]
	ds_write_b64 v122, v[76:77] offset:0
	s_mov_b64 exec, -1
	global_load_dwordx4 v[36:39], v[112:113], off
	global_load_dwordx4 v[40:43], v[112:113], off offset:1024
	s_mov_b64 exec, s[52:53]
	global_load_dwordx4 v[44:47], v[114:115], off
	s_mov_b64 exec, s[54:55]
	global_load_dwordx4 v[48:51], v[116:117], off
	s_mov_b64 exec, -1
	v_lshl_add_u64 v[112:113], v[112:113], 0, s[46:47]
	v_lshl_add_u64 v[114:115], v[114:115], 0, s[46:47]
	v_lshl_add_u64 v[116:117], v[116:117], 0, s[48:49]
	s_waitcnt lgkmcnt(0)
	s_barrier
	ds_read_b128 v[80:83], v123 offset:32768
	v_xor_b32_e32 v124, 16, v123
	ds_read_b128 v[84:87], v124 offset:32768
	v_xor_b32_e32 v124, 32, v123
	ds_read_b128 v[88:91], v124 offset:32768
	v_xor_b32_e32 v124, 48, v123
	ds_read_b128 v[92:95], v124 offset:32768
	v_xor_b32_e32 v124, 64, v123
	ds_read_b128 v[96:99], v124 offset:32768
	v_xor_b32_e32 v124, 80, v123
	ds_read_b128 v[100:103], v124 offset:32768
	v_xor_b32_e32 v124, 96, v123
	ds_read_b128 v[104:107], v124 offset:32768
	v_xor_b32_e32 v124, 112, v123
	ds_read_b128 v[108:111], v124 offset:32768
	s_waitcnt lgkmcnt(0)
	v_pk_add_f32 v[80:81], v[80:81], v[82:83]
	v_pk_add_f32 v[84:85], v[84:85], v[86:87]
	v_pk_add_f32 v[88:89], v[88:89], v[90:91]
	v_pk_add_f32 v[92:93], v[92:93], v[94:95]
	v_pk_add_f32 v[96:97], v[96:97], v[98:99]
	v_pk_add_f32 v[100:101], v[100:101], v[102:103]
	v_pk_add_f32 v[104:105], v[104:105], v[106:107]
	v_pk_add_f32 v[108:109], v[108:109], v[110:111]
	v_pk_add_f32 v[80:81], v[80:81], v[84:85]
	v_pk_add_f32 v[88:89], v[88:89], v[92:93]
	v_pk_add_f32 v[96:97], v[96:97], v[100:101]
	v_pk_add_f32 v[104:105], v[104:105], v[108:109]
	v_pk_add_f32 v[80:81], v[80:81], v[88:89]
	v_pk_add_f32 v[96:97], v[96:97], v[104:105]
	s_nop 0
	v_pk_add_f32 v[80:81], v[80:81], v[96:97]
	s_nop 0
	v_cvt_pk_bf16_f32 v82, v80, v81
	global_store_dword v[118:119], v82, off
	v_lshl_add_u64 v[118:119], v[118:119], 0, s[50:51]
	s_waitcnt vmcnt(9)
	v_lshlrev_b32_e32 v52, 16, v8
	v_and_b32_e32 v53, 0xffff0000, v8
	v_lshlrev_b32_e32 v54, 16, v9
	v_and_b32_e32 v55, 0xffff0000, v9
	v_lshlrev_b32_e32 v56, 16, v10
	v_and_b32_e32 v57, 0xffff0000, v10
	v_lshlrev_b32_e32 v58, 16, v11
	v_and_b32_e32 v59, 0xffff0000, v11
	v_lshlrev_b32_e32 v60, 16, v4
	v_and_b32_e32 v61, 0xffff0000, v4
	v_lshlrev_b32_e32 v62, 16, v5
	v_and_b32_e32 v63, 0xffff0000, v5
	v_lshlrev_b32_e32 v64, 16, v6
	v_and_b32_e32 v65, 0xffff0000, v6
	v_lshlrev_b32_e32 v66, 16, v7
	v_and_b32_e32 v67, 0xffff0000, v7
	v_lshlrev_b32_e32 v68, 16, v12
	v_and_b32_e32 v69, 0xffff0000, v12
	v_lshlrev_b32_e32 v70, 16, v13
	v_and_b32_e32 v71, 0xffff0000, v13
	v_lshlrev_b32_e32 v72, 16, v14
	v_and_b32_e32 v73, 0xffff0000, v14
	v_lshlrev_b32_e32 v74, 16, v15
	v_and_b32_e32 v75, 0xffff0000, v15
	s_cmp_eq_u32 s8, 0
	v_mov_b32_e32 v76, v16
	v_mov_b32_e32 v77, v17
	s_cmp_eq_u32 s8, 0
	s_cbranch_scc1 .Lgs_g0_4
	v_mov_b32_e32 v77, v18
.Lgs_g0_4:
	ds_write_b128 v120, v[52:55] offset:16896
	ds_write_b128 v120, v[56:59] offset:16912
	ds_write_b128 v120, v[60:63] offset:17424
	ds_write_b128 v120, v[64:67] offset:17440
	s_mov_b64 exec, s[52:53]
	ds_write_b128 v121, v[68:71] offset:2048
	ds_write_b128 v121, v[72:75] offset:2064
	s_mov_b64 exec, s[54:55]
	ds_write_b64 v122, v[76:77] offset:128
	s_mov_b64 exec, -1
	global_load_dwordx4 v[4:7], v[112:113], off
	global_load_dwordx4 v[8:11], v[112:113], off offset:1024
	s_mov_b64 exec, s[52:53]
	global_load_dwordx4 v[12:15], v[114:115], off
	s_mov_b64 exec, s[54:55]
	global_load_dwordx4 v[16:19], v[116:117], off
	s_mov_b64 exec, -1
	v_lshl_add_u64 v[112:113], v[112:113], 0, s[46:47]
	v_lshl_add_u64 v[114:115], v[114:115], 0, s[46:47]
	v_lshl_add_u64 v[116:117], v[116:117], 0, s[48:49]
	s_waitcnt lgkmcnt(0)
	s_barrier
	ds_read_b128 v[80:83], v123 offset:0
	v_xor_b32_e32 v124, 16, v123
	ds_read_b128 v[84:87], v124 offset:0
	v_xor_b32_e32 v124, 32, v123
	ds_read_b128 v[88:91], v124 offset:0
	v_xor_b32_e32 v124, 48, v123
	ds_read_b128 v[92:95], v124 offset:0
	v_xor_b32_e32 v124, 64, v123
	ds_read_b128 v[96:99], v124 offset:0
	v_xor_b32_e32 v124, 80, v123
	ds_read_b128 v[100:103], v124 offset:0
	v_xor_b32_e32 v124, 96, v123
	ds_read_b128 v[104:107], v124 offset:0
	v_xor_b32_e32 v124, 112, v123
	ds_read_b128 v[108:111], v124 offset:0
	s_waitcnt lgkmcnt(0)
	v_pk_add_f32 v[80:81], v[80:81], v[82:83]
	v_pk_add_f32 v[84:85], v[84:85], v[86:87]
	v_pk_add_f32 v[88:89], v[88:89], v[90:91]
	v_pk_add_f32 v[92:93], v[92:93], v[94:95]
	v_pk_add_f32 v[96:97], v[96:97], v[98:99]
	v_pk_add_f32 v[100:101], v[100:101], v[102:103]
	v_pk_add_f32 v[104:105], v[104:105], v[106:107]
	v_pk_add_f32 v[108:109], v[108:109], v[110:111]
	v_pk_add_f32 v[80:81], v[80:81], v[84:85]
	v_pk_add_f32 v[88:89], v[88:89], v[92:93]
	v_pk_add_f32 v[96:97], v[96:97], v[100:101]
	v_pk_add_f32 v[104:105], v[104:105], v[108:109]
	v_pk_add_f32 v[80:81], v[80:81], v[88:89]
	v_pk_add_f32 v[96:97], v[96:97], v[104:105]
	s_nop 0
	v_pk_add_f32 v[80:81], v[80:81], v[96:97]
	s_nop 0
	v_cvt_pk_bf16_f32 v82, v80, v81
	global_store_dword v[118:119], v82, off
	v_lshl_add_u64 v[118:119], v[118:119], 0, s[50:51]
	s_waitcnt vmcnt(9)
	v_lshlrev_b32_e32 v52, 16, v24
	v_and_b32_e32 v53, 0xffff0000, v24
	v_lshlrev_b32_e32 v54, 16, v25
	v_and_b32_e32 v55, 0xffff0000, v25
	v_lshlrev_b32_e32 v56, 16, v26
	v_and_b32_e32 v57, 0xffff0000, v26
	v_lshlrev_b32_e32 v58, 16, v27
	v_and_b32_e32 v59, 0xffff0000, v27
	v_lshlrev_b32_e32 v60, 16, v20
	v_and_b32_e32 v61, 0xffff0000, v20
	v_lshlrev_b32_e32 v62, 16, v21
	v_and_b32_e32 v63, 0xffff0000, v21
	v_lshlrev_b32_e32 v64, 16, v22
	v_and_b32_e32 v65, 0xffff0000, v22
	v_lshlrev_b32_e32 v66, 16, v23
	v_and_b32_e32 v67, 0xffff0000, v23
	v_lshlrev_b32_e32 v68, 16, v28
	v_and_b32_e32 v69, 0xffff0000, v28
	v_lshlrev_b32_e32 v70, 16, v29
	v_and_b32_e32 v71, 0xffff0000, v29
	v_lshlrev_b32_e32 v72, 16, v30
	v_and_b32_e32 v73, 0xffff0000, v30
	v_lshlrev_b32_e32 v74, 16, v31
	v_and_b32_e32 v75, 0xffff0000, v31
	s_cmp_eq_u32 s8, 0
	v_mov_b32_e32 v76, v32
	v_mov_b32_e32 v77, v33
	s_cmp_eq_u32 s8, 0
	s_cbranch_scc1 .Lgs_g0_5
	v_mov_b32_e32 v77, v34
.Lgs_g0_5:
	ds_write_b128 v120, v[52:55] offset:0
	ds_write_b128 v120, v[56:59] offset:16
	ds_write_b128 v120, v[60:63] offset:528
	ds_write_b128 v120, v[64:67] offset:544
	s_mov_b64 exec, s[52:53]
	ds_write_b128 v121, v[68:71] offset:0
	ds_write_b128 v121, v[72:75] offset:16
	s_mov_b64 exec, s[54:55]
	ds_write_b64 v122, v[76:77] offset:0
	s_mov_b64 exec, -1
	global_load_dwordx4 v[20:23], v[112:113], off
	global_load_dwordx4 v[24:27], v[112:113], off offset:1024
	s_mov_b64 exec, s[52:53]
	global_load_dwordx4 v[28:31], v[114:115], off
	s_mov_b64 exec, s[54:55]
	global_load_dwordx4 v[32:35], v[116:117], off
	s_mov_b64 exec, -1
	v_lshl_add_u64 v[112:113], v[112:113], 0, s[46:47]
	v_lshl_add_u64 v[114:115], v[114:115], 0, s[46:47]
	v_lshl_add_u64 v[116:117], v[116:117], 0, s[48:49]
	s_waitcnt lgkmcnt(0)
	s_barrier
	ds_read_b128 v[80:83], v123 offset:32768
	v_xor_b32_e32 v124, 16, v123
	ds_read_b128 v[84:87], v124 offset:32768
	v_xor_b32_e32 v124, 32, v123
	ds_read_b128 v[88:91], v124 offset:32768
	v_xor_b32_e32 v124, 48, v123
	ds_read_b128 v[92:95], v124 offset:32768
	v_xor_b32_e32 v124, 64, v123
	ds_read_b128 v[96:99], v124 offset:32768
	v_xor_b32_e32 v124, 80, v123
	ds_read_b128 v[100:103], v124 offset:32768
	v_xor_b32_e32 v124, 96, v123
	ds_read_b128 v[104:107], v124 offset:32768
	v_xor_b32_e32 v124, 112, v123
	ds_read_b128 v[108:111], v124 offset:32768
	s_waitcnt lgkmcnt(0)
	v_pk_add_f32 v[80:81], v[80:81], v[82:83]
	v_pk_add_f32 v[84:85], v[84:85], v[86:87]
	v_pk_add_f32 v[88:89], v[88:89], v[90:91]
	v_pk_add_f32 v[92:93], v[92:93], v[94:95]
	v_pk_add_f32 v[96:97], v[96:97], v[98:99]
	v_pk_add_f32 v[100:101], v[100:101], v[102:103]
	v_pk_add_f32 v[104:105], v[104:105], v[106:107]
	v_pk_add_f32 v[108:109], v[108:109], v[110:111]
	v_pk_add_f32 v[80:81], v[80:81], v[84:85]
	v_pk_add_f32 v[88:89], v[88:89], v[92:93]
	v_pk_add_f32 v[96:97], v[96:97], v[100:101]
	v_pk_add_f32 v[104:105], v[104:105], v[108:109]
	v_pk_add_f32 v[80:81], v[80:81], v[88:89]
	v_pk_add_f32 v[96:97], v[96:97], v[104:105]
	s_nop 0
	v_pk_add_f32 v[80:81], v[80:81], v[96:97]
	s_nop 0
	v_cvt_pk_bf16_f32 v82, v80, v81
	global_store_dword v[118:119], v82, off
	v_lshl_add_u64 v[118:119], v[118:119], 0, s[50:51]
	s_waitcnt vmcnt(9)
	v_lshlrev_b32_e32 v52, 16, v40
	v_and_b32_e32 v53, 0xffff0000, v40
	v_lshlrev_b32_e32 v54, 16, v41
	v_and_b32_e32 v55, 0xffff0000, v41
	v_lshlrev_b32_e32 v56, 16, v42
	v_and_b32_e32 v57, 0xffff0000, v42
	v_lshlrev_b32_e32 v58, 16, v43
	v_and_b32_e32 v59, 0xffff0000, v43
	v_lshlrev_b32_e32 v60, 16, v36
	v_and_b32_e32 v61, 0xffff0000, v36
	v_lshlrev_b32_e32 v62, 16, v37
	v_and_b32_e32 v63, 0xffff0000, v37
	v_lshlrev_b32_e32 v64, 16, v38
	v_and_b32_e32 v65, 0xffff0000, v38
	v_lshlrev_b32_e32 v66, 16, v39
	v_and_b32_e32 v67, 0xffff0000, v39
	v_lshlrev_b32_e32 v68, 16, v44
	v_and_b32_e32 v69, 0xffff0000, v44
	v_lshlrev_b32_e32 v70, 16, v45
	v_and_b32_e32 v71, 0xffff0000, v45
	v_lshlrev_b32_e32 v72, 16, v46
	v_and_b32_e32 v73, 0xffff0000, v46
	v_lshlrev_b32_e32 v74, 16, v47
	v_and_b32_e32 v75, 0xffff0000, v47
	s_cmp_eq_u32 s8, 0
	v_mov_b32_e32 v76, v48
	v_mov_b32_e32 v77, v49
	s_cmp_eq_u32 s8, 0
	s_cbranch_scc1 .Lgs_g0_6
	v_mov_b32_e32 v77, v50
.Lgs_g0_6:
	ds_write_b128 v120, v[52:55] offset:16896
	ds_write_b128 v120, v[56:59] offset:16912
	ds_write_b128 v120, v[60:63] offset:17424
	ds_write_b128 v120, v[64:67] offset:17440
	s_mov_b64 exec, s[52:53]
	ds_write_b128 v121, v[68:71] offset:2048
	ds_write_b128 v121, v[72:75] offset:2064
	s_mov_b64 exec, s[54:55]
	ds_write_b64 v122, v[76:77] offset:128
	s_mov_b64 exec, -1
	global_load_dwordx4 v[36:39], v[112:113], off
	global_load_dwordx4 v[40:43], v[112:113], off offset:1024
	s_mov_b64 exec, s[52:53]
	global_load_dwordx4 v[44:47], v[114:115], off
	s_mov_b64 exec, s[54:55]
	global_load_dwordx4 v[48:51], v[116:117], off
	s_mov_b64 exec, -1
	v_lshl_add_u64 v[112:113], v[112:113], 0, s[46:47]
	v_lshl_add_u64 v[114:115], v[114:115], 0, s[46:47]
	v_lshl_add_u64 v[116:117], v[116:117], 0, s[48:49]
	s_waitcnt lgkmcnt(0)
	s_barrier
	ds_read_b128 v[80:83], v123 offset:0
	v_xor_b32_e32 v124, 16, v123
	ds_read_b128 v[84:87], v124 offset:0
	v_xor_b32_e32 v124, 32, v123
	ds_read_b128 v[88:91], v124 offset:0
	v_xor_b32_e32 v124, 48, v123
	ds_read_b128 v[92:95], v124 offset:0
	v_xor_b32_e32 v124, 64, v123
	ds_read_b128 v[96:99], v124 offset:0
	v_xor_b32_e32 v124, 80, v123
	ds_read_b128 v[100:103], v124 offset:0
	v_xor_b32_e32 v124, 96, v123
	ds_read_b128 v[104:107], v124 offset:0
	v_xor_b32_e32 v124, 112, v123
	ds_read_b128 v[108:111], v124 offset:0
	s_waitcnt lgkmcnt(0)
	v_pk_add_f32 v[80:81], v[80:81], v[82:83]
	v_pk_add_f32 v[84:85], v[84:85], v[86:87]
	v_pk_add_f32 v[88:89], v[88:89], v[90:91]
	v_pk_add_f32 v[92:93], v[92:93], v[94:95]
	v_pk_add_f32 v[96:97], v[96:97], v[98:99]
	v_pk_add_f32 v[100:101], v[100:101], v[102:103]
	v_pk_add_f32 v[104:105], v[104:105], v[106:107]
	v_pk_add_f32 v[108:109], v[108:109], v[110:111]
	v_pk_add_f32 v[80:81], v[80:81], v[84:85]
	v_pk_add_f32 v[88:89], v[88:89], v[92:93]
	v_pk_add_f32 v[96:97], v[96:97], v[100:101]
	v_pk_add_f32 v[104:105], v[104:105], v[108:109]
	v_pk_add_f32 v[80:81], v[80:81], v[88:89]
	v_pk_add_f32 v[96:97], v[96:97], v[104:105]
	s_nop 0
	v_pk_add_f32 v[80:81], v[80:81], v[96:97]
	s_nop 0
	v_cvt_pk_bf16_f32 v82, v80, v81
	global_store_dword v[118:119], v82, off
	v_lshl_add_u64 v[118:119], v[118:119], 0, s[50:51]
	s_waitcnt vmcnt(9)
	v_lshlrev_b32_e32 v52, 16, v8
	v_and_b32_e32 v53, 0xffff0000, v8
	v_lshlrev_b32_e32 v54, 16, v9
	v_and_b32_e32 v55, 0xffff0000, v9
	v_lshlrev_b32_e32 v56, 16, v10
	v_and_b32_e32 v57, 0xffff0000, v10
	v_lshlrev_b32_e32 v58, 16, v11
	v_and_b32_e32 v59, 0xffff0000, v11
	v_lshlrev_b32_e32 v60, 16, v4
	v_and_b32_e32 v61, 0xffff0000, v4
	v_lshlrev_b32_e32 v62, 16, v5
	v_and_b32_e32 v63, 0xffff0000, v5
	v_lshlrev_b32_e32 v64, 16, v6
	v_and_b32_e32 v65, 0xffff0000, v6
	v_lshlrev_b32_e32 v66, 16, v7
	v_and_b32_e32 v67, 0xffff0000, v7
	v_lshlrev_b32_e32 v68, 16, v12
	v_and_b32_e32 v69, 0xffff0000, v12
	v_lshlrev_b32_e32 v70, 16, v13
	v_and_b32_e32 v71, 0xffff0000, v13
	v_lshlrev_b32_e32 v72, 16, v14
	v_and_b32_e32 v73, 0xffff0000, v14
	v_lshlrev_b32_e32 v74, 16, v15
	v_and_b32_e32 v75, 0xffff0000, v15
	s_cmp_eq_u32 s8, 0
	v_mov_b32_e32 v76, v16
	v_mov_b32_e32 v77, v17
	s_cmp_eq_u32 s8, 0
	s_cbranch_scc1 .Lgs_g0_7
	v_mov_b32_e32 v77, v18
.Lgs_g0_7:
	ds_write_b128 v120, v[52:55] offset:0
	ds_write_b128 v120, v[56:59] offset:16
	ds_write_b128 v120, v[60:63] offset:528
	ds_write_b128 v120, v[64:67] offset:544
	s_mov_b64 exec, s[52:53]
	ds_write_b128 v121, v[68:71] offset:0
	ds_write_b128 v121, v[72:75] offset:16
	s_mov_b64 exec, s[54:55]
	ds_write_b64 v122, v[76:77] offset:0
	s_mov_b64 exec, -1
	global_load_dwordx4 v[4:7], v[112:113], off
	global_load_dwordx4 v[8:11], v[112:113], off offset:1024
	s_mov_b64 exec, s[52:53]
	global_load_dwordx4 v[12:15], v[114:115], off
	s_mov_b64 exec, s[54:55]
	global_load_dwordx4 v[16:19], v[116:117], off
	s_mov_b64 exec, -1
	v_lshl_add_u64 v[112:113], v[112:113], 0, s[46:47]
	v_lshl_add_u64 v[114:115], v[114:115], 0, s[46:47]
	v_lshl_add_u64 v[116:117], v[116:117], 0, s[48:49]
	s_waitcnt lgkmcnt(0)
	s_barrier
	s_add_i32 s44, s44, 1
	s_cmp_lt_u32 s44, 42
	s_cbranch_scc1 .Lgs_loop
	ds_read_b128 v[80:83], v123 offset:32768
	v_xor_b32_e32 v124, 16, v123
	ds_read_b128 v[84:87], v124 offset:32768
	v_xor_b32_e32 v124, 32, v123
	ds_read_b128 v[88:91], v124 offset:32768
	v_xor_b32_e32 v124, 48, v123
	ds_read_b128 v[92:95], v124 offset:32768
	v_xor_b32_e32 v124, 64, v123
	ds_read_b128 v[96:99], v124 offset:32768
	v_xor_b32_e32 v124, 80, v123
	ds_read_b128 v[100:103], v124 offset:32768
	v_xor_b32_e32 v124, 96, v123
	ds_read_b128 v[104:107], v124 offset:32768
	v_xor_b32_e32 v124, 112, v123
	ds_read_b128 v[108:111], v124 offset:32768
	s_waitcnt lgkmcnt(0)
	v_pk_add_f32 v[80:81], v[80:81], v[82:83]
	v_pk_add_f32 v[84:85], v[84:85], v[86:87]
	v_pk_add_f32 v[88:89], v[88:89], v[90:91]
	v_pk_add_f32 v[92:93], v[92:93], v[94:95]
	v_pk_add_f32 v[96:97], v[96:97], v[98:99]
	v_pk_add_f32 v[100:101], v[100:101], v[102:103]
	v_pk_add_f32 v[104:105], v[104:105], v[106:107]
	v_pk_add_f32 v[108:109], v[108:109], v[110:111]
	v_pk_add_f32 v[80:81], v[80:81], v[84:85]
	v_pk_add_f32 v[88:89], v[88:89], v[92:93]
	v_pk_add_f32 v[96:97], v[96:97], v[100:101]
	v_pk_add_f32 v[104:105], v[104:105], v[108:109]
	v_pk_add_f32 v[80:81], v[80:81], v[88:89]
	v_pk_add_f32 v[96:97], v[96:97], v[104:105]
	s_nop 0
	v_pk_add_f32 v[80:81], v[80:81], v[96:97]
	s_nop 0
	v_cvt_pk_bf16_f32 v82, v80, v81
	s_cmp_eq_u32 s44, 0
	s_cselect_b64 s[22:23], 0, -1
	s_cselect_b64 s[58:59], 0, s[50:51]
	s_mov_b64 exec, s[22:23]
	global_store_dword v[118:119], v82, off
	s_mov_b64 exec, -1
	v_lshl_add_u64 v[118:119], v[118:119], 0, s[58:59]
	s_waitcnt vmcnt(9)
	v_lshlrev_b32_e32 v52, 16, v24
	v_and_b32_e32 v53, 0xffff0000, v24
	v_lshlrev_b32_e32 v54, 16, v25
	v_and_b32_e32 v55, 0xffff0000, v25
	v_lshlrev_b32_e32 v56, 16, v26
	v_and_b32_e32 v57, 0xffff0000, v26
	v_lshlrev_b32_e32 v58, 16, v27
	v_and_b32_e32 v59, 0xffff0000, v27
	v_lshlrev_b32_e32 v60, 16, v20
	v_and_b32_e32 v61, 0xffff0000, v20
	v_lshlrev_b32_e32 v62, 16, v21
	v_and_b32_e32 v63, 0xffff0000, v21
	v_lshlrev_b32_e32 v64, 16, v22
	v_and_b32_e32 v65, 0xffff0000, v22
	v_lshlrev_b32_e32 v66, 16, v23
	v_and_b32_e32 v67, 0xffff0000, v23
	v_lshlrev_b32_e32 v68, 16, v28
	v_and_b32_e32 v69, 0xffff0000, v28
	v_lshlrev_b32_e32 v70, 16, v29
	v_and_b32_e32 v71, 0xffff0000, v29
	v_lshlrev_b32_e32 v72, 16, v30
	v_and_b32_e32 v73, 0xffff0000, v30
	v_lshlrev_b32_e32 v74, 16, v31
	v_and_b32_e32 v75, 0xffff0000, v31
	s_cmp_eq_u32 s8, 0
	v_mov_b32_e32 v76, v32
	v_mov_b32_e32 v77, v33
	s_cmp_eq_u32 s8, 0
	s_cbranch_scc1 .Lgs_g0_8
	v_mov_b32_e32 v77, v34

.Lgs_g0_10:
	ds_write_b128 v120, v[52:55] offset:16896
	ds_write_b128 v120, v[56:59] offset:16912
	ds_write_b128 v120, v[60:63] offset:17424
	ds_write_b128 v120, v[64:67] offset:17440
	s_mov_b64 exec, s[52:53]
	ds_write_b128 v121, v[68:71] offset:2048
	ds_write_b128 v121, v[72:75] offset:2064
	s_mov_b64 exec, s[54:55]
	ds_write_b64 v122, v[76:77] offset:128
	s_mov_b64 exec, -1
	global_load_dwordx4 v[4:7], v[112:113], off
	global_load_dwordx4 v[8:11], v[112:113], off offset:1024
	s_mov_b64 exec, s[52:53]
	global_load_dwordx4 v[12:15], v[114:115], off
	s_mov_b64 exec, s[54:55]
	global_load_dwordx4 v[16:19], v[116:117], off
	s_mov_b64 exec, -1
	v_lshl_add_u64 v[112:113], v[112:113], 0, s[46:47]
	v_lshl_add_u64 v[114:115], v[114:115], 0, s[46:47]
	v_lshl_add_u64 v[116:117], v[116:117], 0, s[48:49]
	s_waitcnt lgkmcnt(0)
	s_barrier
	ds_read_b128 v[80:83], v123 offset:0
	v_xor_b32_e32 v124, 16, v123
	ds_read_b128 v[84:87], v124 offset:0
	v_xor_b32_e32 v124, 32, v123
	ds_read_b128 v[88:91], v124 offset:0
	v_xor_b32_e32 v124, 48, v123
	ds_read_b128 v[92:95], v124 offset:0
	v_xor_b32_e32 v124, 64, v123
	ds_read_b128 v[96:99], v124 offset:0
	v_xor_b32_e32 v124, 80, v123
	ds_read_b128 v[100:103], v124 offset:0
	v_xor_b32_e32 v124, 96, v123
	ds_read_b128 v[104:107], v124 offset:0
	v_xor_b32_e32 v124, 112, v123
	ds_read_b128 v[108:111], v124 offset:0
	s_waitcnt lgkmcnt(0)
	v_pk_add_f32 v[80:81], v[80:81], v[82:83]
	v_pk_add_f32 v[84:85], v[84:85], v[86:87]
	v_pk_add_f32 v[88:89], v[88:89], v[90:91]
	v_pk_add_f32 v[92:93], v[92:93], v[94:95]
	v_pk_add_f32 v[96:97], v[96:97], v[98:99]
	v_pk_add_f32 v[100:101], v[100:101], v[102:103]
	v_pk_add_f32 v[104:105], v[104:105], v[106:107]
	v_pk_add_f32 v[108:109], v[108:109], v[110:111]
	v_pk_add_f32 v[80:81], v[80:81], v[84:85]
	v_pk_add_f32 v[88:89], v[88:89], v[92:93]
	v_pk_add_f32 v[96:97], v[96:97], v[100:101]
	v_pk_add_f32 v[104:105], v[104:105], v[108:109]
	v_pk_add_f32 v[80:81], v[80:81], v[88:89]
	v_pk_add_f32 v[96:97], v[96:97], v[104:105]
	s_nop 0
	v_pk_add_f32 v[80:81], v[80:81], v[96:97]
	s_nop 0
	v_cvt_pk_bf16_f32 v82, v80, v81
	global_store_dword v[118:119], v82, off
	v_lshl_add_u64 v[118:119], v[118:119], 0, s[50:51]
	s_waitcnt vmcnt(0)
	s_barrier
	ds_read_b128 v[80:83], v123 offset:32768
	v_xor_b32_e32 v124, 16, v123
	ds_read_b128 v[84:87], v124 offset:32768
	v_xor_b32_e32 v124, 32, v123
	ds_read_b128 v[88:91], v124 offset:32768
	v_xor_b32_e32 v124, 48, v123
	ds_read_b128 v[92:95], v124 offset:32768
	v_xor_b32_e32 v124, 64, v123
	ds_read_b128 v[96:99], v124 offset:32768
	v_xor_b32_e32 v124, 80, v123
	ds_read_b128 v[100:103], v124 offset:32768
	v_xor_b32_e32 v124, 96, v123
	ds_read_b128 v[104:107], v124 offset:32768
	v_xor_b32_e32 v124, 112, v123
	ds_read_b128 v[108:111], v124 offset:32768
	s_waitcnt lgkmcnt(0)
	v_pk_add_f32 v[80:81], v[80:81], v[82:83]
	v_pk_add_f32 v[84:85], v[84:85], v[86:87]
	v_pk_add_f32 v[88:89], v[88:89], v[90:91]
	v_pk_add_f32 v[92:93], v[92:93], v[94:95]
	v_pk_add_f32 v[96:97], v[96:97], v[98:99]
	v_pk_add_f32 v[100:101], v[100:101], v[102:103]
	v_pk_add_f32 v[104:105], v[104:105], v[106:107]
	v_pk_add_f32 v[108:109], v[108:109], v[110:111]
	v_pk_add_f32 v[80:81], v[80:81], v[84:85]
	v_pk_add_f32 v[88:89], v[88:89], v[92:93]
	v_pk_add_f32 v[96:97], v[96:97], v[100:101]
	v_pk_add_f32 v[104:105], v[104:105], v[108:109]
	v_pk_add_f32 v[80:81], v[80:81], v[88:89]
	v_pk_add_f32 v[96:97], v[96:97], v[104:105]
	s_nop 0
	v_pk_add_f32 v[80:81], v[80:81], v[96:97]
	s_nop 0
	v_cvt_pk_bf16_f32 v82, v80, v81
	global_store_dword v[118:119], v82, off
	v_lshl_add_u64 v[118:119], v[118:119], 0, s[50:51]
	s_waitcnt vmcnt(0)
